# K-loop back edge rotated (guide 7.11): taken branch before the loop-back barrier, barrier is the loop head, exit path has its own barrier copy
# baseline (speedup 1.0000x reference)
.Lrot_87:
	s_barrier
.LBB0_87:
	ds_read_b128 v[128:131], v220 offset:0
	ds_read_b128 v[132:135], v220 offset:1024
	ds_read_b128 v[136:139], v220 offset:2048
	ds_read_b128 v[140:143], v220 offset:3072
	ds_read_b128 v[144:147], v185
	ds_read_b128 v[148:151], v185 offset:1024
	ds_read_b128 v[152:155], v185 offset:2048
	ds_read_b128 v[156:159], v185 offset:3072
	ds_read_b128 v[170:173], v185 offset:4096
	ds_read_b128 v[174:177], v185 offset:5120
	ds_read_b128 v[178:181], v185 offset:6144
	ds_read_b128 v[186:189], v185 offset:7168
	global_load_lds_dwordx4 v166, s[14:15]
	s_add_i32 m0, s28, 0xe000
	s_nop 0
	global_load_lds_dwordx4 v168, s[14:15]
	s_waitcnt lgkmcnt(8)
	s_barrier
	s_waitcnt lgkmcnt(0)
	v_mfma_f32_16x16x32_bf16 v[124:127], v[128:131], v[144:147], v[124:127]
	v_mfma_f32_16x16x32_bf16 v[120:123], v[136:139], v[144:147], v[120:123]
	v_mfma_f32_16x16x32_bf16 v[108:111], v[128:131], v[152:155], v[108:111]
	v_mfma_f32_16x16x32_bf16 v[104:107], v[136:139], v[152:155], v[104:107]
	s_add_i32 s46, 0, 0x14000
	s_add_i32 s43, s43, s27
	v_mfma_f32_16x16x32_bf16 v[92:95], v[128:131], v[170:173], v[92:95]
	s_mov_b32 m0, s43
	v_mfma_f32_16x16x32_bf16 v[88:91], v[136:139], v[170:173], v[88:91]
	v_mfma_f32_16x16x32_bf16 v[76:79], v[128:131], v[178:181], v[76:79]
	v_mfma_f32_16x16x32_bf16 v[72:75], v[136:139], v[178:181], v[72:75]
	v_mfma_f32_16x16x32_bf16 v[124:127], v[132:135], v[148:151], v[124:127]
	v_mfma_f32_16x16x32_bf16 v[120:123], v[140:143], v[148:151], v[120:123]
	v_mfma_f32_16x16x32_bf16 v[108:111], v[132:135], v[156:159], v[108:111]
	v_mfma_f32_16x16x32_bf16 v[104:107], v[140:143], v[156:159], v[104:107]
	v_mfma_f32_16x16x32_bf16 v[92:95], v[132:135], v[174:177], v[92:95]
	v_mfma_f32_16x16x32_bf16 v[88:91], v[140:143], v[174:177], v[88:91]
	v_mfma_f32_16x16x32_bf16 v[76:79], v[132:135], v[186:189], v[76:79]
	v_mfma_f32_16x16x32_bf16 v[72:75], v[140:143], v[186:189], v[72:75]
	s_barrier
	ds_read_b128 v[196:199], v220 offset:16384
	ds_read_b128 v[204:207], v220 offset:17408
	ds_read_b128 v[208:211], v220 offset:18432
	ds_read_b128 v[214:217], v220 offset:19456
	global_load_lds_dwordx4 v192, s[16:17]
	s_add_i32 m0, s43, 0x2000
	s_nop 0
	global_load_lds_dwordx4 v164, s[16:17]
	s_barrier
	s_waitcnt lgkmcnt(0)
	v_mfma_f32_16x16x32_bf16 v[116:119], v[196:199], v[144:147], v[116:119]
	v_mfma_f32_16x16x32_bf16 v[112:115], v[208:211], v[144:147], v[112:115]
	v_mfma_f32_16x16x32_bf16 v[100:103], v[196:199], v[152:155], v[100:103]
	v_mfma_f32_16x16x32_bf16 v[96:99], v[208:211], v[152:155], v[96:99]
	s_mov_b32 m0, s28
	v_mfma_f32_16x16x32_bf16 v[84:87], v[196:199], v[170:173], v[84:87]
	s_add_u32 s48, s18, 0x80
	s_addc_u32 s49, s19, 0
	v_mfma_f32_16x16x32_bf16 v[80:83], v[208:211], v[170:173], v[80:83]
	v_mfma_f32_16x16x32_bf16 v[68:71], v[196:199], v[178:181], v[68:71]
	v_mfma_f32_16x16x32_bf16 v[64:67], v[208:211], v[178:181], v[64:67]
	v_mfma_f32_16x16x32_bf16 v[116:119], v[204:207], v[148:151], v[116:119]
	v_mfma_f32_16x16x32_bf16 v[112:115], v[214:217], v[148:151], v[112:115]
	v_mfma_f32_16x16x32_bf16 v[100:103], v[204:207], v[156:159], v[100:103]
	v_mfma_f32_16x16x32_bf16 v[96:99], v[214:217], v[156:159], v[96:99]
	v_mfma_f32_16x16x32_bf16 v[84:87], v[204:207], v[174:177], v[84:87]
	v_mfma_f32_16x16x32_bf16 v[80:83], v[214:217], v[174:177], v[80:83]
	v_mfma_f32_16x16x32_bf16 v[68:71], v[204:207], v[186:189], v[68:71]
	v_mfma_f32_16x16x32_bf16 v[64:67], v[214:217], v[186:189], v[64:67]
	s_barrier
	ds_read_b128 v[144:147], v185 offset:16384
	ds_read_b128 v[148:151], v185 offset:17408
	ds_read_b128 v[152:155], v185 offset:18432
	ds_read_b128 v[156:159], v185 offset:19456
	ds_read_b128 v[170:173], v185 offset:20480
	ds_read_b128 v[174:177], v185 offset:21504
	ds_read_b128 v[178:181], v185 offset:22528
	ds_read_b128 v[186:189], v185 offset:23552
	global_load_lds_dwordx4 v160, s[18:19]
	s_mov_b32 m0, s29
	s_nop 0
	global_load_lds_dwordx4 v162, s[18:19]
	s_barrier
	s_waitcnt lgkmcnt(0)
	v_mfma_f32_16x16x32_bf16 v[60:63], v[128:131], v[144:147], v[60:63]
	v_mfma_f32_16x16x32_bf16 v[56:59], v[136:139], v[144:147], v[56:59]
	v_mfma_f32_16x16x32_bf16 v[44:47], v[128:131], v[152:155], v[44:47]
	v_mfma_f32_16x16x32_bf16 v[40:43], v[136:139], v[152:155], v[40:43]
	s_add_u32 s44, s16, 0x80000
	s_addc_u32 s45, s17, 0
	v_mfma_f32_16x16x32_bf16 v[28:31], v[128:131], v[170:173], v[28:31]
	s_add_i32 s43, s46, s27
	s_mov_b32 m0, s43
	v_mfma_f32_16x16x32_bf16 v[24:27], v[136:139], v[170:173], v[24:27]
	v_mfma_f32_16x16x32_bf16 v[12:15], v[128:131], v[178:181], v[12:15]
	v_mfma_f32_16x16x32_bf16 v[8:11], v[136:139], v[178:181], v[8:11]
	v_mfma_f32_16x16x32_bf16 v[60:63], v[132:135], v[148:151], v[60:63]
	v_mfma_f32_16x16x32_bf16 v[56:59], v[140:143], v[148:151], v[56:59]
	v_mfma_f32_16x16x32_bf16 v[44:47], v[132:135], v[156:159], v[44:47]
	v_mfma_f32_16x16x32_bf16 v[40:43], v[140:143], v[156:159], v[40:43]
	v_mfma_f32_16x16x32_bf16 v[28:31], v[132:135], v[174:177], v[28:31]
	v_mfma_f32_16x16x32_bf16 v[24:27], v[140:143], v[174:177], v[24:27]
	v_mfma_f32_16x16x32_bf16 v[12:15], v[132:135], v[186:189], v[12:15]
	v_mfma_f32_16x16x32_bf16 v[8:11], v[140:143], v[186:189], v[8:11]
	s_barrier
	global_load_lds_dwordx4 v192, s[44:45]
	s_add_i32 m0, s43, 0x2000
	s_nop 0
	global_load_lds_dwordx4 v164, s[44:45]
	s_waitcnt vmcnt(6)
	s_barrier
	v_mfma_f32_16x16x32_bf16 v[52:55], v[196:199], v[144:147], v[52:55]
	v_mfma_f32_16x16x32_bf16 v[48:51], v[208:211], v[144:147], v[48:51]
	v_mfma_f32_16x16x32_bf16 v[36:39], v[196:199], v[152:155], v[36:39]
	v_mfma_f32_16x16x32_bf16 v[32:35], v[208:211], v[152:155], v[32:35]
	s_add_i32 s43, 0, 0x18000
	v_mfma_f32_16x16x32_bf16 v[20:23], v[196:199], v[170:173], v[20:23]
	s_add_u32 s18, s18, 0x80000
	s_addc_u32 s19, s19, 0
	v_mfma_f32_16x16x32_bf16 v[16:19], v[208:211], v[170:173], v[16:19]
	s_mov_b32 m0, s30
	v_mfma_f32_16x16x32_bf16 v[4:7], v[196:199], v[178:181], v[4:7]
	v_mfma_f32_16x16x32_bf16 v[0:3], v[208:211], v[178:181], v[0:3]
	v_mfma_f32_16x16x32_bf16 v[52:55], v[204:207], v[148:151], v[52:55]
	v_mfma_f32_16x16x32_bf16 v[48:51], v[214:217], v[148:151], v[48:51]
	v_mfma_f32_16x16x32_bf16 v[36:39], v[204:207], v[156:159], v[36:39]
	v_mfma_f32_16x16x32_bf16 v[32:35], v[214:217], v[156:159], v[32:35]
	v_mfma_f32_16x16x32_bf16 v[20:23], v[204:207], v[174:177], v[20:23]
	v_mfma_f32_16x16x32_bf16 v[16:19], v[214:217], v[174:177], v[16:19]
	v_mfma_f32_16x16x32_bf16 v[4:7], v[204:207], v[186:189], v[4:7]
	v_mfma_f32_16x16x32_bf16 v[0:3], v[214:217], v[186:189], v[0:3]
	s_barrier
	ds_read_b128 v[128:131], v220 offset:32768
	ds_read_b128 v[132:135], v220 offset:33792
	ds_read_b128 v[136:139], v220 offset:34816
	ds_read_b128 v[140:143], v220 offset:35840
	ds_read_b128 v[144:147], v185 offset:32768
	ds_read_b128 v[148:151], v185 offset:33792
	ds_read_b128 v[152:155], v185 offset:34816
	ds_read_b128 v[156:159], v185 offset:35840
	ds_read_b128 v[170:173], v185 offset:36864
	ds_read_b128 v[174:177], v185 offset:37888
	ds_read_b128 v[178:181], v185 offset:38912
	ds_read_b128 v[186:189], v185 offset:39936
	global_load_lds_dwordx4 v160, s[18:19]
	s_mov_b32 m0, s31
	s_nop 0
	global_load_lds_dwordx4 v162, s[18:19]
	s_waitcnt lgkmcnt(8)
	s_barrier
	s_waitcnt lgkmcnt(0)
	v_mfma_f32_16x16x32_bf16 v[124:127], v[128:131], v[144:147], v[124:127]
	v_mfma_f32_16x16x32_bf16 v[120:123], v[136:139], v[144:147], v[120:123]
	v_mfma_f32_16x16x32_bf16 v[108:111], v[128:131], v[152:155], v[108:111]
	v_mfma_f32_16x16x32_bf16 v[104:107], v[136:139], v[152:155], v[104:107]
	s_add_i32 s18, 0, 0x1c000
	s_add_i32 s19, s43, s27
	v_mfma_f32_16x16x32_bf16 v[92:95], v[128:131], v[170:173], v[92:95]
	s_add_i32 m0, s19, 0xffffff80
	v_mfma_f32_16x16x32_bf16 v[88:91], v[136:139], v[170:173], v[88:91]
	v_mfma_f32_16x16x32_bf16 v[76:79], v[128:131], v[178:181], v[76:79]
	v_mfma_f32_16x16x32_bf16 v[72:75], v[136:139], v[178:181], v[72:75]
	v_mfma_f32_16x16x32_bf16 v[124:127], v[132:135], v[148:151], v[124:127]
	v_mfma_f32_16x16x32_bf16 v[120:123], v[140:143], v[148:151], v[120:123]
	v_mfma_f32_16x16x32_bf16 v[108:111], v[132:135], v[156:159], v[108:111]
	v_mfma_f32_16x16x32_bf16 v[104:107], v[140:143], v[156:159], v[104:107]
	v_mfma_f32_16x16x32_bf16 v[92:95], v[132:135], v[174:177], v[92:95]
	v_mfma_f32_16x16x32_bf16 v[88:91], v[140:143], v[174:177], v[88:91]
	v_mfma_f32_16x16x32_bf16 v[76:79], v[132:135], v[186:189], v[76:79]
	v_mfma_f32_16x16x32_bf16 v[72:75], v[140:143], v[186:189], v[72:75]
	s_barrier
	ds_read_b128 v[196:199], v220 offset:49152
	ds_read_b128 v[204:207], v220 offset:50176
	ds_read_b128 v[208:211], v220 offset:51200
	ds_read_b128 v[214:217], v220 offset:52224
	global_load_lds_dwordx4 v192, s[16:17] offset:128
	s_add_i32 m0, s19, 0x1f80
	s_nop 0
	global_load_lds_dwordx4 v164, s[16:17] offset:128
	s_barrier
	s_waitcnt lgkmcnt(0)
	v_mfma_f32_16x16x32_bf16 v[116:119], v[196:199], v[144:147], v[116:119]
	v_mfma_f32_16x16x32_bf16 v[112:115], v[208:211], v[144:147], v[112:115]
	v_mfma_f32_16x16x32_bf16 v[100:103], v[196:199], v[152:155], v[100:103]
	v_mfma_f32_16x16x32_bf16 v[96:99], v[208:211], v[152:155], v[96:99]
	s_mov_b32 m0, s35
	v_mfma_f32_16x16x32_bf16 v[84:87], v[196:199], v[170:173], v[84:87]
	v_mfma_f32_16x16x32_bf16 v[80:83], v[208:211], v[170:173], v[80:83]
	v_mfma_f32_16x16x32_bf16 v[68:71], v[196:199], v[178:181], v[68:71]
	v_mfma_f32_16x16x32_bf16 v[64:67], v[208:211], v[178:181], v[64:67]
	v_mfma_f32_16x16x32_bf16 v[116:119], v[204:207], v[148:151], v[116:119]
	v_mfma_f32_16x16x32_bf16 v[112:115], v[214:217], v[148:151], v[112:115]
	v_mfma_f32_16x16x32_bf16 v[100:103], v[204:207], v[156:159], v[100:103]
	v_mfma_f32_16x16x32_bf16 v[96:99], v[214:217], v[156:159], v[96:99]
	v_mfma_f32_16x16x32_bf16 v[84:87], v[204:207], v[174:177], v[84:87]
	v_mfma_f32_16x16x32_bf16 v[80:83], v[214:217], v[174:177], v[80:83]
	v_mfma_f32_16x16x32_bf16 v[68:71], v[204:207], v[186:189], v[68:71]
	v_mfma_f32_16x16x32_bf16 v[64:67], v[214:217], v[186:189], v[64:67]
	s_barrier
	ds_read_b128 v[144:147], v185 offset:49152
	ds_read_b128 v[148:151], v185 offset:50176
	ds_read_b128 v[152:155], v185 offset:51200
	ds_read_b128 v[156:159], v185 offset:52224
	ds_read_b128 v[170:173], v185 offset:53248
	ds_read_b128 v[174:177], v185 offset:54272
	ds_read_b128 v[178:181], v185 offset:55296
	ds_read_b128 v[186:189], v185 offset:56320
	global_load_lds_dwordx4 v160, s[48:49]
	s_mov_b32 m0, s36
	s_nop 0
	global_load_lds_dwordx4 v162, s[48:49]
	s_barrier
	s_waitcnt lgkmcnt(0)
	v_mfma_f32_16x16x32_bf16 v[60:63], v[128:131], v[144:147], v[60:63]
	v_mfma_f32_16x16x32_bf16 v[56:59], v[136:139], v[144:147], v[56:59]
	v_mfma_f32_16x16x32_bf16 v[44:47], v[128:131], v[152:155], v[44:47]
	v_mfma_f32_16x16x32_bf16 v[40:43], v[136:139], v[152:155], v[40:43]
	s_add_u32 s16, s16, 0x80080
	s_addc_u32 s17, s17, 0
	v_mfma_f32_16x16x32_bf16 v[28:31], v[128:131], v[170:173], v[28:31]
	s_add_i32 s18, s18, s27
	s_mov_b32 m0, s18
	v_mfma_f32_16x16x32_bf16 v[24:27], v[136:139], v[170:173], v[24:27]
	v_mfma_f32_16x16x32_bf16 v[12:15], v[128:131], v[178:181], v[12:15]
	v_mfma_f32_16x16x32_bf16 v[8:11], v[136:139], v[178:181], v[8:11]
	v_mfma_f32_16x16x32_bf16 v[60:63], v[132:135], v[148:151], v[60:63]
	v_mfma_f32_16x16x32_bf16 v[56:59], v[140:143], v[148:151], v[56:59]
	v_mfma_f32_16x16x32_bf16 v[44:47], v[132:135], v[156:159], v[44:47]
	v_mfma_f32_16x16x32_bf16 v[40:43], v[140:143], v[156:159], v[40:43]
	v_mfma_f32_16x16x32_bf16 v[28:31], v[132:135], v[174:177], v[28:31]
	v_mfma_f32_16x16x32_bf16 v[24:27], v[140:143], v[174:177], v[24:27]
	v_mfma_f32_16x16x32_bf16 v[12:15], v[132:135], v[186:189], v[12:15]
	v_mfma_f32_16x16x32_bf16 v[8:11], v[140:143], v[186:189], v[8:11]
	s_barrier
	global_load_lds_dwordx4 v192, s[16:17]
	s_add_i32 m0, s18, 0x2000
	s_nop 0
	global_load_lds_dwordx4 v164, s[16:17]
	s_waitcnt vmcnt(6)
	s_barrier
	v_mfma_f32_16x16x32_bf16 v[52:55], v[196:199], v[144:147], v[52:55]
	v_mfma_f32_16x16x32_bf16 v[48:51], v[208:211], v[144:147], v[48:51]
	v_mfma_f32_16x16x32_bf16 v[36:39], v[196:199], v[152:155], v[36:39]
	v_mfma_f32_16x16x32_bf16 v[32:35], v[208:211], v[152:155], v[32:35]
	s_add_i32 s42, s42, 2
	v_mfma_f32_16x16x32_bf16 v[20:23], v[196:199], v[170:173], v[20:23]
	s_add_u32 s14, s14, 0x100
	s_addc_u32 s15, s15, 0
	v_mfma_f32_16x16x32_bf16 v[16:19], v[208:211], v[170:173], v[16:19]
	s_add_u32 s40, s40, 0x100
	s_addc_u32 s41, s41, 0
	v_mfma_f32_16x16x32_bf16 v[4:7], v[196:199], v[178:181], v[4:7]
	s_add_u32 s16, s14, 0xfff80080
	s_addc_u32 s17, s15, -1
	v_mfma_f32_16x16x32_bf16 v[0:3], v[208:211], v[178:181], v[0:3]
	s_add_i32 s43, 0, 0x10000
	s_cmp_eq_u32 s42, 28
	v_mfma_f32_16x16x32_bf16 v[52:55], v[204:207], v[148:151], v[52:55]
	s_cselect_b32 s19, s7, s17
	s_cselect_b32 s18, s38, s16
	v_mfma_f32_16x16x32_bf16 v[48:51], v[214:217], v[148:151], v[48:51]
	s_cselect_b32 s17, s5, s41
	s_cselect_b32 s16, s39, s40
	v_mfma_f32_16x16x32_bf16 v[36:39], v[204:207], v[156:159], v[36:39]
	s_add_i32 m0, s28, 0xc000
	v_mfma_f32_16x16x32_bf16 v[32:35], v[214:217], v[156:159], v[32:35]
	v_mfma_f32_16x16x32_bf16 v[20:23], v[204:207], v[174:177], v[20:23]
	v_mfma_f32_16x16x32_bf16 v[16:19], v[214:217], v[174:177], v[16:19]
	v_mfma_f32_16x16x32_bf16 v[4:7], v[204:207], v[186:189], v[4:7]
	v_mfma_f32_16x16x32_bf16 v[0:3], v[214:217], v[186:189], v[0:3]
	s_cmp_gt_u32 s42, 29
	s_cbranch_scc0 .Lrot_87
	s_barrier
	v_lshl_or_b32 v128, s13, 8, v184
	v_lshl_add_u32 v172, s12, 8, v182
	v_ashrrev_i32_e32 v129, 31, v128
	v_lshlrev_b64 v[170:171], 1, v[128:129]
	v_ashrrev_i32_e32 v173, 31, v172
	v_lshl_add_u64 v[174:175], s[2:3], 0, v[170:171]
	v_lshlrev_b64 v[128:129], 13, v[172:173]
	v_lshl_add_u64 v[130:131], v[174:175], 0, v[128:129]
	global_load_dwordx4 v[186:189], v[130:131], off
	global_load_dwordx4 v[196:199], v[130:131], off offset:256
	s_lshl_b32 s5, s13, 1
	v_mul_f32_e32 v133, 0xbfb8aa3b, v124
	v_mul_f32_e32 v135, 0xbfb8aa3b, v125
	v_mul_f32_e32 v137, 0xbfb8aa3b, v126
	v_mul_f32_e32 v138, 0xbfb8aa3b, v127
	v_mul_f32_e32 v139, 0xbfb8aa3b, v120
	v_mul_f32_e32 v140, 0xbfb8aa3b, v121
	s_and_b32 s12, s5, -4
	v_or_b32_e32 v132, 16, v172
	v_or_b32_e32 v136, 48, v172
	v_exp_f32_e32 v148, v133
	v_exp_f32_e32 v149, v135
	v_exp_f32_e32 v150, v137
	v_exp_f32_e32 v151, v138
	v_exp_f32_e32 v204, v139
	v_exp_f32_e32 v205, v140
	s_ashr_i32 s13, s12, 31
	v_or_b32_e32 v134, 32, v172
	v_ashrrev_i32_e32 v133, 31, v132
	v_ashrrev_i32_e32 v137, 31, v136
	s_lshl_b64 s[12:13], s[12:13], 2
	v_mul_f32_e32 v141, 0xbfb8aa3b, v122
	v_ashrrev_i32_e32 v135, 31, v134
	v_lshlrev_b64 v[180:181], 13, v[132:133]
	v_lshlrev_b64 v[176:177], 13, v[136:137]
	s_add_u32 s12, s33, s12
	v_exp_f32_e32 v212, v141
	v_lshlrev_b64 v[138:139], 7, v[172:173]
	v_lshlrev_b64 v[140:141], 7, v[132:133]
	v_lshlrev_b64 v[142:143], 7, v[134:135]
	v_lshlrev_b64 v[178:179], 13, v[134:135]
	v_lshlrev_b64 v[144:145], 7, v[136:137]
	v_lshl_add_u64 v[128:129], s[2:3], 0, v[128:129]
	v_lshl_add_u64 v[130:131], v[174:175], 0, v[180:181]
	v_lshl_add_u64 v[136:137], v[174:175], 0, v[176:177]
	s_addc_u32 s13, s34, s13
	v_lshl_add_u64 v[146:147], v[174:175], 0, v[178:179]
	v_lshl_add_u64 v[190:191], v[128:129], 0, v[170:171]
	global_load_dwordx4 v[156:159], v[130:131], off
	global_load_dwordx4 v[152:155], v[130:131], off offset:256
	global_load_dwordx4 v[132:135], v[136:137], off
	s_nop 0
	global_load_dwordx4 v[128:131], v[136:137], off offset:256
	v_add_f32_e32 v148, 1.0, v148
	v_add_f32_e32 v149, 1.0, v149
	v_add_f32_e32 v150, 1.0, v150
	v_add_f32_e32 v151, 1.0, v151
	v_add_f32_e32 v173, 1.0, v204
	v_add_f32_e32 v204, 1.0, v205
	v_lshl_add_u64 v[136:137], s[12:13], 0, v[138:139]
	v_lshl_add_u64 v[138:139], s[12:13], 0, v[140:141]
	v_lshl_add_u64 v[140:141], s[12:13], 0, v[142:143]
	v_lshl_add_u64 v[144:145], s[12:13], 0, v[144:145]
	v_rcp_f32_e32 v214, v148
	v_rcp_f32_e32 v215, v149
	v_rcp_f32_e32 v216, v150
	v_rcp_f32_e32 v217, v151
	v_rcp_f32_e32 v218, v204
	global_load_dwordx4 v[204:207], v[136:137], off
	global_load_dwordx4 v[208:211], v[138:139], off
	s_nop 0
	global_load_dwordx4 v[136:139], v[140:141], off
	global_load_dwordx4 v[148:151], v[146:147], off
	s_nop 0
	global_load_dwordx4 v[140:143], v[146:147], off offset:256
	s_nop 0
	global_load_dwordx4 v[144:147], v[144:145], off
	v_rcp_f32_e32 v173, v173
	v_mul_f32_e32 v124, v124, v214
	v_mul_f32_e32 v125, v125, v215
	v_mul_f32_e32 v127, v127, v217
	v_mul_f32_e32 v120, v120, v173
	v_mul_f32_e32 v121, v121, v218
	s_mov_b32 s14, 0x358637bd
	s_mov_b32 s5, 0x800000
	v_mul_f32_e32 v126, v126, v216
	s_mov_b64 s[16:17], s[10:11]
	s_mov_b32 s11, 0xc000
	s_waitcnt vmcnt(0)
	v_lshlrev_b32_e32 v173, 16, v186
	v_and_b32_e32 v186, 0xffff0000, v186
	v_lshlrev_b32_e32 v214, 16, v187
	v_and_b32_e32 v187, 0xffff0000, v187
	v_mul_f32_e32 v125, v125, v186
	v_mul_f32_e32 v127, v127, v187
	v_add_f32_e32 v186, 1.0, v212
	v_mul_f32_e32 v187, 0xbfb8aa3b, v123
	v_rcp_f32_e32 v186, v186
	v_exp_f32_e32 v187, v187
	v_mul_f32_e32 v124, v124, v173
	v_and_b32_e32 v173, 0xffff0000, v188
	v_mul_f32_e32 v122, v122, v186
	v_add_f32_e32 v186, 1.0, v187
	v_mul_f32_e32 v187, 0xbfb8aa3b, v116
	v_rcp_f32_e32 v186, v186
	v_exp_f32_e32 v187, v187
	v_mul_f32_e32 v121, v121, v173
	v_lshlrev_b32_e32 v173, 16, v189
	v_mul_f32_e32 v123, v123, v186
	v_add_f32_e32 v186, 1.0, v187
	v_mul_f32_e32 v187, 0xbfb8aa3b, v117
	v_rcp_f32_e32 v186, v186
	v_exp_f32_e32 v187, v187
	v_mul_f32_e32 v122, v122, v173
	v_and_b32_e32 v173, 0xffff0000, v189
	v_mul_f32_e32 v116, v116, v186
	v_add_f32_e32 v186, 1.0, v187
	v_mul_f32_e32 v187, 0xbfb8aa3b, v118
	v_rcp_f32_e32 v186, v186
	v_exp_f32_e32 v187, v187
	v_mul_f32_e32 v123, v123, v173
	v_lshlrev_b32_e32 v173, 16, v196
	v_mul_f32_e32 v173, v116, v173
	v_mul_f32_e32 v116, v117, v186
	v_add_f32_e32 v186, 1.0, v187
	v_mul_f32_e32 v187, 0xbfb8aa3b, v119
	v_rcp_f32_e32 v186, v186
	v_exp_f32_e32 v187, v187
	v_and_b32_e32 v117, 0xffff0000, v196
	v_lshlrev_b32_e32 v215, 16, v188
	v_mul_f32_e32 v188, v116, v117
	v_mul_f32_e32 v116, v118, v186
	v_add_f32_e32 v118, 1.0, v187
	v_rcp_f32_e32 v118, v118
	v_mul_f32_e32 v186, 0xbfb8aa3b, v112
	v_exp_f32_e32 v186, v186
	v_lshlrev_b32_e32 v117, 16, v197
	v_mul_f32_e32 v187, v116, v117
	v_mul_f32_e32 v116, v119, v118
	v_mul_f32_e32 v119, 0xbfb8aa3b, v113
	v_add_f32_e32 v118, 1.0, v186
	v_exp_f32_e32 v119, v119
	v_rcp_f32_e32 v118, v118
	v_and_b32_e32 v117, 0xffff0000, v197
	v_mul_f32_e32 v186, v116, v117
	v_add_f32_e32 v117, 1.0, v119
	v_mul_f32_e32 v112, v112, v118
	v_rcp_f32_e32 v117, v117
	v_mul_f32_e32 v118, 0xbfb8aa3b, v114
	v_exp_f32_e32 v118, v118
	v_lshlrev_b32_e32 v116, 16, v198
	v_mul_f32_e32 v189, v112, v116
	v_mul_f32_e32 v112, v113, v117
	v_and_b32_e32 v113, 0xffff0000, v198
	v_add_f32_e32 v116, 1.0, v118
	v_mul_f32_e32 v196, v112, v113
	v_mul_f32_e32 v112, 0xbfb8aa3b, v115
	v_rcp_f32_e32 v116, v116
	v_exp_f32_e32 v112, v112
	v_mov_b32_e32 v117, v206
	v_mov_b32_e32 v206, v211
	v_mul_f32_e32 v113, v114, v116
	v_lshlrev_b32_e32 v114, 16, v199
	v_add_f32_e32 v112, 1.0, v112
	v_mul_f32_e32 v197, v113, v114
	v_rcp_f32_e32 v114, v112
	v_mov_b32_e32 v112, v208
	v_mov_b32_e32 v113, v204
	v_mov_b32_e32 v204, v209
	v_pk_add_f32 v[112:113], v[112:113], v[204:205]
	v_mov_b32_e32 v116, v210
	v_pk_add_f32 v[112:113], v[116:117], v[112:113]
	v_mul_f32_e32 v114, v115, v114
	v_pk_add_f32 v[116:117], v[206:207], v[112:113]
	v_mov_b64_e32 v[112:113], s[14:15]
	s_mov_b32 s14, 0x3b000000
	v_pk_fma_f32 v[118:119], v[116:117], s[14:15], v[112:113] op_sel_hi:[1,0,0]
	v_and_b32_e32 v115, 0xffff0000, v199
	v_mul_f32_e32 v116, 0x4b800000, v119
	v_cmp_gt_f32_e32 vcc, s5, v119
	v_mul_f32_e32 v126, v126, v214
	v_mul_f32_e32 v120, v120, v215
	v_cndmask_b32_e32 v116, v119, v116, vcc
	v_rsq_f32_e32 v116, v116
	v_mul_f32_e32 v119, v114, v115
	v_mul_f32_e32 v114, 0x45800000, v116
	v_cndmask_b32_e32 v198, v116, v114, vcc
	v_mul_f32_e32 v114, v124, v198
	v_mul_f32_e32 v115, v125, v198
	v_cvt_pk_bf16_f32 v114, v114, v115
	v_mul_f32_e32 v115, v126, v198
	v_mul_f32_e32 v116, v127, v198
	v_cvt_pk_bf16_f32 v115, v115, v116
	v_mul_f32_e32 v116, v120, v198
	v_mul_f32_e32 v117, v121, v198
	v_cvt_pk_bf16_f32 v116, v116, v117
	v_mul_f32_e32 v117, v122, v198
	v_mul_f32_e32 v120, v123, v198
	v_cvt_pk_bf16_f32 v117, v117, v120
	global_store_dwordx4 v[190:191], v[114:117], off
	v_mul_f32_e32 v119, v119, v198
	v_cmp_gt_f32_e32 vcc, s5, v118
	v_mul_f32_e32 v114, v173, v198
	v_mul_f32_e32 v115, v188, v198
	v_cvt_pk_bf16_f32 v114, v114, v115
	v_mul_f32_e32 v115, v187, v198
	v_mul_f32_e32 v116, v186, v198
	v_cvt_pk_bf16_f32 v115, v115, v116
	v_mul_f32_e32 v116, v189, v198
	v_mul_f32_e32 v117, v196, v198
	v_cvt_pk_bf16_f32 v116, v116, v117
	v_mul_f32_e32 v117, v197, v198
	v_cvt_pk_bf16_f32 v117, v117, v119
	v_mul_f32_e32 v119, 0x4b800000, v118
	v_cndmask_b32_e32 v118, v118, v119, vcc
	global_store_dwordx4 v[190:191], v[114:117], off offset:256
	v_rsq_f32_e32 v118, v118
	v_mul_f32_e32 v123, 0xbfb8aa3b, v61
	v_mul_f32_e32 v114, 0xbfb8aa3b, v108
	v_exp_f32_e32 v116, v114
	v_mul_f32_e32 v114, 0x45800000, v118
	v_cndmask_b32_e32 v117, v118, v114, vcc
	v_mul_f32_e32 v118, 0xbfb8aa3b, v109
	v_add_f32_e32 v116, 1.0, v116
	v_rcp_f32_e32 v116, v116
	v_exp_f32_e32 v118, v118
	v_lshl_add_u64 v[114:115], s[2:3], 0, v[180:181]
	v_lshl_add_u64 v[114:115], v[114:115], 0, v[170:171]
	v_mul_f32_e32 v108, v108, v116
	v_lshlrev_b32_e32 v116, 16, v156
	v_mul_f32_e32 v108, v108, v116
	v_add_f32_e32 v116, 1.0, v118
	v_rcp_f32_e32 v116, v116
	v_mul_f32_e32 v118, 0xbfb8aa3b, v110
	v_exp_f32_e32 v118, v118
	v_mul_f32_e32 v108, v108, v117
	v_mul_f32_e32 v109, v109, v116
	v_and_b32_e32 v116, 0xffff0000, v156
	v_mul_f32_e32 v109, v109, v116
	v_add_f32_e32 v116, 1.0, v118
	v_mul_f32_e32 v118, 0xbfb8aa3b, v111
	v_rcp_f32_e32 v116, v116
	v_exp_f32_e32 v118, v118
	v_mul_f32_e32 v109, v109, v117
	v_cvt_pk_bf16_f32 v108, v108, v109
	v_mul_f32_e32 v109, v110, v116
	v_add_f32_e32 v110, 1.0, v118
	v_rcp_f32_e32 v110, v110
	v_lshlrev_b32_e32 v116, 16, v157
	v_mul_f32_e32 v109, v109, v116
	v_and_b32_e32 v116, 0xffff0000, v157
	v_mul_f32_e32 v110, v111, v110
	v_mul_f32_e32 v111, 0xbfb8aa3b, v104
	v_exp_f32_e32 v111, v111
	v_mul_f32_e32 v110, v110, v116
	v_mul_f32_e32 v109, v109, v117
	v_mul_f32_e32 v110, v110, v117
	v_add_f32_e32 v111, 1.0, v111
	v_cvt_pk_bf16_f32 v109, v109, v110
	v_mul_f32_e32 v110, 0xbfb8aa3b, v105
	v_rcp_f32_e32 v111, v111
	v_exp_f32_e32 v110, v110
	v_exp_f32_e32 v123, v123
	v_mul_f32_e32 v124, 0xbfb8aa3b, v62
	v_mul_f32_e32 v104, v104, v111
	v_lshlrev_b32_e32 v111, 16, v158
	v_add_f32_e32 v110, 1.0, v110
	v_mul_f32_e32 v104, v104, v111
	v_rcp_f32_e32 v110, v110
	v_mul_f32_e32 v111, 0xbfb8aa3b, v106
	v_exp_f32_e32 v111, v111
	v_mul_f32_e32 v104, v104, v117
	v_mul_f32_e32 v105, v105, v110
	v_and_b32_e32 v110, 0xffff0000, v158
	v_mul_f32_e32 v105, v105, v110
	v_add_f32_e32 v110, 1.0, v111
	v_rcp_f32_e32 v111, v110
	v_mul_f32_e32 v110, 0xbfb8aa3b, v107
	v_exp_f32_e32 v116, v110
	v_mul_f32_e32 v105, v105, v117
	v_cvt_pk_bf16_f32 v110, v104, v105
	v_mul_f32_e32 v104, v106, v111
	v_add_f32_e32 v105, 1.0, v116
	v_rcp_f32_e32 v105, v105
	v_lshlrev_b32_e32 v106, 16, v159
	v_mul_f32_e32 v104, v104, v106
	v_and_b32_e32 v106, 0xffff0000, v159
	v_mul_f32_e32 v105, v107, v105
	v_mul_f32_e32 v107, 0xbfb8aa3b, v100
	v_exp_f32_e32 v107, v107
	v_mul_f32_e32 v104, v104, v117
	v_mul_f32_e32 v105, v105, v106
	v_mul_f32_e32 v105, v105, v117
	v_cvt_pk_bf16_f32 v111, v104, v105
	v_add_f32_e32 v104, 1.0, v107
	v_rcp_f32_e32 v104, v104
	v_mul_f32_e32 v105, 0xbfb8aa3b, v101
	v_exp_f32_e32 v105, v105
	global_store_dwordx4 v[114:115], v[108:111], off
	v_mul_f32_e32 v100, v100, v104
	v_lshlrev_b32_e32 v104, 16, v152
	v_mul_f32_e32 v100, v100, v104
	v_add_f32_e32 v104, 1.0, v105
	v_rcp_f32_e32 v104, v104
	v_mul_f32_e32 v105, 0xbfb8aa3b, v102
	v_exp_f32_e32 v105, v105
	v_mul_f32_e32 v100, v100, v117
	v_mul_f32_e32 v101, v101, v104
	v_and_b32_e32 v104, 0xffff0000, v152
	v_mul_f32_e32 v101, v101, v104
	v_add_f32_e32 v104, 1.0, v105
	v_mul_f32_e32 v105, 0xbfb8aa3b, v103
	v_rcp_f32_e32 v104, v104
	v_exp_f32_e32 v105, v105
	v_mul_f32_e32 v101, v101, v117
	v_cvt_pk_bf16_f32 v100, v100, v101
	v_mul_f32_e32 v101, v102, v104
	v_add_f32_e32 v102, 1.0, v105
	v_rcp_f32_e32 v102, v102
	v_lshlrev_b32_e32 v104, 16, v153
	v_mul_f32_e32 v101, v101, v104
	v_and_b32_e32 v104, 0xffff0000, v153
	v_mul_f32_e32 v102, v103, v102
	v_mul_f32_e32 v103, 0xbfb8aa3b, v96
	v_exp_f32_e32 v103, v103
	v_mul_f32_e32 v102, v102, v104
	v_mul_f32_e32 v101, v101, v117
	v_mul_f32_e32 v102, v102, v117
	v_add_f32_e32 v103, 1.0, v103
	v_cvt_pk_bf16_f32 v101, v101, v102
	v_mul_f32_e32 v102, 0xbfb8aa3b, v97
	v_rcp_f32_e32 v103, v103
	v_exp_f32_e32 v102, v102
	v_add_f32_e32 v123, 1.0, v123
	v_rcp_f32_e32 v123, v123
	v_mul_f32_e32 v96, v96, v103
	v_lshlrev_b32_e32 v103, 16, v154
	v_add_f32_e32 v102, 1.0, v102
	v_mul_f32_e32 v96, v96, v103
	v_rcp_f32_e32 v102, v102
	v_mul_f32_e32 v103, 0xbfb8aa3b, v98
	v_exp_f32_e32 v103, v103
	v_mul_f32_e32 v96, v96, v117
	v_mul_f32_e32 v97, v97, v102
	v_and_b32_e32 v102, 0xffff0000, v154
	v_mul_f32_e32 v97, v97, v102
	v_add_f32_e32 v102, 1.0, v103
	v_rcp_f32_e32 v103, v102
	v_mul_f32_e32 v102, 0xbfb8aa3b, v99
	v_exp_f32_e32 v104, v102
	v_mul_f32_e32 v97, v97, v117
	v_cvt_pk_bf16_f32 v102, v96, v97
	v_mul_f32_e32 v96, v98, v103
	v_add_f32_e32 v97, 1.0, v104
	v_rcp_f32_e32 v97, v97
	v_lshlrev_b32_e32 v98, 16, v155
	v_mul_f32_e32 v96, v96, v98
	v_and_b32_e32 v98, 0xffff0000, v155
	v_mul_f32_e32 v97, v99, v97
	v_mul_f32_e32 v99, 0xbfb8aa3b, v93
	v_exp_f32_e32 v99, v99
	v_mul_f32_e32 v97, v97, v98
	v_mul_f32_e32 v96, v96, v117
	v_mul_f32_e32 v97, v97, v117
	v_cvt_pk_bf16_f32 v103, v96, v97
	global_store_dwordx4 v[114:115], v[100:103], off offset:256
	v_add_f32_e32 v99, 1.0, v99
	v_rcp_f32_e32 v99, v99
	v_mul_f32_e32 v100, 0xbfb8aa3b, v94
	v_exp_f32_e32 v100, v100
	v_mul_f32_e32 v98, 0xbfb8aa3b, v92
	v_mul_f32_e32 v93, v93, v99
	v_exp_f32_e32 v98, v98
	v_add_f32_e32 v99, 1.0, v100
	v_mul_f32_e32 v100, 0xbfb8aa3b, v95
	v_rcp_f32_e32 v99, v99
	v_exp_f32_e32 v100, v100
	v_add_f32_e32 v98, 1.0, v98
	v_rcp_f32_e32 v98, v98
	v_mul_f32_e32 v94, v94, v99
	v_add_f32_e32 v99, 1.0, v100
	v_mul_f32_e32 v100, 0xbfb8aa3b, v88
	v_rcp_f32_e32 v99, v99
	v_exp_f32_e32 v100, v100
	v_mul_f32_e32 v92, v92, v98
	v_lshlrev_b32_e32 v98, 16, v148
	v_mul_f32_e32 v95, v95, v99
	v_add_f32_e32 v99, 1.0, v100
	v_mul_f32_e32 v100, 0xbfb8aa3b, v89
	v_rcp_f32_e32 v99, v99
	v_exp_f32_e32 v100, v100
	v_mul_f32_e32 v92, v92, v98
	v_and_b32_e32 v98, 0xffff0000, v148
	v_mul_f32_e32 v88, v88, v99
	v_add_f32_e32 v99, 1.0, v100
	v_mul_f32_e32 v100, 0xbfb8aa3b, v90
	v_rcp_f32_e32 v99, v99
	v_exp_f32_e32 v100, v100
	v_mul_f32_e32 v93, v93, v98
	v_lshlrev_b32_e32 v98, 16, v149
	v_mul_f32_e32 v89, v89, v99
	v_add_f32_e32 v99, 1.0, v100
	v_mul_f32_e32 v100, 0xbfb8aa3b, v91
	v_rcp_f32_e32 v99, v99
	v_exp_f32_e32 v100, v100
	v_mul_f32_e32 v94, v94, v98
	v_and_b32_e32 v98, 0xffff0000, v149
	v_mul_f32_e32 v90, v90, v99
	v_add_f32_e32 v99, 1.0, v100
	v_mul_f32_e32 v100, 0xbfb8aa3b, v84
	v_rcp_f32_e32 v99, v99
	v_exp_f32_e32 v100, v100
	v_mul_f32_e32 v95, v95, v98
	v_lshlrev_b32_e32 v98, 16, v150
	v_mul_f32_e32 v91, v91, v99
	v_add_f32_e32 v99, 1.0, v100
	v_mul_f32_e32 v100, 0xbfb8aa3b, v85
	v_rcp_f32_e32 v99, v99
	v_exp_f32_e32 v100, v100
	v_mul_f32_e32 v88, v88, v98
	v_and_b32_e32 v98, 0xffff0000, v150
	v_mul_f32_e32 v84, v84, v99
	v_add_f32_e32 v99, 1.0, v100
	v_mul_f32_e32 v100, 0xbfb8aa3b, v86
	v_rcp_f32_e32 v99, v99
	v_exp_f32_e32 v100, v100
	v_mul_f32_e32 v89, v89, v98
	v_lshlrev_b32_e32 v98, 16, v151
	v_mul_f32_e32 v90, v90, v98
	v_and_b32_e32 v98, 0xffff0000, v151
	v_mul_f32_e32 v91, v91, v98
	v_lshlrev_b32_e32 v98, 16, v140
	v_mul_f32_e32 v98, v84, v98
	v_mul_f32_e32 v84, v85, v99
	v_add_f32_e32 v99, 1.0, v100
	v_mul_f32_e32 v100, 0xbfb8aa3b, v87
	v_rcp_f32_e32 v99, v99
	v_exp_f32_e32 v100, v100
	v_and_b32_e32 v85, 0xffff0000, v140
	v_mul_f32_e32 v101, v84, v85
	v_mul_f32_e32 v84, v86, v99
	v_add_f32_e32 v86, 1.0, v100
	v_rcp_f32_e32 v86, v86
	v_mul_f32_e32 v99, 0xbfb8aa3b, v80
	v_exp_f32_e32 v99, v99
	v_lshlrev_b32_e32 v85, 16, v141
	v_mul_f32_e32 v100, v84, v85
	v_mul_f32_e32 v84, v87, v86
	v_mul_f32_e32 v87, 0xbfb8aa3b, v81
	v_add_f32_e32 v86, 1.0, v99
	v_exp_f32_e32 v87, v87
	v_rcp_f32_e32 v86, v86
	v_and_b32_e32 v85, 0xffff0000, v141
	v_mul_f32_e32 v99, v84, v85
	v_add_f32_e32 v85, 1.0, v87
	v_mul_f32_e32 v80, v80, v86
	v_rcp_f32_e32 v85, v85
	v_mul_f32_e32 v86, 0xbfb8aa3b, v82
	v_exp_f32_e32 v86, v86
	v_lshlrev_b32_e32 v84, 16, v142
	v_mul_f32_e32 v87, v80, v84
	v_mul_f32_e32 v80, v81, v85
	v_and_b32_e32 v81, 0xffff0000, v142
	v_add_f32_e32 v84, 1.0, v86
	v_mul_f32_e32 v86, v80, v81
	v_mul_f32_e32 v80, 0xbfb8aa3b, v83
	v_rcp_f32_e32 v84, v84
	v_exp_f32_e32 v80, v80
	v_mov_b32_e32 v85, v138
	v_mov_b32_e32 v138, v147
	v_mul_f32_e32 v81, v82, v84
	v_lshlrev_b32_e32 v82, 16, v143
	v_add_f32_e32 v80, 1.0, v80
	v_mul_f32_e32 v102, v81, v82
	v_rcp_f32_e32 v82, v80
	v_mov_b32_e32 v80, v144
	v_mov_b32_e32 v81, v136
	v_mov_b32_e32 v136, v145
	v_pk_add_f32 v[80:81], v[80:81], v[136:137]
	v_mov_b32_e32 v84, v146
	v_pk_add_f32 v[80:81], v[84:85], v[80:81]
	v_lshl_add_u64 v[96:97], s[2:3], 0, v[178:179]
	v_pk_add_f32 v[80:81], v[138:139], v[80:81]
	v_lshl_add_u64 v[96:97], v[96:97], 0, v[170:171]
	v_pk_fma_f32 v[84:85], v[80:81], s[14:15], v[112:113] op_sel_hi:[1,0,0]
	v_mul_f32_e32 v81, v83, v82
	v_mul_f32_e32 v80, 0x4b800000, v85
	v_cmp_gt_f32_e32 vcc, s5, v85
	v_and_b32_e32 v82, 0xffff0000, v143
	v_exp_f32_e32 v124, v124
	v_cndmask_b32_e32 v80, v85, v80, vcc
	v_rsq_f32_e32 v80, v80
	v_mul_f32_e32 v85, v81, v82
	v_mul_f32_e32 v61, v61, v123
	v_mul_f32_e32 v123, 0xbfb8aa3b, v63
	v_mul_f32_e32 v81, 0x45800000, v80
	v_cndmask_b32_e32 v103, v80, v81, vcc
	v_mul_f32_e32 v80, v92, v103
	v_mul_f32_e32 v81, v93, v103
	v_cvt_pk_bf16_f32 v80, v80, v81
	v_mul_f32_e32 v81, v94, v103
	v_mul_f32_e32 v82, v95, v103
	v_cvt_pk_bf16_f32 v81, v81, v82
	v_mul_f32_e32 v82, v88, v103
	v_mul_f32_e32 v83, v89, v103
	v_cvt_pk_bf16_f32 v82, v82, v83
	v_mul_f32_e32 v83, v90, v103
	v_mul_f32_e32 v88, v91, v103
	v_cvt_pk_bf16_f32 v83, v83, v88
	global_store_dwordx4 v[96:97], v[80:83], off
	v_mul_f32_e32 v85, v85, v103
	v_cmp_gt_f32_e32 vcc, s5, v84
	v_mul_f32_e32 v80, v98, v103
	v_mul_f32_e32 v81, v101, v103
	v_cvt_pk_bf16_f32 v80, v80, v81
	v_mul_f32_e32 v81, v100, v103
	v_mul_f32_e32 v82, v99, v103
	v_cvt_pk_bf16_f32 v81, v81, v82
	v_mul_f32_e32 v82, v87, v103
	v_mul_f32_e32 v83, v86, v103
	v_cvt_pk_bf16_f32 v82, v82, v83
	v_mul_f32_e32 v83, v102, v103
	v_cvt_pk_bf16_f32 v83, v83, v85
	v_mul_f32_e32 v85, 0x4b800000, v84
	v_cndmask_b32_e32 v84, v84, v85, vcc
	global_store_dwordx4 v[96:97], v[80:83], off offset:256
	v_rsq_f32_e32 v84, v84
	v_exp_f32_e32 v123, v123
	v_mul_f32_e32 v80, 0xbfb8aa3b, v76
	v_exp_f32_e32 v82, v80
	v_mul_f32_e32 v80, 0x45800000, v84
	v_cndmask_b32_e32 v83, v84, v80, vcc
	v_mul_f32_e32 v84, 0xbfb8aa3b, v77
	v_add_f32_e32 v82, 1.0, v82
	v_rcp_f32_e32 v82, v82
	v_exp_f32_e32 v84, v84
	v_lshl_add_u64 v[80:81], s[2:3], 0, v[176:177]
	v_lshl_add_u64 v[80:81], v[80:81], 0, v[170:171]
	v_mul_f32_e32 v76, v76, v82
	v_lshlrev_b32_e32 v82, 16, v132
	v_mul_f32_e32 v76, v76, v82
	v_add_f32_e32 v82, 1.0, v84
	v_rcp_f32_e32 v82, v82
	v_mul_f32_e32 v84, 0xbfb8aa3b, v78
	v_exp_f32_e32 v84, v84
	v_mul_f32_e32 v76, v76, v83
	v_mul_f32_e32 v77, v77, v82
	v_and_b32_e32 v82, 0xffff0000, v132
	v_mul_f32_e32 v77, v77, v82
	v_add_f32_e32 v82, 1.0, v84
	v_mul_f32_e32 v84, 0xbfb8aa3b, v79
	v_rcp_f32_e32 v82, v82
	v_exp_f32_e32 v84, v84
	v_mul_f32_e32 v77, v77, v83
	v_cvt_pk_bf16_f32 v76, v76, v77
	v_mul_f32_e32 v77, v78, v82
	v_add_f32_e32 v78, 1.0, v84
	v_rcp_f32_e32 v78, v78
	v_lshlrev_b32_e32 v82, 16, v133
	v_mul_f32_e32 v77, v77, v82
	v_and_b32_e32 v82, 0xffff0000, v133
	v_mul_f32_e32 v78, v79, v78
	v_mul_f32_e32 v79, 0xbfb8aa3b, v72
	v_exp_f32_e32 v79, v79
	v_mul_f32_e32 v78, v78, v82
	v_mul_f32_e32 v77, v77, v83
	v_mul_f32_e32 v78, v78, v83
	v_add_f32_e32 v79, 1.0, v79
	v_cvt_pk_bf16_f32 v77, v77, v78
	v_mul_f32_e32 v78, 0xbfb8aa3b, v73
	v_rcp_f32_e32 v79, v79
	v_exp_f32_e32 v78, v78
	v_mul_f32_e32 v72, v72, v79
	v_lshlrev_b32_e32 v79, 16, v134
	v_add_f32_e32 v78, 1.0, v78
	v_mul_f32_e32 v72, v72, v79
	v_rcp_f32_e32 v78, v78
	v_mul_f32_e32 v79, 0xbfb8aa3b, v74
	v_exp_f32_e32 v79, v79
	v_mul_f32_e32 v72, v72, v83
	v_mul_f32_e32 v73, v73, v78
	v_and_b32_e32 v78, 0xffff0000, v134
	v_mul_f32_e32 v73, v73, v78
	v_add_f32_e32 v78, 1.0, v79
	v_rcp_f32_e32 v79, v78
	v_mul_f32_e32 v78, 0xbfb8aa3b, v75
	v_exp_f32_e32 v82, v78
	v_mul_f32_e32 v73, v73, v83
	v_cvt_pk_bf16_f32 v78, v72, v73
	v_mul_f32_e32 v72, v74, v79
	v_add_f32_e32 v73, 1.0, v82
	v_rcp_f32_e32 v73, v73
	v_lshlrev_b32_e32 v74, 16, v135
	v_mul_f32_e32 v72, v72, v74
	v_and_b32_e32 v74, 0xffff0000, v135
	v_mul_f32_e32 v73, v75, v73
	v_mul_f32_e32 v75, 0xbfb8aa3b, v68
	v_exp_f32_e32 v75, v75
	v_mul_f32_e32 v72, v72, v83
	v_mul_f32_e32 v73, v73, v74
	v_mul_f32_e32 v73, v73, v83
	v_cvt_pk_bf16_f32 v79, v72, v73
	v_add_f32_e32 v72, 1.0, v75
	v_rcp_f32_e32 v72, v72
	v_mul_f32_e32 v73, 0xbfb8aa3b, v69
	v_exp_f32_e32 v73, v73
	global_store_dwordx4 v[80:81], v[76:79], off
	v_mul_f32_e32 v68, v68, v72
	v_lshlrev_b32_e32 v72, 16, v128
	v_mul_f32_e32 v68, v68, v72
	v_add_f32_e32 v72, 1.0, v73
	v_rcp_f32_e32 v72, v72
	v_mul_f32_e32 v73, 0xbfb8aa3b, v70
	v_exp_f32_e32 v73, v73
	v_mul_f32_e32 v68, v68, v83
	v_mul_f32_e32 v69, v69, v72
	v_and_b32_e32 v72, 0xffff0000, v128
	v_mul_f32_e32 v69, v69, v72
	v_add_f32_e32 v72, 1.0, v73
	v_mul_f32_e32 v73, 0xbfb8aa3b, v71
	v_rcp_f32_e32 v72, v72
	v_exp_f32_e32 v73, v73
	v_mul_f32_e32 v69, v69, v83
	v_cvt_pk_bf16_f32 v68, v68, v69
	v_mul_f32_e32 v69, v70, v72
	v_add_f32_e32 v70, 1.0, v73
	v_rcp_f32_e32 v70, v70
	v_lshlrev_b32_e32 v72, 16, v129
	v_mul_f32_e32 v69, v69, v72
	v_and_b32_e32 v72, 0xffff0000, v129
	v_mul_f32_e32 v70, v71, v70
	v_mul_f32_e32 v71, 0xbfb8aa3b, v64
	v_exp_f32_e32 v71, v71
	v_mul_f32_e32 v70, v70, v72
	v_mul_f32_e32 v69, v69, v83
	v_mul_f32_e32 v70, v70, v83
	v_add_f32_e32 v71, 1.0, v71
	v_cvt_pk_bf16_f32 v69, v69, v70
	v_mul_f32_e32 v70, 0xbfb8aa3b, v65
	v_rcp_f32_e32 v71, v71
	v_exp_f32_e32 v70, v70
	v_mul_f32_e32 v64, v64, v71
	v_lshlrev_b32_e32 v71, 16, v130
	v_add_f32_e32 v70, 1.0, v70
	v_mul_f32_e32 v64, v64, v71
	v_rcp_f32_e32 v70, v70
	v_mul_f32_e32 v71, 0xbfb8aa3b, v66
	v_exp_f32_e32 v71, v71
	v_mul_f32_e32 v64, v64, v83
	v_mul_f32_e32 v65, v65, v70
	v_and_b32_e32 v70, 0xffff0000, v130
	v_mul_f32_e32 v65, v65, v70
	v_add_f32_e32 v70, 1.0, v71
	v_rcp_f32_e32 v71, v70
	v_mul_f32_e32 v70, 0xbfb8aa3b, v67
	v_exp_f32_e32 v72, v70
	v_mul_f32_e32 v65, v65, v83
	v_cvt_pk_bf16_f32 v70, v64, v65
	v_mul_f32_e32 v64, v66, v71
	v_add_f32_e32 v65, 1.0, v72
	v_rcp_f32_e32 v65, v65
	v_lshlrev_b32_e32 v66, 16, v131
	v_mul_f32_e32 v64, v64, v66
	v_and_b32_e32 v66, 0xffff0000, v131
	v_mul_f32_e32 v65, v67, v65
	v_mul_f32_e32 v64, v64, v83
	v_mul_f32_e32 v65, v65, v66
	v_mul_f32_e32 v65, v65, v83
	v_cvt_pk_bf16_f32 v71, v64, v65
	v_add_u32_e32 v64, 0x80, v172
	v_ashrrev_i32_e32 v65, 31, v64
	v_lshlrev_b64 v[110:111], 13, v[64:65]
	v_lshl_add_u64 v[66:67], v[174:175], 0, v[110:111]
	global_load_dwordx4 v[102:105], v[66:67], off
	v_lshlrev_b64 v[64:65], 7, v[64:65]
	global_store_dwordx4 v[80:81], v[68:71], off offset:256
	v_lshl_add_u64 v[64:65], s[12:13], 0, v[64:65]
	global_load_dwordx4 v[106:109], v[64:65], off
	v_add_u32_e32 v64, 0x90, v172
	v_ashrrev_i32_e32 v65, 31, v64
	v_lshlrev_b64 v[68:69], 7, v[64:65]
	v_lshl_add_u64 v[68:69], s[12:13], 0, v[68:69]
	global_load_dwordx4 v[114:117], v[66:67], off offset:256
	global_load_dwordx4 v[118:121], v[68:69], off
	v_lshlrev_b64 v[100:101], 13, v[64:65]
	v_lshl_add_u64 v[64:65], v[174:175], 0, v[100:101]
	global_load_dwordx4 v[92:95], v[64:65], off
	global_load_dwordx4 v[88:91], v[64:65], off offset:256
	v_add_u32_e32 v64, 0xa0, v172
	v_ashrrev_i32_e32 v65, 31, v64
	v_lshlrev_b64 v[66:67], 7, v[64:65]
	v_lshl_add_u64 v[66:67], s[12:13], 0, v[66:67]
	v_lshlrev_b64 v[98:99], 13, v[64:65]
	v_lshl_add_u64 v[64:65], v[174:175], 0, v[98:99]
	global_load_dwordx4 v[72:75], v[66:67], off
	global_load_dwordx4 v[84:87], v[64:65], off
	v_add_u32_e32 v66, 0xb0, v172
	v_ashrrev_i32_e32 v67, 31, v66
	v_lshlrev_b64 v[68:69], 7, v[66:67]
	v_lshlrev_b64 v[96:97], 13, v[66:67]
	v_mul_f32_e32 v66, 0xbfb8aa3b, v60
	v_exp_f32_e32 v122, v66
	v_lshl_add_u64 v[68:69], s[12:13], 0, v[68:69]
	global_load_dwordx4 v[76:79], v[64:65], off offset:256
	global_load_dwordx4 v[80:83], v[68:69], off
	v_lshl_add_u64 v[64:65], v[174:175], 0, v[96:97]
	v_add_f32_e32 v122, 1.0, v122
	v_rcp_f32_e32 v122, v122
	global_load_dwordx4 v[68:71], v[64:65], off
	s_nop 0
	global_load_dwordx4 v[64:67], v[64:65], off offset:256
	v_lshl_add_u64 v[110:111], s[2:3], 0, v[110:111]
	v_lshl_add_u64 v[110:111], v[110:111], 0, v[170:171]
	v_mul_f32_e32 v60, v60, v122
	s_mov_b32 s13, s4
	s_mov_b32 s12, s6
	s_waitcnt vmcnt(0)
	v_lshlrev_b32_e32 v122, 16, v102
	v_mul_f32_e32 v60, v60, v122
	v_add_f32_e32 v122, 1.0, v124
	v_rcp_f32_e32 v122, v122
	v_and_b32_e32 v102, 0xffff0000, v102
	v_mul_f32_e32 v61, v61, v102
	v_lshlrev_b32_e32 v102, 16, v103
	v_mul_f32_e32 v62, v62, v122
	v_add_f32_e32 v122, 1.0, v123
	v_mul_f32_e32 v123, 0xbfb8aa3b, v56
	v_rcp_f32_e32 v122, v122
	v_exp_f32_e32 v123, v123
	v_mul_f32_e32 v62, v62, v102
	v_and_b32_e32 v102, 0xffff0000, v103
	v_mul_f32_e32 v63, v63, v122
	v_add_f32_e32 v103, 1.0, v123
	v_mul_f32_e32 v122, 0xbfb8aa3b, v57
	v_rcp_f32_e32 v103, v103
	v_exp_f32_e32 v122, v122
	v_mul_f32_e32 v63, v63, v102
	v_lshlrev_b32_e32 v102, 16, v104
	v_mul_f32_e32 v56, v56, v103
	v_add_f32_e32 v103, 1.0, v122
	v_mul_f32_e32 v122, 0xbfb8aa3b, v58
	v_rcp_f32_e32 v103, v103
	v_exp_f32_e32 v122, v122
	v_mul_f32_e32 v56, v56, v102
	v_and_b32_e32 v102, 0xffff0000, v104
	v_mul_f32_e32 v57, v57, v103
	v_add_f32_e32 v103, 1.0, v122
	v_mul_f32_e32 v104, 0xbfb8aa3b, v59
	v_rcp_f32_e32 v103, v103
	v_exp_f32_e32 v104, v104
	v_mul_f32_e32 v57, v57, v102
	v_lshlrev_b32_e32 v102, 16, v105
	v_mul_f32_e32 v58, v58, v103
	v_add_f32_e32 v103, 1.0, v104
	v_mul_f32_e32 v104, 0xbfb8aa3b, v52
	v_rcp_f32_e32 v103, v103
	v_exp_f32_e32 v104, v104
	v_mul_f32_e32 v58, v58, v102
	v_and_b32_e32 v102, 0xffff0000, v105
	v_mul_f32_e32 v59, v59, v103
	v_add_f32_e32 v103, 1.0, v104
	v_mul_f32_e32 v104, 0xbfb8aa3b, v53
	v_rcp_f32_e32 v103, v103
	v_exp_f32_e32 v104, v104
	v_mul_f32_e32 v59, v59, v102
	v_lshlrev_b32_e32 v102, 16, v114
	v_mul_f32_e32 v52, v52, v103
	v_add_f32_e32 v103, 1.0, v104
	v_mul_f32_e32 v104, 0xbfb8aa3b, v54
	v_rcp_f32_e32 v103, v103
	v_exp_f32_e32 v104, v104
	v_mul_f32_e32 v102, v52, v102
	v_mul_f32_e32 v52, v53, v103
	v_add_f32_e32 v103, 1.0, v104
	v_mul_f32_e32 v104, 0xbfb8aa3b, v55
	v_rcp_f32_e32 v103, v103
	v_exp_f32_e32 v104, v104
	v_and_b32_e32 v53, 0xffff0000, v114
	v_mul_f32_e32 v105, v52, v53
	v_mul_f32_e32 v52, v54, v103
	v_add_f32_e32 v54, 1.0, v104
	v_rcp_f32_e32 v54, v54
	v_mul_f32_e32 v103, 0xbfb8aa3b, v48
	v_exp_f32_e32 v103, v103
	v_lshlrev_b32_e32 v53, 16, v115
	v_mul_f32_e32 v104, v52, v53
	v_mul_f32_e32 v52, v55, v54
	v_mul_f32_e32 v55, 0xbfb8aa3b, v49
	v_add_f32_e32 v54, 1.0, v103
	v_exp_f32_e32 v55, v55
	v_rcp_f32_e32 v54, v54
	v_and_b32_e32 v53, 0xffff0000, v115
	v_mul_f32_e32 v103, v52, v53
	v_add_f32_e32 v53, 1.0, v55
	v_mul_f32_e32 v48, v48, v54
	v_rcp_f32_e32 v53, v53
	v_mul_f32_e32 v54, 0xbfb8aa3b, v50
	v_exp_f32_e32 v54, v54
	v_lshlrev_b32_e32 v52, 16, v116
	v_mul_f32_e32 v55, v48, v52
	v_mul_f32_e32 v48, v49, v53
	v_and_b32_e32 v49, 0xffff0000, v116
	v_add_f32_e32 v52, 1.0, v54
	v_mul_f32_e32 v54, v48, v49
	v_mul_f32_e32 v48, 0xbfb8aa3b, v51
	v_rcp_f32_e32 v52, v52
	v_exp_f32_e32 v48, v48
	v_mov_b32_e32 v53, v108
	v_mov_b32_e32 v108, v121
	v_mul_f32_e32 v49, v50, v52
	v_lshlrev_b32_e32 v50, 16, v117
	v_add_f32_e32 v48, 1.0, v48
	v_mul_f32_e32 v114, v49, v50
	v_rcp_f32_e32 v50, v48
	v_mov_b32_e32 v48, v118
	v_mov_b32_e32 v49, v106
	v_mov_b32_e32 v106, v119
	v_pk_add_f32 v[48:49], v[48:49], v[106:107]
	v_mov_b32_e32 v52, v120
	v_pk_add_f32 v[48:49], v[52:53], v[48:49]
	s_nop 0
	v_pk_add_f32 v[48:49], v[108:109], v[48:49]
	s_nop 0
	v_pk_fma_f32 v[52:53], v[48:49], s[14:15], v[112:113] op_sel_hi:[1,0,0]
	v_mul_f32_e32 v49, v51, v50
	v_mul_f32_e32 v48, 0x4b800000, v53
	v_cmp_gt_f32_e32 vcc, s5, v53
	v_and_b32_e32 v50, 0xffff0000, v117
	s_nop 0
	v_cndmask_b32_e32 v48, v53, v48, vcc
	v_rsq_f32_e32 v48, v48
	v_mul_f32_e32 v53, v49, v50
	v_mul_f32_e32 v49, 0x45800000, v48
	v_cndmask_b32_e32 v106, v48, v49, vcc
	v_mul_f32_e32 v48, v60, v106
	v_mul_f32_e32 v49, v61, v106
	v_cvt_pk_bf16_f32 v48, v48, v49
	v_mul_f32_e32 v49, v62, v106
	v_mul_f32_e32 v50, v63, v106
	v_cvt_pk_bf16_f32 v49, v49, v50
	v_mul_f32_e32 v50, v56, v106
	v_mul_f32_e32 v51, v57, v106
	v_cvt_pk_bf16_f32 v50, v50, v51
	v_mul_f32_e32 v51, v58, v106
	v_mul_f32_e32 v56, v59, v106
	v_cvt_pk_bf16_f32 v51, v51, v56
	global_store_dwordx4 v[110:111], v[48:51], off
	v_mul_f32_e32 v53, v53, v106
	v_cmp_gt_f32_e32 vcc, s5, v52
	v_mul_f32_e32 v48, v102, v106
	v_mul_f32_e32 v49, v105, v106
	v_cvt_pk_bf16_f32 v48, v48, v49
	v_mul_f32_e32 v49, v104, v106
	v_mul_f32_e32 v50, v103, v106
	v_cvt_pk_bf16_f32 v49, v49, v50
	v_mul_f32_e32 v50, v55, v106
	v_mul_f32_e32 v51, v54, v106
	v_cvt_pk_bf16_f32 v50, v50, v51
	v_mul_f32_e32 v51, v114, v106
	v_cvt_pk_bf16_f32 v51, v51, v53
	v_mul_f32_e32 v53, 0x4b800000, v52
	v_cndmask_b32_e32 v52, v52, v53, vcc
	global_store_dwordx4 v[110:111], v[48:51], off offset:256
	v_rsq_f32_e32 v52, v52
	s_nop 0
	v_mul_f32_e32 v48, 0xbfb8aa3b, v44
	v_exp_f32_e32 v50, v48
	v_mul_f32_e32 v48, 0x45800000, v52
	v_cndmask_b32_e32 v51, v52, v48, vcc
	v_mul_f32_e32 v52, 0xbfb8aa3b, v45
	v_add_f32_e32 v50, 1.0, v50
	v_rcp_f32_e32 v50, v50
	v_exp_f32_e32 v52, v52
	v_lshl_add_u64 v[48:49], s[2:3], 0, v[100:101]
	v_lshl_add_u64 v[48:49], v[48:49], 0, v[170:171]
	v_mul_f32_e32 v44, v44, v50
	v_lshlrev_b32_e32 v50, 16, v92
	v_mul_f32_e32 v44, v44, v50
	v_add_f32_e32 v50, 1.0, v52
	v_rcp_f32_e32 v50, v50
	v_mul_f32_e32 v52, 0xbfb8aa3b, v46
	v_exp_f32_e32 v52, v52
	v_mul_f32_e32 v44, v44, v51
	v_mul_f32_e32 v45, v45, v50
	v_and_b32_e32 v50, 0xffff0000, v92
	v_mul_f32_e32 v45, v45, v50
	v_add_f32_e32 v50, 1.0, v52
	v_mul_f32_e32 v52, 0xbfb8aa3b, v47
	v_rcp_f32_e32 v50, v50
	v_exp_f32_e32 v52, v52
	v_mul_f32_e32 v45, v45, v51
	v_cvt_pk_bf16_f32 v44, v44, v45
	v_mul_f32_e32 v45, v46, v50
	v_add_f32_e32 v46, 1.0, v52
	v_rcp_f32_e32 v46, v46
	v_lshlrev_b32_e32 v50, 16, v93
	v_mul_f32_e32 v45, v45, v50
	v_and_b32_e32 v50, 0xffff0000, v93
	v_mul_f32_e32 v46, v47, v46
	v_mul_f32_e32 v47, 0xbfb8aa3b, v40
	v_exp_f32_e32 v47, v47
	v_mul_f32_e32 v46, v46, v50
	v_mul_f32_e32 v45, v45, v51
	v_mul_f32_e32 v46, v46, v51
	v_add_f32_e32 v47, 1.0, v47
	v_cvt_pk_bf16_f32 v45, v45, v46
	v_mul_f32_e32 v46, 0xbfb8aa3b, v41
	v_rcp_f32_e32 v47, v47
	v_exp_f32_e32 v46, v46
	v_mul_f32_e32 v40, v40, v47
	v_lshlrev_b32_e32 v47, 16, v94
	v_add_f32_e32 v46, 1.0, v46
	v_mul_f32_e32 v40, v40, v47
	v_rcp_f32_e32 v46, v46
	v_mul_f32_e32 v47, 0xbfb8aa3b, v42
	v_exp_f32_e32 v47, v47
	v_mul_f32_e32 v40, v40, v51
	v_mul_f32_e32 v41, v41, v46
	v_and_b32_e32 v46, 0xffff0000, v94
	v_mul_f32_e32 v41, v41, v46
	v_add_f32_e32 v46, 1.0, v47
	v_rcp_f32_e32 v47, v46
	v_mul_f32_e32 v46, 0xbfb8aa3b, v43
	v_exp_f32_e32 v50, v46
	v_mul_f32_e32 v41, v41, v51
	v_cvt_pk_bf16_f32 v46, v40, v41
	v_mul_f32_e32 v40, v42, v47
	v_add_f32_e32 v41, 1.0, v50
	v_rcp_f32_e32 v41, v41
	v_lshlrev_b32_e32 v42, 16, v95
	v_mul_f32_e32 v40, v40, v42
	v_and_b32_e32 v42, 0xffff0000, v95
	v_mul_f32_e32 v41, v43, v41
	v_mul_f32_e32 v43, 0xbfb8aa3b, v36
	v_exp_f32_e32 v43, v43
	v_mul_f32_e32 v40, v40, v51
	v_mul_f32_e32 v41, v41, v42
	v_mul_f32_e32 v41, v41, v51
	v_cvt_pk_bf16_f32 v47, v40, v41
	v_add_f32_e32 v40, 1.0, v43
	v_rcp_f32_e32 v40, v40
	v_mul_f32_e32 v41, 0xbfb8aa3b, v37
	v_exp_f32_e32 v41, v41
	global_store_dwordx4 v[48:49], v[44:47], off
	v_mul_f32_e32 v36, v36, v40
	v_lshlrev_b32_e32 v40, 16, v88
	v_mul_f32_e32 v36, v36, v40
	v_add_f32_e32 v40, 1.0, v41
	v_rcp_f32_e32 v40, v40
	v_mul_f32_e32 v41, 0xbfb8aa3b, v38
	v_exp_f32_e32 v41, v41
	v_mul_f32_e32 v36, v36, v51
	v_mul_f32_e32 v37, v37, v40
	v_and_b32_e32 v40, 0xffff0000, v88
	v_mul_f32_e32 v37, v37, v40
	v_add_f32_e32 v40, 1.0, v41
	v_mul_f32_e32 v41, 0xbfb8aa3b, v39
	v_rcp_f32_e32 v40, v40
	v_exp_f32_e32 v41, v41
	v_mul_f32_e32 v37, v37, v51
	v_cvt_pk_bf16_f32 v36, v36, v37
	v_mul_f32_e32 v37, v38, v40
	v_add_f32_e32 v38, 1.0, v41
	v_rcp_f32_e32 v38, v38
	v_lshlrev_b32_e32 v40, 16, v89
	v_mul_f32_e32 v37, v37, v40
	v_and_b32_e32 v40, 0xffff0000, v89
	v_mul_f32_e32 v38, v39, v38
	v_mul_f32_e32 v39, 0xbfb8aa3b, v32
	v_exp_f32_e32 v39, v39
	v_mul_f32_e32 v38, v38, v40
	v_mul_f32_e32 v37, v37, v51
	v_mul_f32_e32 v38, v38, v51
	v_add_f32_e32 v39, 1.0, v39
	v_cvt_pk_bf16_f32 v37, v37, v38
	v_mul_f32_e32 v38, 0xbfb8aa3b, v33
	v_rcp_f32_e32 v39, v39
	v_exp_f32_e32 v38, v38
	v_mul_f32_e32 v32, v32, v39
	v_lshlrev_b32_e32 v39, 16, v90
	v_add_f32_e32 v38, 1.0, v38
	v_mul_f32_e32 v32, v32, v39
	v_rcp_f32_e32 v38, v38
	v_mul_f32_e32 v39, 0xbfb8aa3b, v34
	v_exp_f32_e32 v39, v39
	v_mul_f32_e32 v32, v32, v51
	v_mul_f32_e32 v33, v33, v38
	v_and_b32_e32 v38, 0xffff0000, v90
	v_mul_f32_e32 v33, v33, v38
	v_add_f32_e32 v38, 1.0, v39
	v_rcp_f32_e32 v39, v38
	v_mul_f32_e32 v38, 0xbfb8aa3b, v35
	v_exp_f32_e32 v40, v38
	v_mul_f32_e32 v33, v33, v51
	v_cvt_pk_bf16_f32 v38, v32, v33
	v_mul_f32_e32 v32, v34, v39
	v_add_f32_e32 v33, 1.0, v40
	v_rcp_f32_e32 v33, v33
	v_lshlrev_b32_e32 v34, 16, v91
	v_mul_f32_e32 v32, v32, v34
	v_and_b32_e32 v34, 0xffff0000, v91
	v_mul_f32_e32 v33, v35, v33
	v_mul_f32_e32 v35, 0xbfb8aa3b, v29
	v_exp_f32_e32 v35, v35
	v_mul_f32_e32 v33, v33, v34
	v_mul_f32_e32 v32, v32, v51
	v_mul_f32_e32 v33, v33, v51
	v_cvt_pk_bf16_f32 v39, v32, v33
	global_store_dwordx4 v[48:49], v[36:39], off offset:256
	v_add_f32_e32 v35, 1.0, v35
	v_rcp_f32_e32 v35, v35
	v_mul_f32_e32 v36, 0xbfb8aa3b, v30
	v_exp_f32_e32 v36, v36
	v_mul_f32_e32 v34, 0xbfb8aa3b, v28
	v_mul_f32_e32 v29, v29, v35
	v_exp_f32_e32 v34, v34
	v_add_f32_e32 v35, 1.0, v36
	v_mul_f32_e32 v36, 0xbfb8aa3b, v31
	v_rcp_f32_e32 v35, v35
	v_exp_f32_e32 v36, v36
	v_add_f32_e32 v34, 1.0, v34
	v_rcp_f32_e32 v34, v34
	v_mul_f32_e32 v30, v30, v35
	v_add_f32_e32 v35, 1.0, v36
	v_mul_f32_e32 v36, 0xbfb8aa3b, v24
	v_rcp_f32_e32 v35, v35
	v_exp_f32_e32 v36, v36
	v_mul_f32_e32 v28, v28, v34
	v_lshlrev_b32_e32 v34, 16, v84
	v_mul_f32_e32 v31, v31, v35
	v_add_f32_e32 v35, 1.0, v36
	v_mul_f32_e32 v36, 0xbfb8aa3b, v25
	v_rcp_f32_e32 v35, v35
	v_exp_f32_e32 v36, v36
	v_mul_f32_e32 v28, v28, v34
	v_and_b32_e32 v34, 0xffff0000, v84
	v_mul_f32_e32 v24, v24, v35
	v_add_f32_e32 v35, 1.0, v36
	v_mul_f32_e32 v36, 0xbfb8aa3b, v26
	v_rcp_f32_e32 v35, v35
	v_exp_f32_e32 v36, v36
	v_mul_f32_e32 v29, v29, v34
	v_lshlrev_b32_e32 v34, 16, v85
	v_mul_f32_e32 v25, v25, v35
	v_add_f32_e32 v35, 1.0, v36
	v_mul_f32_e32 v36, 0xbfb8aa3b, v27
	v_rcp_f32_e32 v35, v35
	v_exp_f32_e32 v36, v36
	v_mul_f32_e32 v30, v30, v34
	v_and_b32_e32 v34, 0xffff0000, v85
	v_mul_f32_e32 v26, v26, v35
	v_add_f32_e32 v35, 1.0, v36
	v_mul_f32_e32 v36, 0xbfb8aa3b, v20
	v_rcp_f32_e32 v35, v35
	v_exp_f32_e32 v36, v36
	v_mul_f32_e32 v31, v31, v34
	v_lshlrev_b32_e32 v34, 16, v86
	v_mul_f32_e32 v27, v27, v35
	v_add_f32_e32 v35, 1.0, v36
	v_mul_f32_e32 v36, 0xbfb8aa3b, v21
	v_rcp_f32_e32 v35, v35
	v_exp_f32_e32 v36, v36
	v_mul_f32_e32 v24, v24, v34
	v_and_b32_e32 v34, 0xffff0000, v86
	v_mul_f32_e32 v20, v20, v35
	v_add_f32_e32 v35, 1.0, v36
	v_mul_f32_e32 v36, 0xbfb8aa3b, v22
	v_rcp_f32_e32 v35, v35
	v_exp_f32_e32 v36, v36
	v_mul_f32_e32 v25, v25, v34
	v_lshlrev_b32_e32 v34, 16, v87
	v_mul_f32_e32 v26, v26, v34
	v_and_b32_e32 v34, 0xffff0000, v87
	v_mul_f32_e32 v27, v27, v34
	v_lshlrev_b32_e32 v34, 16, v76
	v_mul_f32_e32 v34, v20, v34
	v_mul_f32_e32 v20, v21, v35
	v_add_f32_e32 v35, 1.0, v36
	v_mul_f32_e32 v36, 0xbfb8aa3b, v23
	v_rcp_f32_e32 v35, v35
	v_exp_f32_e32 v36, v36
	v_and_b32_e32 v21, 0xffff0000, v76
	v_mul_f32_e32 v37, v20, v21
	v_mul_f32_e32 v20, v22, v35
	v_add_f32_e32 v22, 1.0, v36
	v_rcp_f32_e32 v22, v22
	v_mul_f32_e32 v35, 0xbfb8aa3b, v16
	v_exp_f32_e32 v35, v35
	v_lshlrev_b32_e32 v21, 16, v77
	v_mul_f32_e32 v36, v20, v21
	v_mul_f32_e32 v20, v23, v22
	v_mul_f32_e32 v23, 0xbfb8aa3b, v17
	v_add_f32_e32 v22, 1.0, v35
	v_exp_f32_e32 v23, v23
	v_rcp_f32_e32 v22, v22
	v_and_b32_e32 v21, 0xffff0000, v77
	v_mul_f32_e32 v35, v20, v21
	v_add_f32_e32 v21, 1.0, v23
	v_mul_f32_e32 v16, v16, v22
	v_rcp_f32_e32 v21, v21
	v_mul_f32_e32 v22, 0xbfb8aa3b, v18
	v_exp_f32_e32 v22, v22
	v_lshlrev_b32_e32 v20, 16, v78
	v_mul_f32_e32 v23, v16, v20
	v_mul_f32_e32 v16, v17, v21
	v_and_b32_e32 v17, 0xffff0000, v78
	v_add_f32_e32 v20, 1.0, v22
	v_mul_f32_e32 v22, v16, v17
	v_mul_f32_e32 v16, 0xbfb8aa3b, v19
	v_rcp_f32_e32 v20, v20
	v_exp_f32_e32 v16, v16
	v_mov_b32_e32 v21, v74
	v_mov_b32_e32 v74, v83
	v_mul_f32_e32 v17, v18, v20
	v_lshlrev_b32_e32 v18, 16, v79
	v_add_f32_e32 v16, 1.0, v16
	v_mul_f32_e32 v38, v17, v18
	v_rcp_f32_e32 v18, v16
	v_mov_b32_e32 v16, v80
	v_mov_b32_e32 v17, v72
	v_mov_b32_e32 v72, v81
	v_pk_add_f32 v[16:17], v[16:17], v[72:73]
	v_mov_b32_e32 v20, v82
	v_pk_add_f32 v[16:17], v[20:21], v[16:17]
	v_lshl_add_u64 v[32:33], s[2:3], 0, v[98:99]
	v_pk_add_f32 v[16:17], v[74:75], v[16:17]
	v_lshl_add_u64 v[32:33], v[32:33], 0, v[170:171]
	v_pk_fma_f32 v[20:21], v[16:17], s[14:15], v[112:113] op_sel_hi:[1,0,0]
	v_mul_f32_e32 v17, v19, v18
	v_mul_f32_e32 v16, 0x4b800000, v21
	v_cmp_gt_f32_e32 vcc, s5, v21
	v_and_b32_e32 v18, 0xffff0000, v79
	s_mov_b64 s[14:15], s[8:9]
	v_cndmask_b32_e32 v16, v21, v16, vcc
	v_rsq_f32_e32 v16, v16
	v_mul_f32_e32 v21, v17, v18
	v_mul_f32_e32 v17, 0x45800000, v16
	v_cndmask_b32_e32 v39, v16, v17, vcc
	v_mul_f32_e32 v16, v28, v39
	v_mul_f32_e32 v17, v29, v39
	v_cvt_pk_bf16_f32 v16, v16, v17
	v_mul_f32_e32 v17, v30, v39
	v_mul_f32_e32 v18, v31, v39
	v_cvt_pk_bf16_f32 v17, v17, v18
	v_mul_f32_e32 v18, v24, v39
	v_mul_f32_e32 v19, v25, v39
	v_cvt_pk_bf16_f32 v18, v18, v19
	v_mul_f32_e32 v19, v26, v39
	v_mul_f32_e32 v24, v27, v39
	v_cvt_pk_bf16_f32 v19, v19, v24
	global_store_dwordx4 v[32:33], v[16:19], off
	v_mul_f32_e32 v21, v21, v39
	v_cmp_gt_f32_e32 vcc, s5, v20
	v_mul_f32_e32 v16, v34, v39
	v_mul_f32_e32 v17, v37, v39
	v_cvt_pk_bf16_f32 v16, v16, v17
	v_mul_f32_e32 v17, v36, v39
	v_mul_f32_e32 v18, v35, v39
	v_cvt_pk_bf16_f32 v17, v17, v18
	v_mul_f32_e32 v18, v23, v39
	v_mul_f32_e32 v19, v22, v39
	v_cvt_pk_bf16_f32 v18, v18, v19
	v_mul_f32_e32 v19, v38, v39
	v_cvt_pk_bf16_f32 v19, v19, v21
	v_mul_f32_e32 v21, 0x4b800000, v20
	v_cndmask_b32_e32 v20, v20, v21, vcc
	global_store_dwordx4 v[32:33], v[16:19], off offset:256
	v_rsq_f32_e32 v20, v20
	s_nop 0
	v_mul_f32_e32 v16, 0xbfb8aa3b, v12
	v_exp_f32_e32 v18, v16
	v_mul_f32_e32 v16, 0x45800000, v20
	v_cndmask_b32_e32 v19, v20, v16, vcc
	v_mul_f32_e32 v20, 0xbfb8aa3b, v13
	v_add_f32_e32 v18, 1.0, v18
	v_rcp_f32_e32 v18, v18
	v_exp_f32_e32 v20, v20
	v_lshl_add_u64 v[16:17], s[2:3], 0, v[96:97]
	v_lshl_add_u64 v[16:17], v[16:17], 0, v[170:171]
	v_mul_f32_e32 v12, v12, v18
	v_lshlrev_b32_e32 v18, 16, v68
	v_mul_f32_e32 v12, v12, v18
	v_add_f32_e32 v18, 1.0, v20
	v_rcp_f32_e32 v18, v18
	v_mul_f32_e32 v20, 0xbfb8aa3b, v14
	v_exp_f32_e32 v20, v20
	v_mul_f32_e32 v12, v12, v19
	v_mul_f32_e32 v13, v13, v18
	v_and_b32_e32 v18, 0xffff0000, v68
	v_mul_f32_e32 v13, v13, v18
	v_add_f32_e32 v18, 1.0, v20
	v_mul_f32_e32 v20, 0xbfb8aa3b, v15
	v_rcp_f32_e32 v18, v18
	v_exp_f32_e32 v20, v20
	v_mul_f32_e32 v13, v13, v19
	v_cvt_pk_bf16_f32 v12, v12, v13
	v_mul_f32_e32 v13, v14, v18
	v_add_f32_e32 v14, 1.0, v20
	v_rcp_f32_e32 v14, v14
	v_lshlrev_b32_e32 v18, 16, v69
	v_mul_f32_e32 v13, v13, v18
	v_and_b32_e32 v18, 0xffff0000, v69
	v_mul_f32_e32 v14, v15, v14
	v_mul_f32_e32 v15, 0xbfb8aa3b, v8
	v_exp_f32_e32 v15, v15
	v_mul_f32_e32 v14, v14, v18
	v_mul_f32_e32 v13, v13, v19
	v_mul_f32_e32 v14, v14, v19
	v_add_f32_e32 v15, 1.0, v15
	v_cvt_pk_bf16_f32 v13, v13, v14
	v_mul_f32_e32 v14, 0xbfb8aa3b, v9
	v_rcp_f32_e32 v15, v15
	v_exp_f32_e32 v14, v14
	s_and_b64 vcc, exec, s[0:1]
	v_mul_f32_e32 v8, v8, v15
	v_lshlrev_b32_e32 v15, 16, v70
	v_add_f32_e32 v14, 1.0, v14
	v_mul_f32_e32 v8, v8, v15
	v_rcp_f32_e32 v14, v14
	v_mul_f32_e32 v15, 0xbfb8aa3b, v10
	v_exp_f32_e32 v15, v15
	v_mul_f32_e32 v8, v8, v19
	v_mul_f32_e32 v9, v9, v14
	v_and_b32_e32 v14, 0xffff0000, v70
	v_mul_f32_e32 v9, v9, v14
	v_add_f32_e32 v14, 1.0, v15
	v_rcp_f32_e32 v15, v14
	v_mul_f32_e32 v14, 0xbfb8aa3b, v11
	v_exp_f32_e32 v18, v14
	v_mul_f32_e32 v9, v9, v19
	v_cvt_pk_bf16_f32 v14, v8, v9
	v_mul_f32_e32 v8, v10, v15
	v_add_f32_e32 v9, 1.0, v18
	v_rcp_f32_e32 v9, v9
	v_lshlrev_b32_e32 v10, 16, v71
	v_mul_f32_e32 v8, v8, v10
	v_and_b32_e32 v10, 0xffff0000, v71
	v_mul_f32_e32 v9, v11, v9
	v_mul_f32_e32 v11, 0xbfb8aa3b, v4
	v_exp_f32_e32 v11, v11
	v_mul_f32_e32 v8, v8, v19
	v_mul_f32_e32 v9, v9, v10
	v_mul_f32_e32 v9, v9, v19
	v_cvt_pk_bf16_f32 v15, v8, v9
	v_add_f32_e32 v8, 1.0, v11
	v_rcp_f32_e32 v8, v8
	v_mul_f32_e32 v9, 0xbfb8aa3b, v5
	v_exp_f32_e32 v9, v9
	global_store_dwordx4 v[16:17], v[12:15], off
	v_mul_f32_e32 v4, v4, v8
	v_lshlrev_b32_e32 v8, 16, v64
	v_mul_f32_e32 v4, v4, v8
	v_add_f32_e32 v8, 1.0, v9
	v_rcp_f32_e32 v8, v8
	v_mul_f32_e32 v9, 0xbfb8aa3b, v6
	v_exp_f32_e32 v9, v9
	v_mul_f32_e32 v4, v4, v19
	v_mul_f32_e32 v5, v5, v8
	v_and_b32_e32 v8, 0xffff0000, v64
	v_mul_f32_e32 v5, v5, v8
	v_add_f32_e32 v8, 1.0, v9
	v_mul_f32_e32 v9, 0xbfb8aa3b, v7
	v_rcp_f32_e32 v8, v8
	v_exp_f32_e32 v9, v9
	v_mul_f32_e32 v5, v5, v19
	v_cvt_pk_bf16_f32 v4, v4, v5
	v_mul_f32_e32 v5, v6, v8
	v_add_f32_e32 v6, 1.0, v9
	v_rcp_f32_e32 v6, v6
	v_lshlrev_b32_e32 v8, 16, v65
	v_mul_f32_e32 v5, v5, v8
	v_and_b32_e32 v8, 0xffff0000, v65
	v_mul_f32_e32 v6, v7, v6
	v_mul_f32_e32 v7, 0xbfb8aa3b, v0
	v_exp_f32_e32 v7, v7
	v_mul_f32_e32 v6, v6, v8
	v_mul_f32_e32 v5, v5, v19
	v_mul_f32_e32 v6, v6, v19
	v_add_f32_e32 v7, 1.0, v7
	v_cvt_pk_bf16_f32 v5, v5, v6
	v_mul_f32_e32 v6, 0xbfb8aa3b, v1
	v_rcp_f32_e32 v7, v7
	v_exp_f32_e32 v6, v6
	v_mul_f32_e32 v0, v0, v7
	v_lshlrev_b32_e32 v7, 16, v66
	v_add_f32_e32 v6, 1.0, v6
	v_mul_f32_e32 v0, v0, v7
	v_rcp_f32_e32 v6, v6
	v_mul_f32_e32 v7, 0xbfb8aa3b, v2
	v_exp_f32_e32 v7, v7
	v_mul_f32_e32 v0, v0, v19
	v_mul_f32_e32 v1, v1, v6
	v_and_b32_e32 v6, 0xffff0000, v66
	v_mul_f32_e32 v1, v1, v6
	v_add_f32_e32 v6, 1.0, v7
	v_rcp_f32_e32 v7, v6
	v_mul_f32_e32 v6, 0xbfb8aa3b, v3
	v_exp_f32_e32 v8, v6
	v_mul_f32_e32 v1, v1, v19
	v_cvt_pk_bf16_f32 v6, v0, v1
	v_mul_f32_e32 v0, v2, v7
	v_add_f32_e32 v1, 1.0, v8
	v_rcp_f32_e32 v1, v1
	v_lshlrev_b32_e32 v2, 16, v67
	v_mul_f32_e32 v0, v0, v2
	v_and_b32_e32 v2, 0xffff0000, v67
	v_mul_f32_e32 v1, v3, v1
	v_mul_f32_e32 v1, v1, v2
	v_mul_f32_e32 v0, v0, v19
	v_mul_f32_e32 v1, v1, v19
	v_cvt_pk_bf16_f32 v7, v0, v1
	global_store_dwordx4 v[16:17], v[4:7], off offset:256
	s_cbranch_vccz .LBB0_80
	s_waitcnt vmcnt(0)
	s_cmpk_gt_u32 s21, 0xff
	s_cbranch_scc1 .LBB0_91
	s_barrier

.LBB0_200:
	ds_read_b128 v[128:131], v222 offset:0
	ds_read_b128 v[132:135], v222 offset:1024
	ds_read_b128 v[136:139], v222 offset:2048
	ds_read_b128 v[140:143], v222 offset:3072
	ds_read_b128 v[144:147], v240
	ds_read_b128 v[148:151], v240 offset:1024
	ds_read_b128 v[152:155], v240 offset:2048
	ds_read_b128 v[156:159], v240 offset:3072
	ds_read_b128 v[160:163], v240 offset:4096
	ds_read_b128 v[164:167], v240 offset:5120
	ds_read_b128 v[168:171], v240 offset:6144
	ds_read_b128 v[172:175], v240 offset:7168
	global_load_lds_dwordx4 v218, s[14:15]
	s_add_i32 m0, s28, 0xe000
	s_nop 0
	global_load_lds_dwordx4 v220, s[14:15]
	s_waitcnt lgkmcnt(8)
	s_barrier
	s_waitcnt lgkmcnt(0)
	v_mfma_f32_16x16x32_bf16 v[124:127], v[128:131], v[144:147], v[124:127]
	v_mfma_f32_16x16x32_bf16 v[120:123], v[136:139], v[144:147], v[120:123]
	v_mfma_f32_16x16x32_bf16 v[116:119], v[128:131], v[152:155], v[116:119]
	v_mfma_f32_16x16x32_bf16 v[108:111], v[136:139], v[152:155], v[108:111]
	s_add_i32 s44, 0, 0x14000
	s_add_i32 s41, s41, s27
	v_mfma_f32_16x16x32_bf16 v[100:103], v[128:131], v[160:163], v[100:103]
	s_mov_b32 m0, s41
	v_mfma_f32_16x16x32_bf16 v[92:95], v[136:139], v[160:163], v[92:95]
	v_mfma_f32_16x16x32_bf16 v[84:87], v[128:131], v[168:171], v[84:87]
	v_mfma_f32_16x16x32_bf16 v[76:79], v[136:139], v[168:171], v[76:79]
	v_mfma_f32_16x16x32_bf16 v[124:127], v[132:135], v[148:151], v[124:127]
	v_mfma_f32_16x16x32_bf16 v[120:123], v[140:143], v[148:151], v[120:123]
	v_mfma_f32_16x16x32_bf16 v[116:119], v[132:135], v[156:159], v[116:119]
	v_mfma_f32_16x16x32_bf16 v[108:111], v[140:143], v[156:159], v[108:111]
	v_mfma_f32_16x16x32_bf16 v[100:103], v[132:135], v[164:167], v[100:103]
	v_mfma_f32_16x16x32_bf16 v[92:95], v[140:143], v[164:167], v[92:95]
	v_mfma_f32_16x16x32_bf16 v[84:87], v[132:135], v[172:175], v[84:87]
	v_mfma_f32_16x16x32_bf16 v[76:79], v[140:143], v[172:175], v[76:79]
	s_barrier
	ds_read_b128 v[176:179], v222 offset:16384
	ds_read_b128 v[180:183], v222 offset:17408
	ds_read_b128 v[184:187], v222 offset:18432
	ds_read_b128 v[188:191], v222 offset:19456
	global_load_lds_dwordx4 v206, s[16:17]
	s_add_i32 m0, s41, 0x2000
	s_nop 0
	global_load_lds_dwordx4 v210, s[16:17]
	s_barrier
	s_waitcnt lgkmcnt(0)
	v_mfma_f32_16x16x32_bf16 v[112:115], v[176:179], v[144:147], v[112:115]
	v_mfma_f32_16x16x32_bf16 v[104:107], v[184:187], v[144:147], v[104:107]
	v_mfma_f32_16x16x32_bf16 v[96:99], v[176:179], v[152:155], v[96:99]
	v_mfma_f32_16x16x32_bf16 v[88:91], v[184:187], v[152:155], v[88:91]
	s_mov_b32 m0, s28
	v_mfma_f32_16x16x32_bf16 v[80:83], v[176:179], v[160:163], v[80:83]
	s_add_u32 s48, s18, 0x80
	s_addc_u32 s49, s19, 0
	v_mfma_f32_16x16x32_bf16 v[72:75], v[184:187], v[160:163], v[72:75]
	v_mfma_f32_16x16x32_bf16 v[68:71], v[176:179], v[168:171], v[68:71]
	v_mfma_f32_16x16x32_bf16 v[64:67], v[184:187], v[168:171], v[64:67]
	v_mfma_f32_16x16x32_bf16 v[112:115], v[180:183], v[148:151], v[112:115]
	v_mfma_f32_16x16x32_bf16 v[104:107], v[188:191], v[148:151], v[104:107]
	v_mfma_f32_16x16x32_bf16 v[96:99], v[180:183], v[156:159], v[96:99]
	v_mfma_f32_16x16x32_bf16 v[88:91], v[188:191], v[156:159], v[88:91]
	v_mfma_f32_16x16x32_bf16 v[80:83], v[180:183], v[164:167], v[80:83]
	v_mfma_f32_16x16x32_bf16 v[72:75], v[188:191], v[164:167], v[72:75]
	v_mfma_f32_16x16x32_bf16 v[68:71], v[180:183], v[172:175], v[68:71]
	v_mfma_f32_16x16x32_bf16 v[64:67], v[188:191], v[172:175], v[64:67]
	s_barrier
	ds_read_b128 v[144:147], v240 offset:16384
	ds_read_b128 v[148:151], v240 offset:17408
	ds_read_b128 v[152:155], v240 offset:18432
	ds_read_b128 v[156:159], v240 offset:19456
	ds_read_b128 v[160:163], v240 offset:20480
	ds_read_b128 v[164:167], v240 offset:21504
	ds_read_b128 v[168:171], v240 offset:22528
	ds_read_b128 v[172:175], v240 offset:23552
	global_load_lds_dwordx4 v204, s[18:19]
	s_mov_b32 m0, s29
	s_nop 0
	global_load_lds_dwordx4 v208, s[18:19]
	s_barrier
	s_waitcnt lgkmcnt(0)
	v_mfma_f32_16x16x32_bf16 v[60:63], v[128:131], v[144:147], v[60:63]
	v_mfma_f32_16x16x32_bf16 v[56:59], v[136:139], v[144:147], v[56:59]
	v_mfma_f32_16x16x32_bf16 v[52:55], v[128:131], v[152:155], v[52:55]
	v_mfma_f32_16x16x32_bf16 v[44:47], v[136:139], v[152:155], v[44:47]
	s_add_u32 s42, s16, 0x80000
	s_addc_u32 s43, s17, 0
	v_mfma_f32_16x16x32_bf16 v[36:39], v[128:131], v[160:163], v[36:39]
	s_add_i32 s41, s44, s27
	s_mov_b32 m0, s41
	v_mfma_f32_16x16x32_bf16 v[28:31], v[136:139], v[160:163], v[28:31]
	v_mfma_f32_16x16x32_bf16 v[20:23], v[128:131], v[168:171], v[20:23]
	v_mfma_f32_16x16x32_bf16 v[12:15], v[136:139], v[168:171], v[12:15]
	v_mfma_f32_16x16x32_bf16 v[60:63], v[132:135], v[148:151], v[60:63]
	v_mfma_f32_16x16x32_bf16 v[56:59], v[140:143], v[148:151], v[56:59]
	v_mfma_f32_16x16x32_bf16 v[52:55], v[132:135], v[156:159], v[52:55]
	v_mfma_f32_16x16x32_bf16 v[44:47], v[140:143], v[156:159], v[44:47]
	v_mfma_f32_16x16x32_bf16 v[36:39], v[132:135], v[164:167], v[36:39]
	v_mfma_f32_16x16x32_bf16 v[28:31], v[140:143], v[164:167], v[28:31]
	v_mfma_f32_16x16x32_bf16 v[20:23], v[132:135], v[172:175], v[20:23]
	v_mfma_f32_16x16x32_bf16 v[12:15], v[140:143], v[172:175], v[12:15]
	s_barrier
	global_load_lds_dwordx4 v206, s[42:43]
	s_add_i32 m0, s41, 0x2000
	s_nop 0
	global_load_lds_dwordx4 v210, s[42:43]
	s_waitcnt vmcnt(6)
	s_barrier
	v_mfma_f32_16x16x32_bf16 v[48:51], v[176:179], v[144:147], v[48:51]
	v_mfma_f32_16x16x32_bf16 v[40:43], v[184:187], v[144:147], v[40:43]
	v_mfma_f32_16x16x32_bf16 v[32:35], v[176:179], v[152:155], v[32:35]
	v_mfma_f32_16x16x32_bf16 v[24:27], v[184:187], v[152:155], v[24:27]
	s_add_i32 s41, 0, 0x18000
	v_mfma_f32_16x16x32_bf16 v[16:19], v[176:179], v[160:163], v[16:19]
	s_add_u32 s18, s18, 0x80000
	s_addc_u32 s19, s19, 0
	v_mfma_f32_16x16x32_bf16 v[8:11], v[184:187], v[160:163], v[8:11]
	s_mov_b32 m0, s30
	v_mfma_f32_16x16x32_bf16 v[4:7], v[176:179], v[168:171], v[4:7]
	v_mfma_f32_16x16x32_bf16 v[0:3], v[184:187], v[168:171], v[0:3]
	v_mfma_f32_16x16x32_bf16 v[48:51], v[180:183], v[148:151], v[48:51]
	v_mfma_f32_16x16x32_bf16 v[40:43], v[188:191], v[148:151], v[40:43]
	v_mfma_f32_16x16x32_bf16 v[32:35], v[180:183], v[156:159], v[32:35]
	v_mfma_f32_16x16x32_bf16 v[24:27], v[188:191], v[156:159], v[24:27]
	v_mfma_f32_16x16x32_bf16 v[16:19], v[180:183], v[164:167], v[16:19]
	v_mfma_f32_16x16x32_bf16 v[8:11], v[188:191], v[164:167], v[8:11]
	v_mfma_f32_16x16x32_bf16 v[4:7], v[180:183], v[172:175], v[4:7]
	v_mfma_f32_16x16x32_bf16 v[0:3], v[188:191], v[172:175], v[0:3]
	s_barrier
	ds_read_b128 v[128:131], v222 offset:32768
	ds_read_b128 v[132:135], v222 offset:33792
	ds_read_b128 v[136:139], v222 offset:34816
	ds_read_b128 v[140:143], v222 offset:35840
	ds_read_b128 v[144:147], v240 offset:32768
	ds_read_b128 v[148:151], v240 offset:33792
	ds_read_b128 v[152:155], v240 offset:34816
	ds_read_b128 v[156:159], v240 offset:35840
	ds_read_b128 v[160:163], v240 offset:36864
	ds_read_b128 v[164:167], v240 offset:37888
	ds_read_b128 v[168:171], v240 offset:38912
	ds_read_b128 v[172:175], v240 offset:39936
	global_load_lds_dwordx4 v204, s[18:19]
	s_mov_b32 m0, s31
	s_nop 0
	global_load_lds_dwordx4 v208, s[18:19]
	s_waitcnt lgkmcnt(8)
	s_barrier
	s_waitcnt lgkmcnt(0)
	v_mfma_f32_16x16x32_bf16 v[124:127], v[128:131], v[144:147], v[124:127]
	v_mfma_f32_16x16x32_bf16 v[120:123], v[136:139], v[144:147], v[120:123]
	v_mfma_f32_16x16x32_bf16 v[116:119], v[128:131], v[152:155], v[116:119]
	v_mfma_f32_16x16x32_bf16 v[108:111], v[136:139], v[152:155], v[108:111]
	s_add_i32 s18, 0, 0x1c000
	s_add_i32 s19, s41, s27
	v_mfma_f32_16x16x32_bf16 v[100:103], v[128:131], v[160:163], v[100:103]
	s_add_i32 m0, s19, 0xffffff80
	v_mfma_f32_16x16x32_bf16 v[92:95], v[136:139], v[160:163], v[92:95]
	v_mfma_f32_16x16x32_bf16 v[84:87], v[128:131], v[168:171], v[84:87]
	v_mfma_f32_16x16x32_bf16 v[76:79], v[136:139], v[168:171], v[76:79]
	v_mfma_f32_16x16x32_bf16 v[124:127], v[132:135], v[148:151], v[124:127]
	v_mfma_f32_16x16x32_bf16 v[120:123], v[140:143], v[148:151], v[120:123]
	v_mfma_f32_16x16x32_bf16 v[116:119], v[132:135], v[156:159], v[116:119]
	v_mfma_f32_16x16x32_bf16 v[108:111], v[140:143], v[156:159], v[108:111]
	v_mfma_f32_16x16x32_bf16 v[100:103], v[132:135], v[164:167], v[100:103]
	v_mfma_f32_16x16x32_bf16 v[92:95], v[140:143], v[164:167], v[92:95]
	v_mfma_f32_16x16x32_bf16 v[84:87], v[132:135], v[172:175], v[84:87]
	v_mfma_f32_16x16x32_bf16 v[76:79], v[140:143], v[172:175], v[76:79]
	s_barrier
	ds_read_b128 v[176:179], v222 offset:49152
	ds_read_b128 v[180:183], v222 offset:50176
	ds_read_b128 v[184:187], v222 offset:51200
	ds_read_b128 v[188:191], v222 offset:52224
	global_load_lds_dwordx4 v206, s[16:17] offset:128
	s_add_i32 m0, s19, 0x1f80
	s_nop 0
	global_load_lds_dwordx4 v210, s[16:17] offset:128
	s_barrier
	s_waitcnt lgkmcnt(0)
	v_mfma_f32_16x16x32_bf16 v[112:115], v[176:179], v[144:147], v[112:115]
	v_mfma_f32_16x16x32_bf16 v[104:107], v[184:187], v[144:147], v[104:107]
	v_mfma_f32_16x16x32_bf16 v[96:99], v[176:179], v[152:155], v[96:99]
	v_mfma_f32_16x16x32_bf16 v[88:91], v[184:187], v[152:155], v[88:91]
	s_mov_b32 m0, s33
	v_mfma_f32_16x16x32_bf16 v[80:83], v[176:179], v[160:163], v[80:83]
	v_mfma_f32_16x16x32_bf16 v[72:75], v[184:187], v[160:163], v[72:75]
	v_mfma_f32_16x16x32_bf16 v[68:71], v[176:179], v[168:171], v[68:71]
	v_mfma_f32_16x16x32_bf16 v[64:67], v[184:187], v[168:171], v[64:67]
	v_mfma_f32_16x16x32_bf16 v[112:115], v[180:183], v[148:151], v[112:115]
	v_mfma_f32_16x16x32_bf16 v[104:107], v[188:191], v[148:151], v[104:107]
	v_mfma_f32_16x16x32_bf16 v[96:99], v[180:183], v[156:159], v[96:99]
	v_mfma_f32_16x16x32_bf16 v[88:91], v[188:191], v[156:159], v[88:91]
	v_mfma_f32_16x16x32_bf16 v[80:83], v[180:183], v[164:167], v[80:83]
	v_mfma_f32_16x16x32_bf16 v[72:75], v[188:191], v[164:167], v[72:75]
	v_mfma_f32_16x16x32_bf16 v[68:71], v[180:183], v[172:175], v[68:71]
	v_mfma_f32_16x16x32_bf16 v[64:67], v[188:191], v[172:175], v[64:67]
	s_barrier
	ds_read_b128 v[144:147], v240 offset:49152
	ds_read_b128 v[148:151], v240 offset:50176
	ds_read_b128 v[152:155], v240 offset:51200
	ds_read_b128 v[156:159], v240 offset:52224
	ds_read_b128 v[160:163], v240 offset:53248
	ds_read_b128 v[164:167], v240 offset:54272
	ds_read_b128 v[168:171], v240 offset:55296
	ds_read_b128 v[172:175], v240 offset:56320
	global_load_lds_dwordx4 v204, s[48:49]
	s_mov_b32 m0, s34
	s_nop 0
	global_load_lds_dwordx4 v208, s[48:49]
	s_barrier
	s_waitcnt lgkmcnt(0)
	v_mfma_f32_16x16x32_bf16 v[60:63], v[128:131], v[144:147], v[60:63]
	v_mfma_f32_16x16x32_bf16 v[56:59], v[136:139], v[144:147], v[56:59]
	v_mfma_f32_16x16x32_bf16 v[52:55], v[128:131], v[152:155], v[52:55]
	v_mfma_f32_16x16x32_bf16 v[44:47], v[136:139], v[152:155], v[44:47]
	s_add_u32 s16, s16, 0x80080
	s_addc_u32 s17, s17, 0
	v_mfma_f32_16x16x32_bf16 v[36:39], v[128:131], v[160:163], v[36:39]
	s_add_i32 s18, s18, s27
	s_mov_b32 m0, s18
	v_mfma_f32_16x16x32_bf16 v[28:31], v[136:139], v[160:163], v[28:31]
	v_mfma_f32_16x16x32_bf16 v[20:23], v[128:131], v[168:171], v[20:23]
	v_mfma_f32_16x16x32_bf16 v[12:15], v[136:139], v[168:171], v[12:15]
	v_mfma_f32_16x16x32_bf16 v[60:63], v[132:135], v[148:151], v[60:63]
	v_mfma_f32_16x16x32_bf16 v[56:59], v[140:143], v[148:151], v[56:59]
	v_mfma_f32_16x16x32_bf16 v[52:55], v[132:135], v[156:159], v[52:55]
	v_mfma_f32_16x16x32_bf16 v[44:47], v[140:143], v[156:159], v[44:47]
	v_mfma_f32_16x16x32_bf16 v[36:39], v[132:135], v[164:167], v[36:39]
	v_mfma_f32_16x16x32_bf16 v[28:31], v[140:143], v[164:167], v[28:31]
	v_mfma_f32_16x16x32_bf16 v[20:23], v[132:135], v[172:175], v[20:23]
	v_mfma_f32_16x16x32_bf16 v[12:15], v[140:143], v[172:175], v[12:15]
	s_barrier
	global_load_lds_dwordx4 v206, s[16:17]
	s_add_i32 m0, s18, 0x2000
	s_nop 0
	global_load_lds_dwordx4 v210, s[16:17]
	s_waitcnt vmcnt(6)
	s_barrier
	v_mfma_f32_16x16x32_bf16 v[48:51], v[176:179], v[144:147], v[48:51]
	v_mfma_f32_16x16x32_bf16 v[40:43], v[184:187], v[144:147], v[40:43]
	v_mfma_f32_16x16x32_bf16 v[32:35], v[176:179], v[152:155], v[32:35]
	v_mfma_f32_16x16x32_bf16 v[24:27], v[184:187], v[152:155], v[24:27]
	s_add_i32 s40, s40, 2
	v_mfma_f32_16x16x32_bf16 v[16:19], v[176:179], v[160:163], v[16:19]
	s_add_u32 s14, s14, 0x100
	s_addc_u32 s15, s15, 0
	v_mfma_f32_16x16x32_bf16 v[8:11], v[184:187], v[160:163], v[8:11]
	s_add_u32 s38, s38, 0x100
	s_addc_u32 s39, s39, 0
	v_mfma_f32_16x16x32_bf16 v[4:7], v[176:179], v[168:171], v[4:7]
	s_add_u32 s16, s14, 0xfff80080
	s_addc_u32 s17, s15, -1
	v_mfma_f32_16x16x32_bf16 v[0:3], v[184:187], v[168:171], v[0:3]
	s_add_i32 s41, 0, 0x10000
	s_cmp_eq_u32 s40, 28
	v_mfma_f32_16x16x32_bf16 v[48:51], v[180:183], v[148:151], v[48:51]
	s_cselect_b32 s19, s5, s17
	s_cselect_b32 s18, s9, s16
	v_mfma_f32_16x16x32_bf16 v[40:43], v[188:191], v[148:151], v[40:43]
	s_cselect_b32 s17, s7, s39
	s_cselect_b32 s16, s37, s38
	v_mfma_f32_16x16x32_bf16 v[32:35], v[180:183], v[156:159], v[32:35]
	s_add_i32 m0, s28, 0xc000
	v_mfma_f32_16x16x32_bf16 v[24:27], v[188:191], v[156:159], v[24:27]
	v_mfma_f32_16x16x32_bf16 v[16:19], v[180:183], v[164:167], v[16:19]
	v_mfma_f32_16x16x32_bf16 v[8:11], v[188:191], v[164:167], v[8:11]
	v_mfma_f32_16x16x32_bf16 v[4:7], v[180:183], v[172:175], v[4:7]
	v_mfma_f32_16x16x32_bf16 v[0:3], v[188:191], v[172:175], v[0:3]
	s_cmp_gt_u32 s40, 29
	s_cbranch_scc0 .Lrot_200
	s_barrier
	v_lshl_add_u32 v228, s4, 8, v237
	v_or_b32_e32 v226, 16, v228
	s_mov_b64 s[4:5], -1
	s_cmp_lt_i32 s36, 16
	v_ashrrev_i32_e32 v229, 31, v228
	v_lshlrev_b32_e32 v192, 1, v212
	v_ashrrev_i32_e32 v227, 31, v226
	v_or_b32_e32 v224, 32, v228
	v_or_b32_e32 v222, 48, v228
	s_cbranch_scc0 .LBB0_203
	s_and_b32 s7, s36, 7
	s_cmp_gt_i32 s36, 7
	s_cselect_b64 vcc, -1, 0
	s_and_b64 s[4:5], vcc, exec
	s_mov_b32 s4, 0x15000000
	s_cselect_b32 s4, s4, 0xd000000
	s_add_u32 s4, s50, s4
	s_addc_u32 s5, s51, 0
	s_lshl_b32 s9, s7, 9
	s_add_u32 s4, s4, s9
	v_cvt_f32_ubyte0_e32 v128, s7
	s_addc_u32 s5, s5, 0
	v_sub_f32_e32 v128, 0xc0a00000, v128
	s_mov_b32 s7, 0xc2fc0000
	v_lshl_add_u64 v[230:231], s[4:5], 0, v[192:193]
	v_cmp_gt_f32_e64 s[4:5], s7, v128
	v_ashrrev_i32_e32 v225, 31, v224
	s_nop 0
	v_cndmask_b32_e64 v129, 0, v234, s[4:5]
	v_add_f32_e32 v128, v128, v129
	v_exp_f32_e32 v128, v128
	s_and_b64 s[4:5], s[4:5], exec
	s_cselect_b32 s4, 0xffffffc0, 0
	v_mov_b32_e32 v129, v193
	v_ldexp_f32 v128, v128, s4
	v_sub_f32_e32 v128, 1.0, v128
	v_log_f32_e32 v241, v128
	v_lshlrev_b32_e32 v128, 9, v228
	v_and_b32_e32 v128, 0x1f9e00, v128
	v_lshl_add_u64 v[130:131], v[214:215], 0, v[128:129]
	v_lshl_add_u64 v[132:133], v[216:217], 0, v[128:129]
	global_load_dwordx4 v[180:183], v[130:131], off offset:16
	global_load_dwordx4 v[188:191], v[130:131], off
	global_load_dwordx4 v[176:179], v[132:133], off offset:16
	global_load_dwordx4 v[184:187], v[132:133], off
	v_or_b32_e32 v130, 0x2000, v128
	v_mov_b32_e32 v131, v193
	v_lshl_add_u64 v[132:133], v[214:215], 0, v[130:131]
	v_lshl_add_u64 v[130:131], v[216:217], 0, v[130:131]
	global_load_dwordx4 v[164:167], v[132:133], off offset:16
	global_load_dwordx4 v[172:175], v[132:133], off
	global_load_dwordx4 v[160:163], v[130:131], off offset:16
	global_load_dwordx4 v[168:171], v[130:131], off
	v_mul_f32_e64 v196, v241, -v239
	v_cmp_gt_f32_e64 s[4:5], s7, v196
	v_or_b32_e32 v130, 0x4000, v128
	v_mov_b32_e32 v131, v193
	v_cndmask_b32_e64 v196, 0, v234, s[4:5]
	v_fma_f32 v196, v241, -v239, v196
	v_exp_f32_e32 v196, v196
	v_cndmask_b32_e64 v197, 0, v235, s[4:5]
	v_lshl_add_u64 v[132:133], v[214:215], 0, v[130:131]
	v_lshl_add_u64 v[130:131], v[216:217], 0, v[130:131]
	v_ldexp_f32 v196, v196, v197
	v_mul_f32_e32 v196, 0x3d800000, v196
	v_cndmask_b32_e32 v242, 1.0, v196, vcc
	v_mov_b32_e32 v196, v124
	v_mov_b32_e32 v197, v112
	global_load_dwordx4 v[148:151], v[132:133], off offset:16
	global_load_dwordx4 v[156:159], v[132:133], off
	global_load_dwordx4 v[144:147], v[130:131], off offset:16
	global_load_dwordx4 v[152:155], v[130:131], off
	v_or_b32_e32 v128, 0x6000, v128
	v_lshl_add_u64 v[130:131], v[214:215], 0, v[128:129]
	v_lshl_add_u64 v[136:137], v[216:217], 0, v[128:129]
	global_load_dwordx4 v[132:135], v[130:131], off offset:16
	global_load_dwordx4 v[140:143], v[130:131], off
	s_nop 0
	global_load_dwordx4 v[128:131], v[136:137], off offset:16
	s_nop 0
	global_load_dwordx4 v[136:139], v[136:137], off
	s_movk_i32 s4, 0x5f
	s_waitcnt vmcnt(0)
	v_mov_b32_e32 v198, v188
	v_mov_b32_e32 v199, v184
	v_pk_mul_f32 v[196:197], v[196:197], v[198:199]
	s_nop 0
	v_sub_f32_e32 v184, v196, v197
	v_mov_b32_e32 v196, v112
	v_mov_b32_e32 v197, v124
	v_pk_mul_f32 v[196:197], v[196:197], v[198:199]
	v_mul_f32_e32 v223, v242, v184
	v_add_f32_e32 v184, v196, v197
	v_mul_f32_e32 v198, v242, v184
	v_mov_b32_e32 v196, v125
	v_mov_b32_e32 v197, v113
	v_mov_b32_e32 v184, v189
	v_pk_mul_f32 v[188:189], v[196:197], v[184:185]
	s_nop 0
	v_sub_f32_e32 v188, v188, v189
	v_mul_f32_e32 v196, v242, v188
	v_mov_b32_e32 v188, v113
	v_mov_b32_e32 v189, v125
	v_pk_mul_f32 v[184:185], v[188:189], v[184:185]
	v_mov_b32_e32 v188, v190
	v_add_f32_e32 v184, v184, v185
	v_mul_f32_e32 v197, v242, v184
	v_mov_b32_e32 v184, v126
	v_mov_b32_e32 v185, v114
	v_mov_b32_e32 v189, v186
	v_pk_mul_f32 v[184:185], v[184:185], v[188:189]
	v_mov_b32_e32 v186, v191
	v_sub_f32_e32 v184, v184, v185
	v_mul_f32_e32 v190, v242, v184
	v_mov_b32_e32 v184, v114
	v_mov_b32_e32 v185, v126
	v_pk_mul_f32 v[184:185], v[184:185], v[188:189]
	s_nop 0
	v_add_f32_e32 v184, v184, v185
	v_mul_f32_e32 v188, v242, v184
	v_mov_b32_e32 v184, v127
	v_mov_b32_e32 v185, v115
	v_pk_mul_f32 v[184:185], v[184:185], v[186:187]
	s_nop 0
	v_sub_f32_e32 v184, v184, v185
	v_mul_f32_e32 v189, v242, v184
	v_mov_b32_e32 v184, v115
	v_mov_b32_e32 v185, v127
	v_pk_mul_f32 v[184:185], v[184:185], v[186:187]
	v_mov_b32_e32 v186, v180
	v_add_f32_e32 v184, v184, v185
	v_mul_f32_e32 v191, v242, v184
	v_mov_b32_e32 v184, v120
	v_mov_b32_e32 v185, v104
	v_mov_b32_e32 v187, v176
	v_pk_mul_f32 v[184:185], v[184:185], v[186:187]
	s_nop 0
	v_sub_f32_e32 v176, v184, v185
	v_mov_b32_e32 v184, v104
	v_mov_b32_e32 v185, v120
	v_pk_mul_f32 v[184:185], v[184:185], v[186:187]
	v_mul_f32_e32 v199, v242, v176
	v_add_f32_e32 v176, v184, v185
	v_mul_f32_e32 v186, v242, v176
	v_mov_b32_e32 v184, v121
	v_mov_b32_e32 v185, v105
	v_mov_b32_e32 v176, v181
	v_pk_mul_f32 v[180:181], v[184:185], v[176:177]
	s_nop 0
	v_sub_f32_e32 v180, v180, v181
	v_mul_f32_e32 v184, v242, v180
	v_mov_b32_e32 v180, v105
	v_mov_b32_e32 v181, v121
	v_pk_mul_f32 v[176:177], v[180:181], v[176:177]
	v_mov_b32_e32 v180, v182
	v_add_f32_e32 v176, v176, v177
	v_mul_f32_e32 v185, v242, v176
	v_mov_b32_e32 v176, v122
	v_mov_b32_e32 v177, v106
	v_mov_b32_e32 v181, v178
	v_pk_mul_f32 v[176:177], v[176:177], v[180:181]
	v_mov_b32_e32 v178, v183
	v_sub_f32_e32 v176, v176, v177
	v_mul_f32_e32 v182, v242, v176
	v_mov_b32_e32 v176, v106
	v_mov_b32_e32 v177, v122
	v_pk_mul_f32 v[176:177], v[176:177], v[180:181]
	s_nop 0
	v_add_f32_e32 v176, v176, v177
	v_mul_f32_e32 v187, v242, v176
	v_mov_b32_e32 v176, v123
	v_mov_b32_e32 v177, v107
	v_pk_mul_f32 v[176:177], v[176:177], v[178:179]
	s_nop 0
	v_sub_f32_e32 v176, v176, v177
	v_mul_f32_e32 v181, v242, v176
	v_mov_b32_e32 v176, v107
	v_mov_b32_e32 v177, v123
	v_pk_mul_f32 v[176:177], v[176:177], v[178:179]
	v_cvt_pk_bf16_f32 v178, v223, v196
	v_cvt_pk_bf16_f32 v179, v190, v189
	v_cvt_pk_bf16_f32 v180, v199, v184
	v_cvt_pk_bf16_f32 v181, v182, v181
	v_cvt_pk_bf16_f32 v182, v198, v197
	s_nop 0
	v_add_f32_e32 v176, v176, v177
	v_mul_f32_e32 v176, v242, v176
	v_cvt_pk_bf16_f32 v183, v188, v191
	v_cvt_pk_bf16_f32 v184, v186, v185
	v_cvt_pk_bf16_f32 v185, v187, v176
	v_lshlrev_b64 v[176:177], 12, v[228:229]
	v_lshl_add_u64 v[176:177], v[230:231], 0, v[176:177]
	global_store_dwordx4 v[176:177], v[178:181], off
	global_store_dwordx4 v[176:177], v[182:185], off offset:256
	v_ashrrev_i32_e32 v223, 31, v222
	v_bitop3_b32 v178, v228, s4, 16 bitop3:0xc8
	v_add_u32_e32 v178, 1, v178
	v_cvt_f32_ubyte0_e32 v178, v178
	v_mul_f32_e64 v179, v241, -v178
	v_cmp_gt_f32_e64 s[4:5], s7, v179
	v_mov_b32_e32 v181, v168
	v_mov_b32_e32 v190, v60
	v_cndmask_b32_e64 v180, 0, v234, s[4:5]
	v_fma_f32 v178, v241, -v178, v180
	v_exp_f32_e32 v178, v178
	v_cndmask_b32_e64 v179, 0, v235, s[4:5]
	v_mov_b32_e32 v180, v172
	s_movk_i32 s4, 0x6f
	v_ldexp_f32 v178, v178, v179
	v_mul_f32_e32 v178, 0x3d800000, v178
	v_cndmask_b32_e32 v182, 1.0, v178, vcc
	v_mov_b32_e32 v178, v116
	v_mov_b32_e32 v179, v96
	v_pk_mul_f32 v[178:179], v[178:179], v[180:181]
	v_mov_b32_e32 v191, v48
	v_sub_f32_e32 v168, v178, v179
	v_mov_b32_e32 v178, v96
	v_mov_b32_e32 v179, v116
	v_pk_mul_f32 v[178:179], v[178:179], v[180:181]
	v_mul_f32_e32 v183, v182, v168
	v_add_f32_e32 v168, v178, v179
	v_mul_f32_e32 v180, v182, v168
	v_mov_b32_e32 v178, v117
	v_mov_b32_e32 v179, v97
	v_mov_b32_e32 v168, v173
	v_pk_mul_f32 v[172:173], v[178:179], v[168:169]
	s_nop 0
	v_sub_f32_e32 v172, v172, v173
	v_mul_f32_e32 v178, v182, v172
	v_mov_b32_e32 v172, v97
	v_mov_b32_e32 v173, v117
	v_pk_mul_f32 v[168:169], v[172:173], v[168:169]
	v_mov_b32_e32 v172, v174
	v_add_f32_e32 v168, v168, v169
	v_mul_f32_e32 v179, v182, v168
	v_mov_b32_e32 v168, v118
	v_mov_b32_e32 v169, v98
	v_mov_b32_e32 v173, v170
	v_pk_mul_f32 v[168:169], v[168:169], v[172:173]
	v_mov_b32_e32 v170, v175
	v_sub_f32_e32 v168, v168, v169
	v_mul_f32_e32 v174, v182, v168
	v_mov_b32_e32 v168, v98
	v_mov_b32_e32 v169, v118
	v_pk_mul_f32 v[168:169], v[168:169], v[172:173]
	s_nop 0
	v_add_f32_e32 v168, v168, v169
	v_mul_f32_e32 v172, v182, v168
	v_mov_b32_e32 v168, v119
	v_mov_b32_e32 v169, v99
	v_pk_mul_f32 v[168:169], v[168:169], v[170:171]
	s_nop 0
	v_sub_f32_e32 v168, v168, v169
	v_mul_f32_e32 v173, v182, v168
	v_mov_b32_e32 v168, v99
	v_mov_b32_e32 v169, v119
	v_pk_mul_f32 v[168:169], v[168:169], v[170:171]
	v_mov_b32_e32 v170, v164
	v_add_f32_e32 v168, v168, v169
	v_mul_f32_e32 v175, v182, v168
	v_mov_b32_e32 v168, v108
	v_mov_b32_e32 v169, v88
	v_mov_b32_e32 v171, v160
	v_pk_mul_f32 v[168:169], v[168:169], v[170:171]
	s_nop 0
	v_sub_f32_e32 v160, v168, v169
	v_mov_b32_e32 v168, v88
	v_mov_b32_e32 v169, v108
	v_pk_mul_f32 v[168:169], v[168:169], v[170:171]
	v_mul_f32_e32 v181, v182, v160
	v_add_f32_e32 v160, v168, v169
	v_mul_f32_e32 v170, v182, v160
	v_mov_b32_e32 v168, v109
	v_mov_b32_e32 v169, v89
	v_mov_b32_e32 v160, v165
	v_pk_mul_f32 v[164:165], v[168:169], v[160:161]
	s_nop 0
	v_sub_f32_e32 v164, v164, v165
	v_mul_f32_e32 v168, v182, v164
	v_mov_b32_e32 v164, v89
	v_mov_b32_e32 v165, v109
	v_pk_mul_f32 v[160:161], v[164:165], v[160:161]
	v_mov_b32_e32 v164, v166
	v_add_f32_e32 v160, v160, v161
	v_mul_f32_e32 v169, v182, v160
	v_mov_b32_e32 v160, v110
	v_mov_b32_e32 v161, v90
	v_mov_b32_e32 v165, v162
	v_pk_mul_f32 v[160:161], v[160:161], v[164:165]
	v_mov_b32_e32 v162, v167
	v_sub_f32_e32 v160, v160, v161
	v_mul_f32_e32 v166, v182, v160
	v_mov_b32_e32 v160, v90
	v_mov_b32_e32 v161, v110
	v_pk_mul_f32 v[160:161], v[160:161], v[164:165]
	s_nop 0
	v_add_f32_e32 v160, v160, v161
	v_mul_f32_e32 v171, v182, v160
	v_mov_b32_e32 v160, v111
	v_mov_b32_e32 v161, v91
	v_pk_mul_f32 v[160:161], v[160:161], v[162:163]
	s_nop 0
	v_sub_f32_e32 v160, v160, v161
	v_mul_f32_e32 v164, v182, v160
	v_mov_b32_e32 v160, v91
	v_mov_b32_e32 v161, v111
	v_pk_mul_f32 v[160:161], v[160:161], v[162:163]
	s_nop 0
	v_add_f32_e32 v160, v160, v161
	v_mul_f32_e32 v167, v182, v160
	v_cvt_pk_bf16_f32 v160, v183, v178
	v_cvt_pk_bf16_f32 v161, v174, v173
	v_cvt_pk_bf16_f32 v162, v181, v168
	v_cvt_pk_bf16_f32 v163, v166, v164
	v_cvt_pk_bf16_f32 v164, v180, v179
	v_cvt_pk_bf16_f32 v165, v172, v175
	v_cvt_pk_bf16_f32 v166, v170, v169
	v_lshlrev_b64 v[168:169], 12, v[226:227]
	v_lshl_add_u64 v[168:169], v[230:231], 0, v[168:169]
	v_cvt_pk_bf16_f32 v167, v171, v167
	global_store_dwordx4 v[168:169], v[160:163], off
	global_store_dwordx4 v[168:169], v[164:167], off offset:256
	s_nop 0
	v_bitop3_b32 v160, v228, s4, 32 bitop3:0xc8
	v_add_u32_e32 v160, 1, v160
	v_cvt_f32_ubyte0_e32 v160, v160
	v_mul_f32_e64 v161, v241, -v160
	v_cmp_gt_f32_e64 s[4:5], s7, v161
	v_mov_b32_e32 v163, v152
	s_nop 0
	v_cndmask_b32_e64 v162, 0, v234, s[4:5]
	v_fma_f32 v160, v241, -v160, v162
	v_exp_f32_e32 v160, v160
	v_cndmask_b32_e64 v161, 0, v235, s[4:5]
	v_mov_b32_e32 v162, v156
	s_movk_i32 s4, 0x7f
	v_ldexp_f32 v160, v160, v161
	v_mul_f32_e32 v160, 0x3d800000, v160
	v_cndmask_b32_e32 v164, 1.0, v160, vcc
	v_mov_b32_e32 v160, v100
	v_mov_b32_e32 v161, v80
	v_pk_mul_f32 v[160:161], v[160:161], v[162:163]
	s_nop 0
	v_sub_f32_e32 v152, v160, v161
	v_mov_b32_e32 v160, v80
	v_mov_b32_e32 v161, v100
	v_pk_mul_f32 v[160:161], v[160:161], v[162:163]
	v_mul_f32_e32 v165, v164, v152
	v_add_f32_e32 v152, v160, v161
	v_mul_f32_e32 v162, v164, v152
	v_mov_b32_e32 v160, v101
	v_mov_b32_e32 v161, v81
	v_mov_b32_e32 v152, v157
	v_pk_mul_f32 v[156:157], v[160:161], v[152:153]
	s_nop 0
	v_sub_f32_e32 v156, v156, v157
	v_mul_f32_e32 v160, v164, v156
	v_mov_b32_e32 v156, v81
	v_mov_b32_e32 v157, v101
	v_pk_mul_f32 v[152:153], v[156:157], v[152:153]
	v_mov_b32_e32 v156, v158
	v_add_f32_e32 v152, v152, v153
	v_mul_f32_e32 v161, v164, v152
	v_mov_b32_e32 v152, v102
	v_mov_b32_e32 v153, v82
	v_mov_b32_e32 v157, v154
	v_pk_mul_f32 v[152:153], v[152:153], v[156:157]
	v_mov_b32_e32 v154, v159
	v_sub_f32_e32 v152, v152, v153
	v_mul_f32_e32 v158, v164, v152
	v_mov_b32_e32 v152, v82
	v_mov_b32_e32 v153, v102
	v_pk_mul_f32 v[152:153], v[152:153], v[156:157]
	s_nop 0
	v_add_f32_e32 v152, v152, v153
	v_mul_f32_e32 v156, v164, v152
	v_mov_b32_e32 v152, v103
	v_mov_b32_e32 v153, v83
	v_pk_mul_f32 v[152:153], v[152:153], v[154:155]
	s_nop 0
	v_sub_f32_e32 v152, v152, v153
	v_mul_f32_e32 v157, v164, v152
	v_mov_b32_e32 v152, v83
	v_mov_b32_e32 v153, v103
	v_pk_mul_f32 v[152:153], v[152:153], v[154:155]
	v_mov_b32_e32 v154, v148
	v_add_f32_e32 v152, v152, v153
	v_mul_f32_e32 v159, v164, v152
	v_mov_b32_e32 v152, v92
	v_mov_b32_e32 v153, v72
	v_mov_b32_e32 v155, v144
	v_pk_mul_f32 v[152:153], v[152:153], v[154:155]
	s_nop 0
	v_sub_f32_e32 v144, v152, v153
	v_mov_b32_e32 v152, v72
	v_mov_b32_e32 v153, v92
	v_pk_mul_f32 v[152:153], v[152:153], v[154:155]
	v_mul_f32_e32 v163, v164, v144
	v_add_f32_e32 v144, v152, v153
	v_mul_f32_e32 v154, v164, v144
	v_mov_b32_e32 v152, v93
	v_mov_b32_e32 v153, v73
	v_mov_b32_e32 v144, v149
	v_pk_mul_f32 v[148:149], v[152:153], v[144:145]
	s_nop 0
	v_sub_f32_e32 v148, v148, v149
	v_mul_f32_e32 v152, v164, v148
	v_mov_b32_e32 v148, v73
	v_mov_b32_e32 v149, v93
	v_pk_mul_f32 v[144:145], v[148:149], v[144:145]
	v_mov_b32_e32 v148, v150
	v_add_f32_e32 v144, v144, v145
	v_mul_f32_e32 v153, v164, v144
	v_mov_b32_e32 v144, v94
	v_mov_b32_e32 v145, v74
	v_mov_b32_e32 v149, v146
	v_pk_mul_f32 v[144:145], v[144:145], v[148:149]
	v_mov_b32_e32 v146, v151
	v_sub_f32_e32 v144, v144, v145
	v_mul_f32_e32 v150, v164, v144
	v_mov_b32_e32 v144, v74
	v_mov_b32_e32 v145, v94
	v_pk_mul_f32 v[144:145], v[144:145], v[148:149]
	s_nop 0
	v_add_f32_e32 v144, v144, v145
	v_mul_f32_e32 v155, v164, v144
	v_mov_b32_e32 v144, v95
	v_mov_b32_e32 v145, v75
	v_pk_mul_f32 v[144:145], v[144:145], v[146:147]
	s_nop 0
	v_sub_f32_e32 v144, v144, v145
	v_mul_f32_e32 v148, v164, v144
	v_mov_b32_e32 v144, v75
	v_mov_b32_e32 v145, v95
	v_pk_mul_f32 v[144:145], v[144:145], v[146:147]
	s_nop 0
	v_add_f32_e32 v144, v144, v145
	v_mul_f32_e32 v151, v164, v144
	v_cvt_pk_bf16_f32 v144, v165, v160
	v_cvt_pk_bf16_f32 v145, v158, v157
	v_cvt_pk_bf16_f32 v146, v163, v152
	v_cvt_pk_bf16_f32 v147, v150, v148
	v_cvt_pk_bf16_f32 v148, v162, v161
	v_cvt_pk_bf16_f32 v149, v156, v159
	v_cvt_pk_bf16_f32 v150, v154, v153
	v_lshlrev_b64 v[152:153], 12, v[224:225]
	v_lshl_add_u64 v[152:153], v[230:231], 0, v[152:153]
	v_cvt_pk_bf16_f32 v151, v155, v151
	global_store_dwordx4 v[152:153], v[144:147], off
	global_store_dwordx4 v[152:153], v[148:151], off offset:256
	s_nop 0
	v_bitop3_b32 v144, v228, s4, 48 bitop3:0xc8
	v_add_u32_e32 v144, 1, v144
	v_cvt_f32_ubyte0_e32 v144, v144
	v_mul_f32_e64 v145, v241, -v144
	v_cmp_gt_f32_e64 s[4:5], s7, v145
	v_mov_b32_e32 v147, v136
	s_nop 0
	v_cndmask_b32_e64 v146, 0, v234, s[4:5]
	v_fma_f32 v144, v241, -v144, v146
	v_exp_f32_e32 v144, v144
	v_cndmask_b32_e64 v145, 0, v235, s[4:5]
	v_mov_b32_e32 v146, v140
	s_mov_b64 s[4:5], 0x80000
	v_ldexp_f32 v144, v144, v145
	v_mul_f32_e32 v144, 0x3d800000, v144
	v_cndmask_b32_e32 v148, 1.0, v144, vcc
	v_mov_b32_e32 v144, v84
	v_mov_b32_e32 v145, v68
	v_pk_mul_f32 v[144:145], v[144:145], v[146:147]
	s_nop 0
	v_sub_f32_e32 v136, v144, v145
	v_mov_b32_e32 v144, v68
	v_mov_b32_e32 v145, v84
	v_pk_mul_f32 v[144:145], v[144:145], v[146:147]
	v_mul_f32_e32 v149, v148, v136
	v_add_f32_e32 v136, v144, v145
	v_mul_f32_e32 v146, v148, v136
	v_mov_b32_e32 v144, v85
	v_mov_b32_e32 v145, v69
	v_mov_b32_e32 v136, v141
	v_pk_mul_f32 v[140:141], v[144:145], v[136:137]
	s_nop 0
	v_sub_f32_e32 v140, v140, v141
	v_mul_f32_e32 v144, v148, v140
	v_mov_b32_e32 v140, v69
	v_mov_b32_e32 v141, v85
	v_pk_mul_f32 v[136:137], v[140:141], v[136:137]
	v_mov_b32_e32 v140, v142
	v_add_f32_e32 v136, v136, v137
	v_mul_f32_e32 v145, v148, v136
	v_mov_b32_e32 v136, v86
	v_mov_b32_e32 v137, v70
	v_mov_b32_e32 v141, v138
	v_pk_mul_f32 v[136:137], v[136:137], v[140:141]
	v_mov_b32_e32 v138, v143
	v_sub_f32_e32 v136, v136, v137
	v_mul_f32_e32 v142, v148, v136
	v_mov_b32_e32 v136, v70
	v_mov_b32_e32 v137, v86
	v_pk_mul_f32 v[136:137], v[136:137], v[140:141]
	s_nop 0
	v_add_f32_e32 v136, v136, v137
	v_mul_f32_e32 v140, v148, v136
	v_mov_b32_e32 v136, v87
	v_mov_b32_e32 v137, v71
	v_pk_mul_f32 v[136:137], v[136:137], v[138:139]
	s_nop 0
	v_sub_f32_e32 v136, v136, v137
	v_mul_f32_e32 v141, v148, v136
	v_mov_b32_e32 v136, v71
	v_mov_b32_e32 v137, v87
	v_pk_mul_f32 v[136:137], v[136:137], v[138:139]
	v_mov_b32_e32 v138, v132
	v_add_f32_e32 v136, v136, v137
	v_mul_f32_e32 v143, v148, v136
	v_mov_b32_e32 v136, v76
	v_mov_b32_e32 v137, v64
	v_mov_b32_e32 v139, v128
	v_pk_mul_f32 v[136:137], v[136:137], v[138:139]
	s_nop 0
	v_sub_f32_e32 v128, v136, v137
	v_mov_b32_e32 v136, v64
	v_mov_b32_e32 v137, v76
	v_pk_mul_f32 v[136:137], v[136:137], v[138:139]
	v_mul_f32_e32 v147, v148, v128
	v_add_f32_e32 v128, v136, v137
	v_mul_f32_e32 v138, v148, v128
	v_mov_b32_e32 v136, v77
	v_mov_b32_e32 v137, v65
	v_mov_b32_e32 v128, v133
	v_pk_mul_f32 v[132:133], v[136:137], v[128:129]
	s_nop 0
	v_sub_f32_e32 v132, v132, v133
	v_mul_f32_e32 v136, v148, v132
	v_mov_b32_e32 v132, v65
	v_mov_b32_e32 v133, v77
	v_pk_mul_f32 v[128:129], v[132:133], v[128:129]
	v_mov_b32_e32 v132, v134
	v_add_f32_e32 v128, v128, v129
	v_mul_f32_e32 v137, v148, v128
	v_mov_b32_e32 v128, v78
	v_mov_b32_e32 v129, v66
	v_mov_b32_e32 v133, v130
	v_pk_mul_f32 v[128:129], v[128:129], v[132:133]
	v_mov_b32_e32 v130, v135
	v_sub_f32_e32 v128, v128, v129
	v_mul_f32_e32 v134, v148, v128
	v_mov_b32_e32 v128, v66
	v_mov_b32_e32 v129, v78
	v_pk_mul_f32 v[128:129], v[128:129], v[132:133]
	s_nop 0
	v_add_f32_e32 v128, v128, v129
	v_mul_f32_e32 v139, v148, v128
	v_mov_b32_e32 v128, v79
	v_mov_b32_e32 v129, v67
	v_pk_mul_f32 v[128:129], v[128:129], v[130:131]
	s_nop 0
	v_sub_f32_e32 v128, v128, v129
	v_mul_f32_e32 v132, v148, v128
	v_mov_b32_e32 v128, v67
	v_mov_b32_e32 v129, v79
	v_pk_mul_f32 v[128:129], v[128:129], v[130:131]
	s_nop 0
	v_add_f32_e32 v128, v128, v129
	v_mul_f32_e32 v135, v148, v128
	v_cvt_pk_bf16_f32 v128, v149, v144
	v_cvt_pk_bf16_f32 v129, v142, v141
	v_cvt_pk_bf16_f32 v130, v147, v136
	v_cvt_pk_bf16_f32 v131, v134, v132
	v_cvt_pk_bf16_f32 v132, v146, v145
	v_cvt_pk_bf16_f32 v133, v140, v143
	v_cvt_pk_bf16_f32 v134, v138, v137
	v_lshlrev_b64 v[136:137], 12, v[222:223]
	v_lshl_add_u64 v[136:137], v[230:231], 0, v[136:137]
	v_cvt_pk_bf16_f32 v135, v139, v135
	global_store_dwordx4 v[136:137], v[128:131], off
	global_store_dwordx4 v[136:137], v[132:135], off offset:256
	s_nop 0
	v_mov_b32_e32 v128, 0x4000
	v_lshl_add_u32 v128, v228, 7, v128
	v_and_b32_e32 v128, 0x7e780, v128
	v_lshlrev_b32_e32 v128, 2, v128
	v_mov_b32_e32 v129, v193
	v_lshl_add_u64 v[130:131], v[214:215], 0, v[128:129]
	v_lshl_add_u64 v[132:133], v[216:217], 0, v[128:129]
	global_load_dwordx4 v[168:171], v[130:131], off offset:16
	global_load_dwordx4 v[172:175], v[130:131], off
	global_load_dwordx4 v[178:181], v[132:133], off offset:16
	global_load_dwordx4 v[182:185], v[132:133], off
	v_or_b32_e32 v130, 0x2000, v128
	v_mov_b32_e32 v131, v193
	v_lshl_add_u64 v[132:133], v[214:215], 0, v[130:131]
	v_lshl_add_u64 v[130:131], v[216:217], 0, v[130:131]
	global_load_dwordx4 v[164:167], v[132:133], off offset:16
	global_load_dwordx4 v[186:189], v[132:133], off
	global_load_dwordx4 v[160:163], v[130:131], off offset:16
	global_load_dwordx4 v[196:199], v[130:131], off
	v_or_b32_e32 v130, 0x4000, v128
	v_mov_b32_e32 v131, v193
	v_lshl_add_u64 v[132:133], v[214:215], 0, v[130:131]
	v_lshl_add_u64 v[130:131], v[216:217], 0, v[130:131]
	global_load_dwordx4 v[148:151], v[132:133], off offset:16
	global_load_dwordx4 v[156:159], v[132:133], off
	global_load_dwordx4 v[144:147], v[130:131], off offset:16
	global_load_dwordx4 v[152:155], v[130:131], off
	v_or_b32_e32 v128, 0x6000, v128
	v_lshl_add_u64 v[130:131], v[214:215], 0, v[128:129]
	v_lshl_add_u64 v[136:137], v[216:217], 0, v[128:129]
	global_load_dwordx4 v[132:135], v[130:131], off offset:16
	global_load_dwordx4 v[140:143], v[130:131], off
	s_nop 0
	global_load_dwordx4 v[128:131], v[136:137], off offset:16
	s_nop 0
	global_load_dwordx4 v[136:139], v[136:137], off
	s_waitcnt vmcnt(0)
	v_mov_b32_e32 v244, v172
	v_mov_b32_e32 v245, v182
	v_pk_mul_f32 v[190:191], v[190:191], v[244:245]
	v_mov_b32_e32 v182, v173
	v_sub_f32_e32 v172, v190, v191
	v_mov_b32_e32 v190, v48
	v_mov_b32_e32 v191, v60
	v_pk_mul_f32 v[190:191], v[190:191], v[244:245]
	v_mul_f32_e32 v223, v242, v172
	v_add_f32_e32 v172, v190, v191
	v_mov_b32_e32 v190, v61
	v_mov_b32_e32 v191, v49
	v_mul_f32_e32 v225, v242, v172
	v_pk_mul_f32 v[172:173], v[190:191], v[182:183]
	s_nop 0
	v_sub_f32_e32 v172, v172, v173
	v_mul_f32_e32 v190, v242, v172
	v_mov_b32_e32 v172, v49
	v_mov_b32_e32 v173, v61
	v_pk_mul_f32 v[172:173], v[172:173], v[182:183]
	v_mov_b32_e32 v182, v174
	v_add_f32_e32 v172, v172, v173
	v_mul_f32_e32 v191, v242, v172
	v_mov_b32_e32 v172, v62
	v_mov_b32_e32 v173, v50
	v_mov_b32_e32 v183, v184
	v_pk_mul_f32 v[172:173], v[172:173], v[182:183]
	v_mov_b32_e32 v184, v175
	v_sub_f32_e32 v172, v172, v173
	v_mul_f32_e32 v243, v242, v172
	v_mov_b32_e32 v172, v50
	v_mov_b32_e32 v173, v62
	v_pk_mul_f32 v[172:173], v[172:173], v[182:183]
	v_mov_b32_e32 v174, v168
	v_add_f32_e32 v172, v172, v173
	v_mul_f32_e32 v182, v242, v172
	v_mov_b32_e32 v172, v63
	v_mov_b32_e32 v173, v51
	v_pk_mul_f32 v[172:173], v[172:173], v[184:185]
	v_mov_b32_e32 v175, v178
	v_sub_f32_e32 v172, v172, v173
	v_mul_f32_e32 v183, v242, v172
	v_mov_b32_e32 v172, v51
	v_mov_b32_e32 v173, v63
	v_pk_mul_f32 v[172:173], v[172:173], v[184:185]
	v_mov_b32_e32 v178, v169
	v_add_f32_e32 v172, v172, v173
	v_mul_f32_e32 v184, v242, v172
	v_mov_b32_e32 v172, v56
	v_mov_b32_e32 v173, v40
	v_pk_mul_f32 v[172:173], v[172:173], v[174:175]
	s_nop 0
	v_sub_f32_e32 v168, v172, v173
	v_mov_b32_e32 v172, v40
	v_mov_b32_e32 v173, v56
	v_pk_mul_f32 v[172:173], v[172:173], v[174:175]
	v_mul_f32_e32 v185, v242, v168
	v_add_f32_e32 v168, v172, v173
	v_mov_b32_e32 v172, v57
	v_mov_b32_e32 v173, v41
	v_mul_f32_e32 v174, v242, v168
	v_pk_mul_f32 v[168:169], v[172:173], v[178:179]
	v_mov_b32_e32 v172, v170
	v_sub_f32_e32 v168, v168, v169
	v_mul_f32_e32 v175, v242, v168
	v_mov_b32_e32 v168, v41
	v_mov_b32_e32 v169, v57
	v_pk_mul_f32 v[168:169], v[168:169], v[178:179]
	v_mov_b32_e32 v173, v180
	v_add_f32_e32 v168, v168, v169
	v_mul_f32_e32 v178, v242, v168
	v_mov_b32_e32 v168, v58
	v_mov_b32_e32 v169, v42
	v_pk_mul_f32 v[168:169], v[168:169], v[172:173]
	v_mov_b32_e32 v180, v171
	v_sub_f32_e32 v168, v168, v169
	v_mul_f32_e32 v179, v242, v168
	v_mov_b32_e32 v168, v42
	v_mov_b32_e32 v169, v58
	v_pk_mul_f32 v[168:169], v[168:169], v[172:173]
	s_nop 0
	v_add_f32_e32 v168, v168, v169
	v_mul_f32_e32 v244, v242, v168
	v_mov_b32_e32 v168, v59
	v_mov_b32_e32 v169, v43
	v_pk_mul_f32 v[168:169], v[168:169], v[180:181]
	s_nop 0
	v_sub_f32_e32 v168, v168, v169
	v_mul_f32_e32 v171, v242, v168
	v_mov_b32_e32 v168, v43
	v_mov_b32_e32 v169, v59
	v_pk_mul_f32 v[168:169], v[168:169], v[180:181]
	s_nop 0
	v_add_f32_e32 v168, v168, v169
	v_mul_f32_e32 v180, v242, v168
	v_cvt_pk_bf16_f32 v168, v223, v190
	v_cvt_pk_bf16_f32 v169, v243, v183
	v_cvt_pk_bf16_f32 v170, v185, v175
	v_cvt_pk_bf16_f32 v171, v179, v171
	v_cvt_pk_bf16_f32 v172, v225, v191
	v_cvt_pk_bf16_f32 v173, v182, v184
	v_cvt_pk_bf16_f32 v174, v174, v178
	v_lshl_add_u64 v[178:179], v[176:177], 0, s[4:5]
	s_mov_b32 s4, 0x80000
	v_add_co_u32_e64 v176, s[4:5], s4, v176
	v_cvt_pk_bf16_f32 v175, v244, v180
	s_nop 1
	v_addc_co_u32_e64 v177, s[4:5], 0, v177, s[4:5]
	global_store_dwordx4 v[176:177], v[168:171], off
	global_store_dwordx4 v[178:179], v[172:175], off offset:256
	s_nop 0
	v_add_u32_e32 v168, 0x90, v228
	v_and_b32_e32 v169, 0x5f, v168
	v_add_u32_e32 v169, 1, v169
	v_cvt_f32_ubyte0_e32 v169, v169
	v_mul_f32_e64 v170, v241, -v169
	v_cmp_gt_f32_e64 s[4:5], s7, v170
	v_mov_b32_e32 v171, v32
	v_mov_b32_e32 v172, v186
	v_cndmask_b32_e64 v170, 0, v234, s[4:5]
	v_fma_f32 v169, v241, -v169, v170
	v_exp_f32_e32 v169, v169
	v_cndmask_b32_e64 v170, 0, v235, s[4:5]
	v_mov_b32_e32 v173, v196
	v_mov_b32_e32 v196, v187
	v_ldexp_f32 v169, v169, v170
	v_mov_b32_e32 v170, v52
	v_mul_f32_e32 v169, 0x3d800000, v169
	v_pk_mul_f32 v[170:171], v[170:171], v[172:173]
	v_cndmask_b32_e32 v169, 1.0, v169, vcc
	v_sub_f32_e32 v170, v170, v171
	v_mul_f32_e32 v174, v169, v170
	v_mov_b32_e32 v170, v32
	v_mov_b32_e32 v171, v52
	v_pk_mul_f32 v[170:171], v[170:171], v[172:173]
	v_mov_b32_e32 v172, v188
	v_add_f32_e32 v170, v170, v171
	v_mul_f32_e32 v175, v169, v170
	v_mov_b32_e32 v170, v53
	v_mov_b32_e32 v171, v33
	v_pk_mul_f32 v[170:171], v[170:171], v[196:197]
	v_mov_b32_e32 v173, v198
	v_sub_f32_e32 v170, v170, v171
	v_mul_f32_e32 v176, v169, v170
	v_mov_b32_e32 v170, v33
	v_mov_b32_e32 v171, v53
	v_pk_mul_f32 v[170:171], v[170:171], v[196:197]
	v_mov_b32_e32 v198, v189
	v_add_f32_e32 v170, v170, v171
	v_mul_f32_e32 v177, v169, v170
	v_mov_b32_e32 v170, v54
	v_mov_b32_e32 v171, v34
	v_pk_mul_f32 v[170:171], v[170:171], v[172:173]
	s_nop 0
	v_sub_f32_e32 v170, v170, v171
	v_mul_f32_e32 v178, v169, v170
	v_mov_b32_e32 v170, v34
	v_mov_b32_e32 v171, v54
	v_pk_mul_f32 v[170:171], v[170:171], v[172:173]
	v_mov_b32_e32 v172, v164
	v_add_f32_e32 v170, v170, v171
	v_mul_f32_e32 v179, v169, v170
	v_mov_b32_e32 v170, v55
	v_mov_b32_e32 v171, v35
	v_pk_mul_f32 v[170:171], v[170:171], v[198:199]
	v_mov_b32_e32 v173, v160
	v_sub_f32_e32 v170, v170, v171
	v_mul_f32_e32 v180, v169, v170
	v_mov_b32_e32 v170, v35
	v_mov_b32_e32 v171, v55
	v_pk_mul_f32 v[170:171], v[170:171], v[198:199]
	s_nop 0
	v_add_f32_e32 v170, v170, v171
	v_mul_f32_e32 v181, v169, v170
	v_mov_b32_e32 v170, v44
	v_mov_b32_e32 v171, v24
	v_pk_mul_f32 v[170:171], v[170:171], v[172:173]
	s_nop 0
	v_sub_f32_e32 v160, v170, v171
	v_mov_b32_e32 v170, v24
	v_mov_b32_e32 v171, v44
	v_pk_mul_f32 v[170:171], v[170:171], v[172:173]
	v_mul_f32_e32 v182, v169, v160
	v_add_f32_e32 v160, v170, v171
	v_mul_f32_e32 v172, v169, v160
	v_mov_b32_e32 v170, v45
	v_mov_b32_e32 v171, v25
	v_mov_b32_e32 v160, v165
	v_pk_mul_f32 v[164:165], v[170:171], v[160:161]
	s_nop 0
	v_sub_f32_e32 v164, v164, v165
	v_mul_f32_e32 v170, v169, v164
	v_mov_b32_e32 v164, v25
	v_mov_b32_e32 v165, v45
	v_pk_mul_f32 v[160:161], v[164:165], v[160:161]
	v_mov_b32_e32 v164, v166
	v_add_f32_e32 v160, v160, v161
	v_mul_f32_e32 v171, v169, v160
	v_mov_b32_e32 v160, v46
	v_mov_b32_e32 v161, v26
	v_mov_b32_e32 v165, v162
	v_pk_mul_f32 v[160:161], v[160:161], v[164:165]
	v_mov_b32_e32 v162, v167
	v_sub_f32_e32 v160, v160, v161
	v_mul_f32_e32 v166, v169, v160
	v_mov_b32_e32 v160, v26
	v_mov_b32_e32 v161, v46
	v_pk_mul_f32 v[160:161], v[160:161], v[164:165]
	s_nop 0
	v_add_f32_e32 v160, v160, v161
	v_mul_f32_e32 v173, v169, v160
	v_mov_b32_e32 v160, v47
	v_mov_b32_e32 v161, v27
	v_pk_mul_f32 v[160:161], v[160:161], v[162:163]
	s_nop 0
	v_sub_f32_e32 v160, v160, v161
	v_mul_f32_e32 v164, v169, v160
	v_mov_b32_e32 v160, v27
	v_mov_b32_e32 v161, v47
	v_pk_mul_f32 v[160:161], v[160:161], v[162:163]
	s_nop 0
	v_add_f32_e32 v160, v160, v161
	v_mul_f32_e32 v167, v169, v160
	v_ashrrev_i32_e32 v169, 31, v168
	v_lshlrev_b64 v[168:169], 12, v[168:169]
	v_cvt_pk_bf16_f32 v160, v174, v176
	v_cvt_pk_bf16_f32 v161, v178, v180
	v_cvt_pk_bf16_f32 v162, v182, v170
	v_cvt_pk_bf16_f32 v163, v166, v164
	v_lshl_add_u64 v[168:169], v[230:231], 0, v[168:169]
	v_cvt_pk_bf16_f32 v164, v175, v177
	v_cvt_pk_bf16_f32 v165, v179, v181
	v_cvt_pk_bf16_f32 v166, v172, v171
	v_cvt_pk_bf16_f32 v167, v173, v167
	global_store_dwordx4 v[168:169], v[160:163], off
	global_store_dwordx4 v[168:169], v[164:167], off offset:256
	s_nop 0
	v_add_u32_e32 v160, 0xa0, v228
	v_and_b32_e32 v161, 0x6f, v160
	v_add_u32_e32 v161, 1, v161
	v_cvt_f32_ubyte0_e32 v161, v161
	v_mul_f32_e64 v162, v241, -v161
	v_cmp_gt_f32_e64 s[4:5], s7, v162
	v_mov_b32_e32 v163, v16
	v_mov_b32_e32 v164, v156
	v_cndmask_b32_e64 v162, 0, v234, s[4:5]
	v_fma_f32 v161, v241, -v161, v162
	v_exp_f32_e32 v161, v161
	v_cndmask_b32_e64 v162, 0, v235, s[4:5]
	v_mov_b32_e32 v165, v152
	v_ldexp_f32 v161, v161, v162
	v_mov_b32_e32 v162, v36
	v_pk_mul_f32 v[162:163], v[162:163], v[164:165]
	v_mul_f32_e32 v161, 0x3d800000, v161
	v_sub_f32_e32 v152, v162, v163
	v_mov_b32_e32 v162, v16
	v_mov_b32_e32 v163, v36
	v_cndmask_b32_e32 v161, 1.0, v161, vcc
	v_pk_mul_f32 v[162:163], v[162:163], v[164:165]
	v_mul_f32_e32 v166, v161, v152
	v_add_f32_e32 v152, v162, v163
	v_mul_f32_e32 v164, v161, v152
	v_mov_b32_e32 v162, v37
	v_mov_b32_e32 v163, v17
	v_mov_b32_e32 v152, v157
	v_pk_mul_f32 v[156:157], v[162:163], v[152:153]
	s_nop 0
	v_sub_f32_e32 v156, v156, v157
	v_mul_f32_e32 v162, v161, v156
	v_mov_b32_e32 v156, v17
	v_mov_b32_e32 v157, v37
	v_pk_mul_f32 v[152:153], v[156:157], v[152:153]
	v_mov_b32_e32 v156, v158
	v_add_f32_e32 v152, v152, v153
	v_mul_f32_e32 v163, v161, v152
	v_mov_b32_e32 v152, v38
	v_mov_b32_e32 v153, v18
	v_mov_b32_e32 v157, v154
	v_pk_mul_f32 v[152:153], v[152:153], v[156:157]
	v_mov_b32_e32 v154, v159
	v_sub_f32_e32 v152, v152, v153
	v_mul_f32_e32 v158, v161, v152
	v_mov_b32_e32 v152, v18
	v_mov_b32_e32 v153, v38
	v_pk_mul_f32 v[152:153], v[152:153], v[156:157]
	s_nop 0
	v_add_f32_e32 v152, v152, v153
	v_mul_f32_e32 v156, v161, v152
	v_mov_b32_e32 v152, v39
	v_mov_b32_e32 v153, v19
	v_pk_mul_f32 v[152:153], v[152:153], v[154:155]
	s_nop 0
	v_sub_f32_e32 v152, v152, v153
	v_mul_f32_e32 v157, v161, v152
	v_mov_b32_e32 v152, v19
	v_mov_b32_e32 v153, v39
	v_pk_mul_f32 v[152:153], v[152:153], v[154:155]
	v_mov_b32_e32 v154, v148
	v_add_f32_e32 v152, v152, v153
	v_mul_f32_e32 v159, v161, v152
	v_mov_b32_e32 v152, v28
	v_mov_b32_e32 v153, v8
	v_mov_b32_e32 v155, v144
	v_pk_mul_f32 v[152:153], v[152:153], v[154:155]
	s_nop 0
	v_sub_f32_e32 v144, v152, v153
	v_mov_b32_e32 v152, v8
	v_mov_b32_e32 v153, v28
	v_pk_mul_f32 v[152:153], v[152:153], v[154:155]
	v_mul_f32_e32 v165, v161, v144
	v_add_f32_e32 v144, v152, v153
	v_mul_f32_e32 v154, v161, v144
	v_mov_b32_e32 v152, v29
	v_mov_b32_e32 v153, v9
	v_mov_b32_e32 v144, v149
	v_pk_mul_f32 v[148:149], v[152:153], v[144:145]
	s_nop 0
	v_sub_f32_e32 v148, v148, v149
	v_mul_f32_e32 v152, v161, v148
	v_mov_b32_e32 v148, v9
	v_mov_b32_e32 v149, v29
	v_pk_mul_f32 v[144:145], v[148:149], v[144:145]
	v_mov_b32_e32 v148, v150
	v_add_f32_e32 v144, v144, v145
	v_mul_f32_e32 v153, v161, v144
	v_mov_b32_e32 v144, v30
	v_mov_b32_e32 v145, v10
	v_mov_b32_e32 v149, v146
	v_pk_mul_f32 v[144:145], v[144:145], v[148:149]
	v_mov_b32_e32 v146, v151
	v_sub_f32_e32 v144, v144, v145
	v_mul_f32_e32 v150, v161, v144
	v_mov_b32_e32 v144, v10
	v_mov_b32_e32 v145, v30
	v_pk_mul_f32 v[144:145], v[144:145], v[148:149]
	s_nop 0
	v_add_f32_e32 v144, v144, v145
	v_mul_f32_e32 v155, v161, v144
	v_mov_b32_e32 v144, v31
	v_mov_b32_e32 v145, v11
	v_pk_mul_f32 v[144:145], v[144:145], v[146:147]
	s_nop 0
	v_sub_f32_e32 v144, v144, v145
	v_mul_f32_e32 v148, v161, v144
	v_mov_b32_e32 v144, v11
	v_mov_b32_e32 v145, v31
	v_pk_mul_f32 v[144:145], v[144:145], v[146:147]
	s_nop 0
	v_add_f32_e32 v144, v144, v145
	v_mul_f32_e32 v151, v161, v144
	v_ashrrev_i32_e32 v161, 31, v160
	v_cvt_pk_bf16_f32 v144, v166, v162
	v_cvt_pk_bf16_f32 v145, v158, v157
	v_cvt_pk_bf16_f32 v146, v165, v152
	v_cvt_pk_bf16_f32 v147, v150, v148
	v_cvt_pk_bf16_f32 v148, v164, v163
	v_cvt_pk_bf16_f32 v149, v156, v159
	v_cvt_pk_bf16_f32 v150, v154, v153
	v_lshlrev_b64 v[152:153], 12, v[160:161]
	v_lshl_add_u64 v[152:153], v[230:231], 0, v[152:153]
	v_cvt_pk_bf16_f32 v151, v155, v151
	global_store_dwordx4 v[152:153], v[144:147], off
	global_store_dwordx4 v[152:153], v[148:151], off offset:256
	s_nop 0
	v_add_u32_e32 v144, 0xb0, v228
	v_and_b32_e32 v145, 0x7f, v144
	v_add_u32_e32 v145, 1, v145
	v_cvt_f32_ubyte0_e32 v145, v145
	v_mul_f32_e64 v146, v241, -v145
	v_cmp_gt_f32_e64 s[4:5], s7, v146
	v_mov_b32_e32 v147, v4
	v_mov_b32_e32 v148, v140
	v_cndmask_b32_e64 v146, 0, v234, s[4:5]
	v_fma_f32 v145, v241, -v145, v146
	v_exp_f32_e32 v145, v145
	v_cndmask_b32_e64 v146, 0, v235, s[4:5]
	v_mov_b32_e32 v149, v136
	s_mov_b64 s[4:5], 0
	v_ldexp_f32 v145, v145, v146
	v_mov_b32_e32 v146, v20
	v_pk_mul_f32 v[146:147], v[146:147], v[148:149]
	v_mul_f32_e32 v145, 0x3d800000, v145
	v_sub_f32_e32 v136, v146, v147
	v_mov_b32_e32 v146, v4
	v_mov_b32_e32 v147, v20
	v_cndmask_b32_e32 v145, 1.0, v145, vcc
	v_pk_mul_f32 v[146:147], v[146:147], v[148:149]
	v_mul_f32_e32 v150, v145, v136
	v_add_f32_e32 v136, v146, v147
	v_mul_f32_e32 v148, v145, v136
	v_mov_b32_e32 v146, v21
	v_mov_b32_e32 v147, v5
	v_mov_b32_e32 v136, v141
	v_pk_mul_f32 v[140:141], v[146:147], v[136:137]
	s_nop 0
	v_sub_f32_e32 v140, v140, v141
	v_mul_f32_e32 v146, v145, v140
	v_mov_b32_e32 v140, v5
	v_mov_b32_e32 v141, v21
	v_pk_mul_f32 v[136:137], v[140:141], v[136:137]
	v_mov_b32_e32 v140, v142
	v_add_f32_e32 v136, v136, v137
	v_mul_f32_e32 v147, v145, v136
	v_mov_b32_e32 v136, v22
	v_mov_b32_e32 v137, v6
	v_mov_b32_e32 v141, v138
	v_pk_mul_f32 v[136:137], v[136:137], v[140:141]
	v_mov_b32_e32 v138, v143
	v_sub_f32_e32 v136, v136, v137
	v_mul_f32_e32 v142, v145, v136
	v_mov_b32_e32 v136, v6
	v_mov_b32_e32 v137, v22
	v_pk_mul_f32 v[136:137], v[136:137], v[140:141]
	s_nop 0
	v_add_f32_e32 v136, v136, v137
	v_mul_f32_e32 v140, v145, v136
	v_mov_b32_e32 v136, v23
	v_mov_b32_e32 v137, v7
	v_pk_mul_f32 v[136:137], v[136:137], v[138:139]
	s_nop 0
	v_sub_f32_e32 v136, v136, v137
	v_mul_f32_e32 v141, v145, v136
	v_mov_b32_e32 v136, v7
	v_mov_b32_e32 v137, v23
	v_pk_mul_f32 v[136:137], v[136:137], v[138:139]
	v_mov_b32_e32 v138, v132
	v_add_f32_e32 v136, v136, v137
	v_mul_f32_e32 v143, v145, v136
	v_mov_b32_e32 v136, v12
	v_mov_b32_e32 v137, v0
	v_mov_b32_e32 v139, v128
	v_pk_mul_f32 v[136:137], v[136:137], v[138:139]
	s_nop 0
	v_sub_f32_e32 v128, v136, v137
	v_mov_b32_e32 v136, v0
	v_mov_b32_e32 v137, v12
	v_pk_mul_f32 v[136:137], v[136:137], v[138:139]
	v_mul_f32_e32 v149, v145, v128
	v_add_f32_e32 v128, v136, v137
	v_mul_f32_e32 v138, v145, v128
	v_mov_b32_e32 v136, v13
	v_mov_b32_e32 v137, v1
	v_mov_b32_e32 v128, v133
	v_pk_mul_f32 v[132:133], v[136:137], v[128:129]
	s_nop 0
	v_sub_f32_e32 v132, v132, v133
	v_mul_f32_e32 v136, v145, v132
	v_mov_b32_e32 v132, v1
	v_mov_b32_e32 v133, v13
	v_pk_mul_f32 v[128:129], v[132:133], v[128:129]
	v_mov_b32_e32 v132, v134
	v_add_f32_e32 v128, v128, v129
	v_mul_f32_e32 v139, v145, v128
	v_mov_b32_e32 v128, v14
	v_mov_b32_e32 v129, v2
	v_mov_b32_e32 v133, v130
	v_pk_mul_f32 v[128:129], v[128:129], v[132:133]
	v_mov_b32_e32 v130, v135
	v_sub_f32_e32 v128, v128, v129
	v_mul_f32_e32 v137, v145, v128
	v_mov_b32_e32 v128, v2
	v_mov_b32_e32 v129, v14
	v_pk_mul_f32 v[128:129], v[128:129], v[132:133]
	v_cvt_pk_bf16_f32 v134, v150, v146
	v_cvt_pk_bf16_f32 v135, v142, v141
	v_cvt_pk_bf16_f32 v136, v149, v136
	s_nop 0
	v_add_f32_e32 v128, v128, v129
	v_mul_f32_e32 v132, v145, v128
	v_mov_b32_e32 v128, v15
	v_mov_b32_e32 v129, v3
	v_pk_mul_f32 v[128:129], v[128:129], v[130:131]
	s_nop 0
	v_sub_f32_e32 v128, v128, v129
	v_mul_f32_e32 v133, v145, v128
	v_mov_b32_e32 v128, v3
	v_mov_b32_e32 v129, v15
	v_pk_mul_f32 v[128:129], v[128:129], v[130:131]
	v_cvt_pk_bf16_f32 v137, v137, v133
	s_nop 0
	v_add_f32_e32 v128, v128, v129
	v_mul_f32_e32 v131, v145, v128
	v_ashrrev_i32_e32 v145, 31, v144
	v_cvt_pk_bf16_f32 v128, v148, v147
	v_cvt_pk_bf16_f32 v129, v140, v143
	v_cvt_pk_bf16_f32 v130, v138, v139
	v_cvt_pk_bf16_f32 v131, v132, v131
	v_lshlrev_b64 v[132:133], 12, v[144:145]
	v_lshl_add_u64 v[132:133], v[230:231], 0, v[132:133]
	global_store_dwordx4 v[132:133], v[134:137], off

.LBB0_217:
	ds_read_b128 v[144:147], v220 offset:0
	ds_read_b128 v[148:151], v220 offset:1024
	ds_read_b128 v[152:155], v220 offset:2048
	ds_read_b128 v[156:159], v220 offset:3072
	ds_read_b128 v[160:163], v143
	ds_read_b128 v[164:167], v143 offset:1024
	ds_read_b128 v[168:171], v143 offset:2048
	ds_read_b128 v[172:175], v143 offset:3072
	ds_read_b128 v[176:179], v143 offset:4096
	ds_read_b128 v[180:183], v143 offset:5120
	ds_read_b128 v[184:187], v143 offset:6144
	ds_read_b128 v[188:191], v143 offset:7168
	global_load_lds_dwordx4 v134, s[14:15]
	s_add_i32 m0, s13, 0xe000
	s_nop 0
	global_load_lds_dwordx4 v136, s[14:15]
	s_waitcnt lgkmcnt(8)
	s_barrier
	s_waitcnt lgkmcnt(0)
	v_mfma_f32_16x16x32_bf16 v[124:127], v[144:147], v[160:163], v[124:127]
	v_mfma_f32_16x16x32_bf16 v[116:119], v[152:155], v[160:163], v[116:119]
	v_mfma_f32_16x16x32_bf16 v[108:111], v[144:147], v[168:171], v[108:111]
	v_mfma_f32_16x16x32_bf16 v[100:103], v[152:155], v[168:171], v[100:103]
	s_add_i32 s44, 0, 0x14000
	s_add_i32 s41, s41, s26
	v_mfma_f32_16x16x32_bf16 v[92:95], v[144:147], v[176:179], v[92:95]
	s_mov_b32 m0, s41
	v_mfma_f32_16x16x32_bf16 v[84:87], v[152:155], v[176:179], v[84:87]
	v_mfma_f32_16x16x32_bf16 v[76:79], v[144:147], v[184:187], v[76:79]
	v_mfma_f32_16x16x32_bf16 v[68:71], v[152:155], v[184:187], v[68:71]
	v_mfma_f32_16x16x32_bf16 v[124:127], v[148:151], v[164:167], v[124:127]
	v_mfma_f32_16x16x32_bf16 v[116:119], v[156:159], v[164:167], v[116:119]
	v_mfma_f32_16x16x32_bf16 v[108:111], v[148:151], v[172:175], v[108:111]
	v_mfma_f32_16x16x32_bf16 v[100:103], v[156:159], v[172:175], v[100:103]
	v_mfma_f32_16x16x32_bf16 v[92:95], v[148:151], v[180:183], v[92:95]
	v_mfma_f32_16x16x32_bf16 v[84:87], v[156:159], v[180:183], v[84:87]
	v_mfma_f32_16x16x32_bf16 v[76:79], v[148:151], v[188:191], v[76:79]
	v_mfma_f32_16x16x32_bf16 v[68:71], v[156:159], v[188:191], v[68:71]
	s_barrier
	ds_read_b128 v[196:199], v220 offset:16384
	ds_read_b128 v[204:207], v220 offset:17408
	ds_read_b128 v[208:211], v220 offset:18432
	ds_read_b128 v[214:217], v220 offset:19456
	global_load_lds_dwordx4 v192, s[16:17]
	s_add_i32 m0, s41, 0x2000
	s_nop 0
	global_load_lds_dwordx4 v128, s[16:17]
	s_barrier
	s_waitcnt lgkmcnt(0)
	v_mfma_f32_16x16x32_bf16 v[120:123], v[196:199], v[160:163], v[120:123]
	v_mfma_f32_16x16x32_bf16 v[112:115], v[208:211], v[160:163], v[112:115]
	v_mfma_f32_16x16x32_bf16 v[104:107], v[196:199], v[168:171], v[104:107]
	v_mfma_f32_16x16x32_bf16 v[96:99], v[208:211], v[168:171], v[96:99]
	s_mov_b32 m0, s13
	v_mfma_f32_16x16x32_bf16 v[88:91], v[196:199], v[176:179], v[88:91]
	s_add_u32 s48, s18, 0x80
	s_addc_u32 s49, s19, 0
	v_mfma_f32_16x16x32_bf16 v[80:83], v[208:211], v[176:179], v[80:83]
	v_mfma_f32_16x16x32_bf16 v[72:75], v[196:199], v[184:187], v[72:75]
	v_mfma_f32_16x16x32_bf16 v[64:67], v[208:211], v[184:187], v[64:67]
	v_mfma_f32_16x16x32_bf16 v[120:123], v[204:207], v[164:167], v[120:123]
	v_mfma_f32_16x16x32_bf16 v[112:115], v[214:217], v[164:167], v[112:115]
	v_mfma_f32_16x16x32_bf16 v[104:107], v[204:207], v[172:175], v[104:107]
	v_mfma_f32_16x16x32_bf16 v[96:99], v[214:217], v[172:175], v[96:99]
	v_mfma_f32_16x16x32_bf16 v[88:91], v[204:207], v[180:183], v[88:91]
	v_mfma_f32_16x16x32_bf16 v[80:83], v[214:217], v[180:183], v[80:83]
	v_mfma_f32_16x16x32_bf16 v[72:75], v[204:207], v[188:191], v[72:75]
	v_mfma_f32_16x16x32_bf16 v[64:67], v[214:217], v[188:191], v[64:67]
	s_barrier
	ds_read_b128 v[160:163], v143 offset:16384
	ds_read_b128 v[164:167], v143 offset:17408
	ds_read_b128 v[168:171], v143 offset:18432
	ds_read_b128 v[172:175], v143 offset:19456
	ds_read_b128 v[176:179], v143 offset:20480
	ds_read_b128 v[180:183], v143 offset:21504
	ds_read_b128 v[184:187], v143 offset:22528
	ds_read_b128 v[188:191], v143 offset:23552
	global_load_lds_dwordx4 v132, s[18:19]
	s_mov_b32 m0, s28
	s_nop 0
	global_load_lds_dwordx4 v130, s[18:19]
	s_barrier
	s_waitcnt lgkmcnt(0)
	v_mfma_f32_16x16x32_bf16 v[60:63], v[144:147], v[160:163], v[60:63]
	v_mfma_f32_16x16x32_bf16 v[52:55], v[152:155], v[160:163], v[52:55]
	v_mfma_f32_16x16x32_bf16 v[44:47], v[144:147], v[168:171], v[44:47]
	v_mfma_f32_16x16x32_bf16 v[36:39], v[152:155], v[168:171], v[36:39]
	s_add_u32 s42, s16, 0x80000
	s_addc_u32 s43, s17, 0
	v_mfma_f32_16x16x32_bf16 v[28:31], v[144:147], v[176:179], v[28:31]
	s_add_i32 s41, s44, s26
	s_mov_b32 m0, s41
	v_mfma_f32_16x16x32_bf16 v[20:23], v[152:155], v[176:179], v[20:23]
	v_mfma_f32_16x16x32_bf16 v[12:15], v[144:147], v[184:187], v[12:15]
	v_mfma_f32_16x16x32_bf16 v[4:7], v[152:155], v[184:187], v[4:7]
	v_mfma_f32_16x16x32_bf16 v[60:63], v[148:151], v[164:167], v[60:63]
	v_mfma_f32_16x16x32_bf16 v[52:55], v[156:159], v[164:167], v[52:55]
	v_mfma_f32_16x16x32_bf16 v[44:47], v[148:151], v[172:175], v[44:47]
	v_mfma_f32_16x16x32_bf16 v[36:39], v[156:159], v[172:175], v[36:39]
	v_mfma_f32_16x16x32_bf16 v[28:31], v[148:151], v[180:183], v[28:31]
	v_mfma_f32_16x16x32_bf16 v[20:23], v[156:159], v[180:183], v[20:23]
	v_mfma_f32_16x16x32_bf16 v[12:15], v[148:151], v[188:191], v[12:15]
	v_mfma_f32_16x16x32_bf16 v[4:7], v[156:159], v[188:191], v[4:7]
	s_barrier
	global_load_lds_dwordx4 v192, s[42:43]
	s_add_i32 m0, s41, 0x2000
	s_nop 0
	global_load_lds_dwordx4 v128, s[42:43]
	s_waitcnt vmcnt(6)
	s_barrier
	v_mfma_f32_16x16x32_bf16 v[56:59], v[196:199], v[160:163], v[56:59]
	v_mfma_f32_16x16x32_bf16 v[48:51], v[208:211], v[160:163], v[48:51]
	v_mfma_f32_16x16x32_bf16 v[40:43], v[196:199], v[168:171], v[40:43]
	v_mfma_f32_16x16x32_bf16 v[32:35], v[208:211], v[168:171], v[32:35]
	s_add_i32 s41, 0, 0x18000
	v_mfma_f32_16x16x32_bf16 v[24:27], v[196:199], v[176:179], v[24:27]
	s_add_u32 s18, s18, 0x80000
	s_addc_u32 s19, s19, 0
	v_mfma_f32_16x16x32_bf16 v[16:19], v[208:211], v[176:179], v[16:19]
	s_mov_b32 m0, s29
	v_mfma_f32_16x16x32_bf16 v[8:11], v[196:199], v[184:187], v[8:11]
	v_mfma_f32_16x16x32_bf16 v[0:3], v[208:211], v[184:187], v[0:3]
	v_mfma_f32_16x16x32_bf16 v[56:59], v[204:207], v[164:167], v[56:59]
	v_mfma_f32_16x16x32_bf16 v[48:51], v[214:217], v[164:167], v[48:51]
	v_mfma_f32_16x16x32_bf16 v[40:43], v[204:207], v[172:175], v[40:43]
	v_mfma_f32_16x16x32_bf16 v[32:35], v[214:217], v[172:175], v[32:35]
	v_mfma_f32_16x16x32_bf16 v[24:27], v[204:207], v[180:183], v[24:27]
	v_mfma_f32_16x16x32_bf16 v[16:19], v[214:217], v[180:183], v[16:19]
	v_mfma_f32_16x16x32_bf16 v[8:11], v[204:207], v[188:191], v[8:11]
	v_mfma_f32_16x16x32_bf16 v[0:3], v[214:217], v[188:191], v[0:3]
	s_barrier
	ds_read_b128 v[144:147], v220 offset:32768
	ds_read_b128 v[148:151], v220 offset:33792
	ds_read_b128 v[152:155], v220 offset:34816
	ds_read_b128 v[156:159], v220 offset:35840
	ds_read_b128 v[160:163], v143 offset:32768
	ds_read_b128 v[164:167], v143 offset:33792
	ds_read_b128 v[168:171], v143 offset:34816
	ds_read_b128 v[172:175], v143 offset:35840
	ds_read_b128 v[176:179], v143 offset:36864
	ds_read_b128 v[180:183], v143 offset:37888
	ds_read_b128 v[184:187], v143 offset:38912
	ds_read_b128 v[188:191], v143 offset:39936
	global_load_lds_dwordx4 v132, s[18:19]
	s_mov_b32 m0, s30
	s_nop 0
	global_load_lds_dwordx4 v130, s[18:19]
	s_waitcnt lgkmcnt(8)
	s_barrier
	s_waitcnt lgkmcnt(0)
	v_mfma_f32_16x16x32_bf16 v[124:127], v[144:147], v[160:163], v[124:127]
	v_mfma_f32_16x16x32_bf16 v[116:119], v[152:155], v[160:163], v[116:119]
	v_mfma_f32_16x16x32_bf16 v[108:111], v[144:147], v[168:171], v[108:111]
	v_mfma_f32_16x16x32_bf16 v[100:103], v[152:155], v[168:171], v[100:103]
	s_add_i32 s18, 0, 0x1c000
	s_add_i32 s19, s41, s26
	v_mfma_f32_16x16x32_bf16 v[92:95], v[144:147], v[176:179], v[92:95]
	s_add_i32 m0, s19, 0xffffff80
	v_mfma_f32_16x16x32_bf16 v[84:87], v[152:155], v[176:179], v[84:87]
	v_mfma_f32_16x16x32_bf16 v[76:79], v[144:147], v[184:187], v[76:79]
	v_mfma_f32_16x16x32_bf16 v[68:71], v[152:155], v[184:187], v[68:71]
	v_mfma_f32_16x16x32_bf16 v[124:127], v[148:151], v[164:167], v[124:127]
	v_mfma_f32_16x16x32_bf16 v[116:119], v[156:159], v[164:167], v[116:119]
	v_mfma_f32_16x16x32_bf16 v[108:111], v[148:151], v[172:175], v[108:111]
	v_mfma_f32_16x16x32_bf16 v[100:103], v[156:159], v[172:175], v[100:103]
	v_mfma_f32_16x16x32_bf16 v[92:95], v[148:151], v[180:183], v[92:95]
	v_mfma_f32_16x16x32_bf16 v[84:87], v[156:159], v[180:183], v[84:87]
	v_mfma_f32_16x16x32_bf16 v[76:79], v[148:151], v[188:191], v[76:79]
	v_mfma_f32_16x16x32_bf16 v[68:71], v[156:159], v[188:191], v[68:71]
	s_barrier
	ds_read_b128 v[196:199], v220 offset:49152
	ds_read_b128 v[204:207], v220 offset:50176
	ds_read_b128 v[208:211], v220 offset:51200
	ds_read_b128 v[214:217], v220 offset:52224
	global_load_lds_dwordx4 v192, s[16:17] offset:128
	s_add_i32 m0, s19, 0x1f80
	s_nop 0
	global_load_lds_dwordx4 v128, s[16:17] offset:128
	s_barrier
	s_waitcnt lgkmcnt(0)
	v_mfma_f32_16x16x32_bf16 v[120:123], v[196:199], v[160:163], v[120:123]
	v_mfma_f32_16x16x32_bf16 v[112:115], v[208:211], v[160:163], v[112:115]
	v_mfma_f32_16x16x32_bf16 v[104:107], v[196:199], v[168:171], v[104:107]
	v_mfma_f32_16x16x32_bf16 v[96:99], v[208:211], v[168:171], v[96:99]
	s_mov_b32 m0, s33
	v_mfma_f32_16x16x32_bf16 v[88:91], v[196:199], v[176:179], v[88:91]
	v_mfma_f32_16x16x32_bf16 v[80:83], v[208:211], v[176:179], v[80:83]
	v_mfma_f32_16x16x32_bf16 v[72:75], v[196:199], v[184:187], v[72:75]
	v_mfma_f32_16x16x32_bf16 v[64:67], v[208:211], v[184:187], v[64:67]
	v_mfma_f32_16x16x32_bf16 v[120:123], v[204:207], v[164:167], v[120:123]
	v_mfma_f32_16x16x32_bf16 v[112:115], v[214:217], v[164:167], v[112:115]
	v_mfma_f32_16x16x32_bf16 v[104:107], v[204:207], v[172:175], v[104:107]
	v_mfma_f32_16x16x32_bf16 v[96:99], v[214:217], v[172:175], v[96:99]
	v_mfma_f32_16x16x32_bf16 v[88:91], v[204:207], v[180:183], v[88:91]
	v_mfma_f32_16x16x32_bf16 v[80:83], v[214:217], v[180:183], v[80:83]
	v_mfma_f32_16x16x32_bf16 v[72:75], v[204:207], v[188:191], v[72:75]
	v_mfma_f32_16x16x32_bf16 v[64:67], v[214:217], v[188:191], v[64:67]
	s_barrier
	ds_read_b128 v[160:163], v143 offset:49152
	ds_read_b128 v[164:167], v143 offset:50176
	ds_read_b128 v[168:171], v143 offset:51200
	ds_read_b128 v[172:175], v143 offset:52224
	ds_read_b128 v[176:179], v143 offset:53248
	ds_read_b128 v[180:183], v143 offset:54272
	ds_read_b128 v[184:187], v143 offset:55296
	ds_read_b128 v[188:191], v143 offset:56320
	global_load_lds_dwordx4 v132, s[48:49]
	s_mov_b32 m0, s34
	s_nop 0
	global_load_lds_dwordx4 v130, s[48:49]
	s_barrier
	s_waitcnt lgkmcnt(0)
	v_mfma_f32_16x16x32_bf16 v[60:63], v[144:147], v[160:163], v[60:63]
	v_mfma_f32_16x16x32_bf16 v[52:55], v[152:155], v[160:163], v[52:55]
	v_mfma_f32_16x16x32_bf16 v[44:47], v[144:147], v[168:171], v[44:47]
	v_mfma_f32_16x16x32_bf16 v[36:39], v[152:155], v[168:171], v[36:39]
	s_add_u32 s16, s16, 0x80080
	s_addc_u32 s17, s17, 0
	v_mfma_f32_16x16x32_bf16 v[28:31], v[144:147], v[176:179], v[28:31]
	s_add_i32 s18, s18, s26
	s_mov_b32 m0, s18
	v_mfma_f32_16x16x32_bf16 v[20:23], v[152:155], v[176:179], v[20:23]
	v_mfma_f32_16x16x32_bf16 v[12:15], v[144:147], v[184:187], v[12:15]
	v_mfma_f32_16x16x32_bf16 v[4:7], v[152:155], v[184:187], v[4:7]
	v_mfma_f32_16x16x32_bf16 v[60:63], v[148:151], v[164:167], v[60:63]
	v_mfma_f32_16x16x32_bf16 v[52:55], v[156:159], v[164:167], v[52:55]
	v_mfma_f32_16x16x32_bf16 v[44:47], v[148:151], v[172:175], v[44:47]
	v_mfma_f32_16x16x32_bf16 v[36:39], v[156:159], v[172:175], v[36:39]
	v_mfma_f32_16x16x32_bf16 v[28:31], v[148:151], v[180:183], v[28:31]
	v_mfma_f32_16x16x32_bf16 v[20:23], v[156:159], v[180:183], v[20:23]
	v_mfma_f32_16x16x32_bf16 v[12:15], v[148:151], v[188:191], v[12:15]
	v_mfma_f32_16x16x32_bf16 v[4:7], v[156:159], v[188:191], v[4:7]
	s_barrier
	global_load_lds_dwordx4 v192, s[16:17]
	s_add_i32 m0, s18, 0x2000
	s_nop 0
	global_load_lds_dwordx4 v128, s[16:17]
	s_waitcnt vmcnt(6)
	s_barrier
	v_mfma_f32_16x16x32_bf16 v[56:59], v[196:199], v[160:163], v[56:59]
	v_mfma_f32_16x16x32_bf16 v[48:51], v[208:211], v[160:163], v[48:51]
	v_mfma_f32_16x16x32_bf16 v[40:43], v[196:199], v[168:171], v[40:43]
	v_mfma_f32_16x16x32_bf16 v[32:35], v[208:211], v[168:171], v[32:35]
	s_add_i32 s40, s40, 2
	v_mfma_f32_16x16x32_bf16 v[24:27], v[196:199], v[176:179], v[24:27]
	s_add_u32 s14, s14, 0x100
	s_addc_u32 s15, s15, 0
	v_mfma_f32_16x16x32_bf16 v[16:19], v[208:211], v[176:179], v[16:19]
	s_add_u32 s38, s38, 0x100
	s_addc_u32 s39, s39, 0
	v_mfma_f32_16x16x32_bf16 v[8:11], v[196:199], v[184:187], v[8:11]
	s_add_u32 s16, s14, 0xfff80080
	s_addc_u32 s17, s15, -1
	v_mfma_f32_16x16x32_bf16 v[0:3], v[208:211], v[184:187], v[0:3]
	s_add_i32 s41, 0, 0x10000
	s_cmp_eq_u32 s40, 28
	v_mfma_f32_16x16x32_bf16 v[56:59], v[204:207], v[164:167], v[56:59]
	s_cselect_b32 s19, s7, s17
	s_cselect_b32 s18, s36, s16
	v_mfma_f32_16x16x32_bf16 v[48:51], v[214:217], v[164:167], v[48:51]
	s_cselect_b32 s17, s5, s39
	s_cselect_b32 s16, s37, s38
	v_mfma_f32_16x16x32_bf16 v[40:43], v[204:207], v[172:175], v[40:43]
	s_add_i32 m0, s13, 0xc000
	v_mfma_f32_16x16x32_bf16 v[32:35], v[214:217], v[172:175], v[32:35]
	v_mfma_f32_16x16x32_bf16 v[24:27], v[204:207], v[180:183], v[24:27]
	v_mfma_f32_16x16x32_bf16 v[16:19], v[214:217], v[180:183], v[16:19]
	v_mfma_f32_16x16x32_bf16 v[8:11], v[204:207], v[188:191], v[8:11]
	v_mfma_f32_16x16x32_bf16 v[0:3], v[214:217], v[188:191], v[0:3]
	s_cmp_gt_u32 s40, 29
	s_cbranch_scc0 .Lrot_217
	s_barrier
	v_mul_f32_e32 v145, 0xbfb8aa3b, v124
	v_exp_f32_e32 v145, v145
	v_lshl_or_b32 v146, s35, 7, v142
	v_lshl_add_u32 v144, s12, 8, v140
	v_ashrrev_i32_e32 v147, 31, v146
	v_add_f32_e32 v145, 1.0, v145
	v_rcp_f32_e32 v145, v145
	v_mov_b64_e32 v[138:139], s[2:3]
	s_movk_i32 s5, 0x2c00
	v_mad_i64_i32 v[148:149], s[14:15], v144, s5, v[138:139]
	v_mul_f32_e32 v124, v124, v145
	v_mul_f32_e32 v120, v124, v120
	v_mul_f32_e32 v124, 0xbfb8aa3b, v125
	v_exp_f32_e32 v124, v124
	s_and_b64 vcc, exec, s[0:1]
	s_mov_b32 s35, s4
	s_mov_b32 s12, s6
	v_add_f32_e32 v124, 1.0, v124
	v_rcp_f32_e32 v124, v124
	s_mov_b64 s[16:17], s[10:11]
	v_mul_f32_e32 v124, v125, v124
	v_mul_f32_e32 v121, v124, v121
	v_mul_f32_e32 v124, 0xbfb8aa3b, v126
	v_exp_f32_e32 v124, v124
	s_nop 0
	v_add_f32_e32 v124, 1.0, v124
	v_rcp_f32_e32 v124, v124
	s_nop 0
	v_mul_f32_e32 v124, v126, v124
	v_mul_f32_e32 v122, v124, v122
	v_mul_f32_e32 v124, 0xbfb8aa3b, v127
	v_exp_f32_e32 v124, v124
	s_nop 0
	v_add_f32_e32 v124, 1.0, v124
	v_rcp_f32_e32 v124, v124
	s_nop 0
	v_mul_f32_e32 v124, v127, v124
	v_mul_f32_e32 v123, v124, v123
	v_mul_f32_e32 v124, 0xbfb8aa3b, v116
	v_exp_f32_e32 v124, v124
	s_nop 0
	v_add_f32_e32 v124, 1.0, v124
	v_rcp_f32_e32 v124, v124
	s_nop 0
	v_mul_f32_e32 v116, v116, v124
	v_mul_f32_e32 v116, v116, v112
	v_mul_f32_e32 v112, 0xbfb8aa3b, v117
	v_exp_f32_e32 v112, v112
	s_nop 0
	v_add_f32_e32 v112, 1.0, v112
	v_rcp_f32_e32 v112, v112
	s_nop 0
	v_mul_f32_e32 v112, v117, v112
	v_mul_f32_e32 v117, v112, v113
	v_mul_f32_e32 v112, 0xbfb8aa3b, v118
	v_exp_f32_e32 v112, v112
	s_nop 0
	v_add_f32_e32 v112, 1.0, v112
	v_rcp_f32_e32 v112, v112
	s_nop 0
	v_mul_f32_e32 v112, v118, v112
	v_mul_f32_e32 v124, v112, v114
	v_mul_f32_e32 v112, 0xbfb8aa3b, v119
	v_exp_f32_e32 v112, v112
	v_cvt_pk_bf16_f32 v114, v120, v121
	s_nop 0
	v_add_f32_e32 v112, 1.0, v112
	v_rcp_f32_e32 v112, v112
	s_nop 0
	v_mul_f32_e32 v112, v119, v112
	v_mul_f32_e32 v125, v112, v115
	v_lshlrev_b64 v[112:113], 1, v[146:147]
	v_lshl_add_u64 v[118:119], v[148:149], 0, v[112:113]
	v_cvt_pk_bf16_f32 v115, v122, v123
	v_cvt_pk_bf16_f32 v116, v116, v117
	v_cvt_pk_bf16_f32 v117, v124, v125
	global_store_dwordx4 v[118:119], v[114:117], off
	s_nop 1
	v_mul_f32_e32 v116, 0xbfb8aa3b, v108
	v_exp_f32_e32 v116, v116
	v_or_b32_e32 v114, 16, v144
	v_mad_i64_i32 v[114:115], s[14:15], v114, s5, v[138:139]
	v_add_f32_e32 v116, 1.0, v116
	v_rcp_f32_e32 v116, v116
	s_nop 0
	v_mul_f32_e32 v108, v108, v116
	v_mul_f32_e32 v104, v108, v104
	v_mul_f32_e32 v108, 0xbfb8aa3b, v109
	v_exp_f32_e32 v108, v108
	s_nop 0
	v_add_f32_e32 v108, 1.0, v108
	v_rcp_f32_e32 v108, v108
	s_nop 0
	v_mul_f32_e32 v108, v109, v108
	v_mul_f32_e32 v105, v108, v105
	v_mul_f32_e32 v108, 0xbfb8aa3b, v110
	v_exp_f32_e32 v108, v108
	s_nop 0
	v_add_f32_e32 v108, 1.0, v108
	v_rcp_f32_e32 v108, v108
	s_nop 0
	v_mul_f32_e32 v108, v110, v108
	v_mul_f32_e32 v106, v108, v106
	v_mul_f32_e32 v108, 0xbfb8aa3b, v111
	v_exp_f32_e32 v108, v108
	s_nop 0
	v_add_f32_e32 v108, 1.0, v108
	v_rcp_f32_e32 v108, v108
	s_nop 0
	v_mul_f32_e32 v108, v111, v108
	v_mul_f32_e32 v107, v108, v107
	v_mul_f32_e32 v108, 0xbfb8aa3b, v100
	v_exp_f32_e32 v108, v108
	s_nop 0
	v_add_f32_e32 v108, 1.0, v108
	v_rcp_f32_e32 v108, v108
	s_nop 0
	v_mul_f32_e32 v100, v100, v108
	v_mul_f32_e32 v108, v100, v96
	v_mul_f32_e32 v96, 0xbfb8aa3b, v101
	v_exp_f32_e32 v96, v96
	s_nop 0
	v_add_f32_e32 v96, 1.0, v96
	v_rcp_f32_e32 v96, v96
	s_nop 0
	v_mul_f32_e32 v96, v101, v96
	v_mul_f32_e32 v109, v96, v97
	v_mul_f32_e32 v96, 0xbfb8aa3b, v102
	v_exp_f32_e32 v96, v96
	v_lshl_add_u64 v[100:101], v[114:115], 0, v[112:113]
	v_add_f32_e32 v96, 1.0, v96
	v_rcp_f32_e32 v96, v96
	s_nop 0
	v_mul_f32_e32 v96, v102, v96
	v_mul_f32_e32 v102, v96, v98
	v_mul_f32_e32 v96, 0xbfb8aa3b, v103
	v_exp_f32_e32 v96, v96
	s_nop 0
	v_add_f32_e32 v96, 1.0, v96
	v_rcp_f32_e32 v96, v96
	s_nop 0
	v_mul_f32_e32 v96, v103, v96
	v_mul_f32_e32 v99, v96, v99
	v_cvt_pk_bf16_f32 v96, v104, v105
	v_cvt_pk_bf16_f32 v97, v106, v107
	v_cvt_pk_bf16_f32 v98, v108, v109
	v_cvt_pk_bf16_f32 v99, v102, v99
	global_store_dwordx4 v[100:101], v[96:99], off
	s_nop 1
	v_mul_f32_e32 v98, 0xbfb8aa3b, v92
	v_exp_f32_e32 v98, v98
	v_or_b32_e32 v96, 32, v144
	v_mad_i64_i32 v[96:97], s[14:15], v96, s5, v[138:139]
	v_add_f32_e32 v98, 1.0, v98
	v_rcp_f32_e32 v98, v98
	s_nop 0
	v_mul_f32_e32 v92, v92, v98
	v_mul_f32_e32 v88, v92, v88
	v_mul_f32_e32 v92, 0xbfb8aa3b, v93
	v_exp_f32_e32 v92, v92
	s_nop 0
	v_add_f32_e32 v92, 1.0, v92
	v_rcp_f32_e32 v92, v92
	s_nop 0
	v_mul_f32_e32 v92, v93, v92
	v_mul_f32_e32 v89, v92, v89
	v_mul_f32_e32 v92, 0xbfb8aa3b, v94
	v_exp_f32_e32 v92, v92
	s_nop 0
	v_add_f32_e32 v92, 1.0, v92
	v_rcp_f32_e32 v92, v92
	s_nop 0
	v_mul_f32_e32 v92, v94, v92
	v_mul_f32_e32 v90, v92, v90
	v_mul_f32_e32 v92, 0xbfb8aa3b, v95
	v_exp_f32_e32 v92, v92
	s_nop 0
	v_add_f32_e32 v92, 1.0, v92
	v_rcp_f32_e32 v92, v92
	s_nop 0
	v_mul_f32_e32 v92, v95, v92
	v_mul_f32_e32 v91, v92, v91
	v_mul_f32_e32 v92, 0xbfb8aa3b, v84
	v_exp_f32_e32 v92, v92
	s_nop 0
	v_add_f32_e32 v92, 1.0, v92
	v_rcp_f32_e32 v92, v92
	s_nop 0
	v_mul_f32_e32 v84, v84, v92
	v_mul_f32_e32 v92, v84, v80
	v_mul_f32_e32 v80, 0xbfb8aa3b, v85
	v_exp_f32_e32 v80, v80
	s_nop 0
	v_add_f32_e32 v80, 1.0, v80
	v_rcp_f32_e32 v80, v80
	s_nop 0
	v_mul_f32_e32 v80, v85, v80
	v_mul_f32_e32 v93, v80, v81
	v_mul_f32_e32 v80, 0xbfb8aa3b, v86
	v_exp_f32_e32 v80, v80
	v_lshl_add_u64 v[84:85], v[96:97], 0, v[112:113]
	v_add_f32_e32 v80, 1.0, v80
	v_rcp_f32_e32 v80, v80
	s_nop 0
	v_mul_f32_e32 v80, v86, v80
	v_mul_f32_e32 v86, v80, v82
	v_mul_f32_e32 v80, 0xbfb8aa3b, v87
	v_exp_f32_e32 v80, v80
	s_nop 0
	v_add_f32_e32 v80, 1.0, v80
	v_rcp_f32_e32 v80, v80
	s_nop 0
	v_mul_f32_e32 v80, v87, v80
	v_mul_f32_e32 v83, v80, v83
	v_cvt_pk_bf16_f32 v80, v88, v89
	v_cvt_pk_bf16_f32 v81, v90, v91
	v_cvt_pk_bf16_f32 v82, v92, v93
	v_cvt_pk_bf16_f32 v83, v86, v83
	global_store_dwordx4 v[84:85], v[80:83], off
	s_nop 1
	v_mul_f32_e32 v82, 0xbfb8aa3b, v76
	v_exp_f32_e32 v82, v82
	v_or_b32_e32 v80, 48, v144
	v_mad_i64_i32 v[80:81], s[14:15], v80, s5, v[138:139]
	v_add_f32_e32 v82, 1.0, v82
	v_rcp_f32_e32 v82, v82
	s_nop 0
	v_mul_f32_e32 v76, v76, v82
	v_mul_f32_e32 v72, v76, v72
	v_mul_f32_e32 v76, 0xbfb8aa3b, v77
	v_exp_f32_e32 v76, v76
	s_nop 0
	v_add_f32_e32 v76, 1.0, v76
	v_rcp_f32_e32 v76, v76
	s_nop 0
	v_mul_f32_e32 v76, v77, v76
	v_mul_f32_e32 v73, v76, v73
	v_mul_f32_e32 v76, 0xbfb8aa3b, v78
	v_exp_f32_e32 v76, v76
	s_nop 0
	v_add_f32_e32 v76, 1.0, v76
	v_rcp_f32_e32 v76, v76
	s_nop 0
	v_mul_f32_e32 v76, v78, v76
	v_mul_f32_e32 v74, v76, v74
	v_mul_f32_e32 v76, 0xbfb8aa3b, v79
	v_exp_f32_e32 v76, v76
	s_nop 0
	v_add_f32_e32 v76, 1.0, v76
	v_rcp_f32_e32 v76, v76
	s_nop 0
	v_mul_f32_e32 v76, v79, v76
	v_mul_f32_e32 v75, v76, v75
	v_mul_f32_e32 v76, 0xbfb8aa3b, v68
	v_exp_f32_e32 v76, v76
	s_nop 0
	v_add_f32_e32 v76, 1.0, v76
	v_rcp_f32_e32 v76, v76
	s_nop 0
	v_mul_f32_e32 v68, v68, v76
	v_mul_f32_e32 v76, v68, v64
	v_mul_f32_e32 v64, 0xbfb8aa3b, v69
	v_exp_f32_e32 v64, v64
	s_nop 0
	v_add_f32_e32 v64, 1.0, v64
	v_rcp_f32_e32 v64, v64
	s_nop 0
	v_mul_f32_e32 v64, v69, v64
	v_mul_f32_e32 v77, v64, v65
	v_mul_f32_e32 v64, 0xbfb8aa3b, v70
	v_exp_f32_e32 v64, v64
	v_lshl_add_u64 v[68:69], v[80:81], 0, v[112:113]
	v_add_f32_e32 v64, 1.0, v64
	v_rcp_f32_e32 v64, v64
	s_nop 0
	v_mul_f32_e32 v64, v70, v64
	v_mul_f32_e32 v70, v64, v66
	v_mul_f32_e32 v64, 0xbfb8aa3b, v71
	v_exp_f32_e32 v64, v64
	s_nop 0
	v_add_f32_e32 v64, 1.0, v64
	v_rcp_f32_e32 v64, v64
	s_nop 0
	v_mul_f32_e32 v64, v71, v64
	v_mul_f32_e32 v67, v64, v67
	v_cvt_pk_bf16_f32 v64, v72, v73
	v_cvt_pk_bf16_f32 v65, v74, v75
	v_cvt_pk_bf16_f32 v66, v76, v77
	v_cvt_pk_bf16_f32 v67, v70, v67
	global_store_dwordx4 v[68:69], v[64:67], off
	s_nop 1
	v_mul_f32_e32 v66, 0xbfb8aa3b, v60
	v_exp_f32_e32 v66, v66
	v_add_u32_e32 v64, 0x80, v144
	v_mad_i64_i32 v[64:65], s[14:15], v64, s5, v[138:139]
	v_add_f32_e32 v66, 1.0, v66
	v_rcp_f32_e32 v66, v66
	s_nop 0
	v_mul_f32_e32 v60, v60, v66
	v_mul_f32_e32 v56, v60, v56
	v_mul_f32_e32 v60, 0xbfb8aa3b, v61
	v_exp_f32_e32 v60, v60
	s_nop 0
	v_add_f32_e32 v60, 1.0, v60
	v_rcp_f32_e32 v60, v60
	s_nop 0
	v_mul_f32_e32 v60, v61, v60
	v_mul_f32_e32 v57, v60, v57
	v_mul_f32_e32 v60, 0xbfb8aa3b, v62
	v_exp_f32_e32 v60, v60
	s_nop 0
	v_add_f32_e32 v60, 1.0, v60
	v_rcp_f32_e32 v60, v60
	s_nop 0
	v_mul_f32_e32 v60, v62, v60
	v_mul_f32_e32 v58, v60, v58
	v_mul_f32_e32 v60, 0xbfb8aa3b, v63
	v_exp_f32_e32 v60, v60
	s_nop 0
	v_add_f32_e32 v60, 1.0, v60
	v_rcp_f32_e32 v60, v60
	s_nop 0
	v_mul_f32_e32 v60, v63, v60
	v_mul_f32_e32 v59, v60, v59
	v_mul_f32_e32 v60, 0xbfb8aa3b, v52
	v_exp_f32_e32 v60, v60
	s_nop 0
	v_add_f32_e32 v60, 1.0, v60
	v_rcp_f32_e32 v60, v60
	s_nop 0
	v_mul_f32_e32 v52, v52, v60
	v_mul_f32_e32 v60, v52, v48
	v_mul_f32_e32 v48, 0xbfb8aa3b, v53
	v_exp_f32_e32 v48, v48
	s_nop 0
	v_add_f32_e32 v48, 1.0, v48
	v_rcp_f32_e32 v48, v48
	s_nop 0
	v_mul_f32_e32 v48, v53, v48
	v_mul_f32_e32 v61, v48, v49
	v_mul_f32_e32 v48, 0xbfb8aa3b, v54
	v_exp_f32_e32 v48, v48
	v_lshl_add_u64 v[52:53], v[64:65], 0, v[112:113]
	v_add_f32_e32 v48, 1.0, v48
	v_rcp_f32_e32 v48, v48
	s_nop 0
	v_mul_f32_e32 v48, v54, v48
	v_mul_f32_e32 v54, v48, v50
	v_mul_f32_e32 v48, 0xbfb8aa3b, v55
	v_exp_f32_e32 v48, v48
	s_nop 0
	v_add_f32_e32 v48, 1.0, v48
	v_rcp_f32_e32 v48, v48
	s_nop 0
	v_mul_f32_e32 v48, v55, v48
	v_mul_f32_e32 v51, v48, v51
	v_cvt_pk_bf16_f32 v48, v56, v57
	v_cvt_pk_bf16_f32 v49, v58, v59
	v_cvt_pk_bf16_f32 v50, v60, v61
	v_cvt_pk_bf16_f32 v51, v54, v51
	global_store_dwordx4 v[52:53], v[48:51], off
	s_nop 1
	v_mul_f32_e32 v50, 0xbfb8aa3b, v44
	v_exp_f32_e32 v50, v50
	v_add_u32_e32 v48, 0x90, v144
	v_mad_i64_i32 v[48:49], s[14:15], v48, s5, v[138:139]
	v_add_f32_e32 v50, 1.0, v50
	v_rcp_f32_e32 v50, v50
	s_nop 0
	v_mul_f32_e32 v44, v44, v50
	v_mul_f32_e32 v40, v44, v40
	v_mul_f32_e32 v44, 0xbfb8aa3b, v45
	v_exp_f32_e32 v44, v44
	s_nop 0
	v_add_f32_e32 v44, 1.0, v44
	v_rcp_f32_e32 v44, v44
	s_nop 0
	v_mul_f32_e32 v44, v45, v44
	v_mul_f32_e32 v41, v44, v41
	v_mul_f32_e32 v44, 0xbfb8aa3b, v46
	v_exp_f32_e32 v44, v44
	s_nop 0
	v_add_f32_e32 v44, 1.0, v44
	v_rcp_f32_e32 v44, v44
	s_nop 0
	v_mul_f32_e32 v44, v46, v44
	v_mul_f32_e32 v42, v44, v42
	v_mul_f32_e32 v44, 0xbfb8aa3b, v47
	v_exp_f32_e32 v44, v44
	s_nop 0
	v_add_f32_e32 v44, 1.0, v44
	v_rcp_f32_e32 v44, v44
	s_nop 0
	v_mul_f32_e32 v44, v47, v44
	v_mul_f32_e32 v43, v44, v43
	v_mul_f32_e32 v44, 0xbfb8aa3b, v36
	v_exp_f32_e32 v44, v44
	s_nop 0
	v_add_f32_e32 v44, 1.0, v44
	v_rcp_f32_e32 v44, v44
	s_nop 0
	v_mul_f32_e32 v36, v36, v44
	v_mul_f32_e32 v44, v36, v32
	v_mul_f32_e32 v32, 0xbfb8aa3b, v37
	v_exp_f32_e32 v32, v32
	s_nop 0
	v_add_f32_e32 v32, 1.0, v32
	v_rcp_f32_e32 v32, v32
	s_nop 0
	v_mul_f32_e32 v32, v37, v32
	v_mul_f32_e32 v45, v32, v33
	v_mul_f32_e32 v32, 0xbfb8aa3b, v38
	v_exp_f32_e32 v32, v32
	v_lshl_add_u64 v[36:37], v[48:49], 0, v[112:113]
	v_add_f32_e32 v32, 1.0, v32
	v_rcp_f32_e32 v32, v32
	s_nop 0
	v_mul_f32_e32 v32, v38, v32
	v_mul_f32_e32 v38, v32, v34
	v_mul_f32_e32 v32, 0xbfb8aa3b, v39
	v_exp_f32_e32 v32, v32
	s_nop 0
	v_add_f32_e32 v32, 1.0, v32
	v_rcp_f32_e32 v32, v32
	s_nop 0
	v_mul_f32_e32 v32, v39, v32
	v_mul_f32_e32 v35, v32, v35
	v_cvt_pk_bf16_f32 v32, v40, v41
	v_cvt_pk_bf16_f32 v33, v42, v43
	v_cvt_pk_bf16_f32 v34, v44, v45
	v_cvt_pk_bf16_f32 v35, v38, v35
	global_store_dwordx4 v[36:37], v[32:35], off
	s_nop 1
	v_mul_f32_e32 v34, 0xbfb8aa3b, v28
	v_exp_f32_e32 v34, v34
	v_add_u32_e32 v32, 0xa0, v144
	v_mad_i64_i32 v[32:33], s[14:15], v32, s5, v[138:139]
	v_add_f32_e32 v34, 1.0, v34
	v_rcp_f32_e32 v34, v34
	s_nop 0
	v_mul_f32_e32 v28, v28, v34
	v_mul_f32_e32 v24, v28, v24
	v_mul_f32_e32 v28, 0xbfb8aa3b, v29
	v_exp_f32_e32 v28, v28
	s_nop 0
	v_add_f32_e32 v28, 1.0, v28
	v_rcp_f32_e32 v28, v28
	s_nop 0
	v_mul_f32_e32 v28, v29, v28
	v_mul_f32_e32 v25, v28, v25
	v_mul_f32_e32 v28, 0xbfb8aa3b, v30
	v_exp_f32_e32 v28, v28
	s_nop 0
	v_add_f32_e32 v28, 1.0, v28
	v_rcp_f32_e32 v28, v28
	s_nop 0
	v_mul_f32_e32 v28, v30, v28
	v_mul_f32_e32 v26, v28, v26
	v_mul_f32_e32 v28, 0xbfb8aa3b, v31
	v_exp_f32_e32 v28, v28
	s_nop 0
	v_add_f32_e32 v28, 1.0, v28
	v_rcp_f32_e32 v28, v28
	s_nop 0
	v_mul_f32_e32 v28, v31, v28
	v_mul_f32_e32 v27, v28, v27
	v_mul_f32_e32 v28, 0xbfb8aa3b, v20
	v_exp_f32_e32 v28, v28
	s_nop 0
	v_add_f32_e32 v28, 1.0, v28
	v_rcp_f32_e32 v28, v28
	s_nop 0
	v_mul_f32_e32 v20, v20, v28
	v_mul_f32_e32 v28, v20, v16
	v_mul_f32_e32 v16, 0xbfb8aa3b, v21
	v_exp_f32_e32 v16, v16
	s_nop 0
	v_add_f32_e32 v16, 1.0, v16
	v_rcp_f32_e32 v16, v16
	s_nop 0
	v_mul_f32_e32 v16, v21, v16
	v_mul_f32_e32 v29, v16, v17
	v_mul_f32_e32 v16, 0xbfb8aa3b, v22
	v_exp_f32_e32 v16, v16
	v_lshl_add_u64 v[20:21], v[32:33], 0, v[112:113]
	v_add_f32_e32 v16, 1.0, v16
	v_rcp_f32_e32 v16, v16
	s_nop 0
	v_mul_f32_e32 v16, v22, v16
	v_mul_f32_e32 v22, v16, v18
	v_mul_f32_e32 v16, 0xbfb8aa3b, v23
	v_exp_f32_e32 v16, v16
	s_nop 0
	v_add_f32_e32 v16, 1.0, v16
	v_rcp_f32_e32 v16, v16
	s_nop 0
	v_mul_f32_e32 v16, v23, v16
	v_mul_f32_e32 v19, v16, v19
	v_cvt_pk_bf16_f32 v16, v24, v25
	v_cvt_pk_bf16_f32 v17, v26, v27
	v_cvt_pk_bf16_f32 v18, v28, v29
	v_cvt_pk_bf16_f32 v19, v22, v19
	global_store_dwordx4 v[20:21], v[16:19], off
	s_nop 1
	v_mul_f32_e32 v18, 0xbfb8aa3b, v12
	v_exp_f32_e32 v18, v18
	v_add_u32_e32 v16, 0xb0, v144
	v_mad_i64_i32 v[16:17], s[14:15], v16, s5, v[138:139]
	v_add_f32_e32 v18, 1.0, v18
	v_rcp_f32_e32 v18, v18
	s_mov_b64 s[14:15], s[8:9]
	v_mul_f32_e32 v12, v12, v18
	v_mul_f32_e32 v8, v12, v8
	v_mul_f32_e32 v12, 0xbfb8aa3b, v13
	v_exp_f32_e32 v12, v12
	s_nop 0
	v_add_f32_e32 v12, 1.0, v12
	v_rcp_f32_e32 v12, v12
	s_nop 0
	v_mul_f32_e32 v12, v13, v12
	v_mul_f32_e32 v9, v12, v9
	v_mul_f32_e32 v12, 0xbfb8aa3b, v14
	v_exp_f32_e32 v12, v12
	s_nop 0
	v_add_f32_e32 v12, 1.0, v12
	v_rcp_f32_e32 v12, v12
	s_nop 0
	v_mul_f32_e32 v12, v14, v12
	v_mul_f32_e32 v10, v12, v10
	v_mul_f32_e32 v12, 0xbfb8aa3b, v15
	v_exp_f32_e32 v12, v12
	s_nop 0
	v_add_f32_e32 v12, 1.0, v12
	v_rcp_f32_e32 v12, v12
	s_nop 0
	v_mul_f32_e32 v12, v15, v12
	v_mul_f32_e32 v11, v12, v11
	v_mul_f32_e32 v12, 0xbfb8aa3b, v4
	v_exp_f32_e32 v12, v12
	s_nop 0
	v_add_f32_e32 v12, 1.0, v12
	v_rcp_f32_e32 v12, v12
	s_nop 0
	v_mul_f32_e32 v4, v4, v12
	v_mul_f32_e32 v12, v4, v0
	v_mul_f32_e32 v0, 0xbfb8aa3b, v5
	v_exp_f32_e32 v0, v0
	s_nop 0
	v_add_f32_e32 v0, 1.0, v0
	v_rcp_f32_e32 v0, v0
	s_nop 0
	v_mul_f32_e32 v0, v5, v0
	v_mul_f32_e32 v13, v0, v1
	v_mul_f32_e32 v0, 0xbfb8aa3b, v6
	v_exp_f32_e32 v0, v0
	v_lshl_add_u64 v[4:5], v[16:17], 0, v[112:113]
	v_add_f32_e32 v0, 1.0, v0
	v_rcp_f32_e32 v0, v0
	s_nop 0
	v_mul_f32_e32 v0, v6, v0
	v_mul_f32_e32 v6, v0, v2
	v_mul_f32_e32 v0, 0xbfb8aa3b, v7
	v_exp_f32_e32 v0, v0
	s_nop 0
	v_add_f32_e32 v0, 1.0, v0
	v_rcp_f32_e32 v0, v0
	s_nop 0
	v_mul_f32_e32 v0, v7, v0
	v_mul_f32_e32 v3, v0, v3
	v_cvt_pk_bf16_f32 v0, v8, v9
	v_cvt_pk_bf16_f32 v1, v10, v11
	v_cvt_pk_bf16_f32 v2, v12, v13
	v_cvt_pk_bf16_f32 v3, v6, v3
	global_store_dwordx4 v[4:5], v[0:3], off
	s_cbranch_vccz .LBB0_214
	s_waitcnt vmcnt(0)
	v_readlane_b32 s34, v254, 18
	s_cmpk_gt_u32 s21, 0xff
	v_readlane_b32 s35, v254, 19
	v_readlane_b32 s31, v254, 20
	s_cbranch_scc1 .LBB0_221
	s_barrier

.LBB0_246:
	s_add_i32 s44, s12, 2
	s_add_u32 s14, s10, 0x80
	s_addc_u32 s13, s11, 0
	s_add_i32 s45, 0, 0x10000
	ds_read_b128 v[120:123], v218 offset:0
	ds_read_b128 v[124:127], v218 offset:1024
	ds_read_b128 v[128:131], v218 offset:2048
	ds_read_b128 v[132:135], v218 offset:3072
	s_cmp_eq_u32 s36, s12
	s_cselect_b32 s12, s4, s14
	s_cselect_b32 s13, s5, s13
	s_cselect_b32 s15, s7, s43
	s_cselect_b32 s14, s6, s42
	s_add_i32 m0, s26, 0xc000
	ds_read_b128 v[144:147], v205
	ds_read_b128 v[148:151], v205 offset:1024
	ds_read_b128 v[152:155], v205 offset:2048
	ds_read_b128 v[156:159], v205 offset:3072
	ds_read_b128 v[160:163], v205 offset:4096
	ds_read_b128 v[164:167], v205 offset:5120
	ds_read_b128 v[178:181], v205 offset:6144
	ds_read_b128 v[182:185], v205 offset:7168
	global_load_lds_dwordx4 v174, s[10:11]
	s_add_i32 m0, s26, 0xe000
	s_nop 0
	global_load_lds_dwordx4 v176, s[10:11]
	s_waitcnt lgkmcnt(8)
	s_barrier
	s_waitcnt lgkmcnt(0)
	v_mfma_f32_16x16x32_bf16 v[140:143], v[120:123], v[144:147], v[140:143]
	v_mfma_f32_16x16x32_bf16 v[136:139], v[128:131], v[144:147], v[136:139]
	v_mfma_f32_16x16x32_bf16 v[108:111], v[120:123], v[152:155], v[108:111]
	v_mfma_f32_16x16x32_bf16 v[104:107], v[128:131], v[152:155], v[104:107]
	s_add_i32 s46, 0, 0x14000
	s_add_i32 s45, s45, s25
	v_mfma_f32_16x16x32_bf16 v[92:95], v[120:123], v[160:163], v[92:95]
	s_add_u32 s68, s14, 0x80
	s_addc_u32 s69, s15, 0
	v_mfma_f32_16x16x32_bf16 v[88:91], v[128:131], v[160:163], v[88:91]
	s_mov_b32 m0, s45
	v_mfma_f32_16x16x32_bf16 v[76:79], v[120:123], v[178:181], v[76:79]
	v_mfma_f32_16x16x32_bf16 v[72:75], v[128:131], v[178:181], v[72:75]
	v_mfma_f32_16x16x32_bf16 v[140:143], v[124:127], v[148:151], v[140:143]
	v_mfma_f32_16x16x32_bf16 v[136:139], v[132:135], v[148:151], v[136:139]
	v_mfma_f32_16x16x32_bf16 v[108:111], v[124:127], v[156:159], v[108:111]
	v_mfma_f32_16x16x32_bf16 v[104:107], v[132:135], v[156:159], v[104:107]
	v_mfma_f32_16x16x32_bf16 v[92:95], v[124:127], v[164:167], v[92:95]
	v_mfma_f32_16x16x32_bf16 v[88:91], v[132:135], v[164:167], v[88:91]
	v_mfma_f32_16x16x32_bf16 v[76:79], v[124:127], v[182:185], v[76:79]
	v_mfma_f32_16x16x32_bf16 v[72:75], v[132:135], v[182:185], v[72:75]
	s_barrier
	ds_read_b128 v[186:189], v218 offset:16384
	ds_read_b128 v[196:199], v218 offset:17408
	ds_read_b128 v[206:209], v218 offset:18432
	ds_read_b128 v[214:217], v218 offset:19456
	global_load_lds_dwordx4 v192, s[14:15]
	s_add_i32 m0, s45, 0x2000
	s_nop 0
	global_load_lds_dwordx4 v172, s[14:15]
	s_barrier
	s_waitcnt lgkmcnt(0)
	v_mfma_f32_16x16x32_bf16 v[116:119], v[186:189], v[144:147], v[116:119]
	v_mfma_f32_16x16x32_bf16 v[112:115], v[206:209], v[144:147], v[112:115]
	v_mfma_f32_16x16x32_bf16 v[100:103], v[186:189], v[152:155], v[100:103]
	v_mfma_f32_16x16x32_bf16 v[96:99], v[206:209], v[152:155], v[96:99]
	s_mov_b32 m0, s26
	v_mfma_f32_16x16x32_bf16 v[84:87], v[186:189], v[160:163], v[84:87]
	s_add_u32 s70, s12, 0x80
	s_addc_u32 s71, s13, 0
	v_mfma_f32_16x16x32_bf16 v[80:83], v[206:209], v[160:163], v[80:83]
	v_mfma_f32_16x16x32_bf16 v[68:71], v[186:189], v[178:181], v[68:71]
	v_mfma_f32_16x16x32_bf16 v[64:67], v[206:209], v[178:181], v[64:67]
	v_mfma_f32_16x16x32_bf16 v[116:119], v[196:199], v[148:151], v[116:119]
	v_mfma_f32_16x16x32_bf16 v[112:115], v[214:217], v[148:151], v[112:115]
	v_mfma_f32_16x16x32_bf16 v[100:103], v[196:199], v[156:159], v[100:103]
	v_mfma_f32_16x16x32_bf16 v[96:99], v[214:217], v[156:159], v[96:99]
	v_mfma_f32_16x16x32_bf16 v[84:87], v[196:199], v[164:167], v[84:87]
	v_mfma_f32_16x16x32_bf16 v[80:83], v[214:217], v[164:167], v[80:83]
	v_mfma_f32_16x16x32_bf16 v[68:71], v[196:199], v[182:185], v[68:71]
	v_mfma_f32_16x16x32_bf16 v[64:67], v[214:217], v[182:185], v[64:67]
	s_barrier
	ds_read_b128 v[144:147], v205 offset:16384
	ds_read_b128 v[148:151], v205 offset:17408
	ds_read_b128 v[152:155], v205 offset:18432
	ds_read_b128 v[156:159], v205 offset:19456
	ds_read_b128 v[160:163], v205 offset:20480
	ds_read_b128 v[164:167], v205 offset:21504
	ds_read_b128 v[178:181], v205 offset:22528
	ds_read_b128 v[182:185], v205 offset:23552
	global_load_lds_dwordx4 v168, s[12:13]
	s_mov_b32 m0, s27
	s_nop 0
	global_load_lds_dwordx4 v170, s[12:13]
	s_barrier
	s_waitcnt lgkmcnt(0)
	v_mfma_f32_16x16x32_bf16 v[60:63], v[120:123], v[144:147], v[60:63]
	v_mfma_f32_16x16x32_bf16 v[56:59], v[128:131], v[144:147], v[56:59]
	v_mfma_f32_16x16x32_bf16 v[44:47], v[120:123], v[152:155], v[44:47]
	v_mfma_f32_16x16x32_bf16 v[40:43], v[128:131], v[152:155], v[40:43]
	s_add_u32 s14, s14, s52
	s_addc_u32 s15, s15, 0
	v_mfma_f32_16x16x32_bf16 v[28:31], v[120:123], v[160:163], v[28:31]
	s_add_i32 s45, s46, s25
	s_mov_b32 m0, s45
	v_mfma_f32_16x16x32_bf16 v[24:27], v[128:131], v[160:163], v[24:27]
	v_mfma_f32_16x16x32_bf16 v[12:15], v[120:123], v[178:181], v[12:15]
	v_mfma_f32_16x16x32_bf16 v[8:11], v[128:131], v[178:181], v[8:11]
	v_mfma_f32_16x16x32_bf16 v[60:63], v[124:127], v[148:151], v[60:63]
	v_mfma_f32_16x16x32_bf16 v[56:59], v[132:135], v[148:151], v[56:59]
	v_mfma_f32_16x16x32_bf16 v[44:47], v[124:127], v[156:159], v[44:47]
	v_mfma_f32_16x16x32_bf16 v[40:43], v[132:135], v[156:159], v[40:43]
	v_mfma_f32_16x16x32_bf16 v[28:31], v[124:127], v[164:167], v[28:31]
	v_mfma_f32_16x16x32_bf16 v[24:27], v[132:135], v[164:167], v[24:27]
	v_mfma_f32_16x16x32_bf16 v[12:15], v[124:127], v[182:185], v[12:15]
	v_mfma_f32_16x16x32_bf16 v[8:11], v[132:135], v[182:185], v[8:11]
	s_barrier
	global_load_lds_dwordx4 v192, s[14:15]
	s_add_i32 m0, s45, 0x2000
	s_nop 0
	global_load_lds_dwordx4 v172, s[14:15]
	s_waitcnt vmcnt(6)
	s_barrier
	v_mfma_f32_16x16x32_bf16 v[52:55], v[186:189], v[144:147], v[52:55]
	v_mfma_f32_16x16x32_bf16 v[48:51], v[206:209], v[144:147], v[48:51]
	v_mfma_f32_16x16x32_bf16 v[36:39], v[186:189], v[152:155], v[36:39]
	v_mfma_f32_16x16x32_bf16 v[32:35], v[206:209], v[152:155], v[32:35]
	s_add_i32 s14, 0, 0x18000
	v_mfma_f32_16x16x32_bf16 v[20:23], v[186:189], v[160:163], v[20:23]
	s_add_u32 s12, s12, s52
	s_addc_u32 s13, s13, 0
	v_mfma_f32_16x16x32_bf16 v[16:19], v[206:209], v[160:163], v[16:19]
	s_mov_b32 m0, s28
	v_mfma_f32_16x16x32_bf16 v[4:7], v[186:189], v[178:181], v[4:7]
	v_mfma_f32_16x16x32_bf16 v[0:3], v[206:209], v[178:181], v[0:3]
	v_mfma_f32_16x16x32_bf16 v[52:55], v[196:199], v[148:151], v[52:55]
	v_mfma_f32_16x16x32_bf16 v[48:51], v[214:217], v[148:151], v[48:51]
	v_mfma_f32_16x16x32_bf16 v[36:39], v[196:199], v[156:159], v[36:39]
	v_mfma_f32_16x16x32_bf16 v[32:35], v[214:217], v[156:159], v[32:35]
	v_mfma_f32_16x16x32_bf16 v[20:23], v[196:199], v[164:167], v[20:23]
	v_mfma_f32_16x16x32_bf16 v[16:19], v[214:217], v[164:167], v[16:19]
	v_mfma_f32_16x16x32_bf16 v[4:7], v[196:199], v[182:185], v[4:7]
	v_mfma_f32_16x16x32_bf16 v[0:3], v[214:217], v[182:185], v[0:3]
	s_barrier
	ds_read_b128 v[120:123], v218 offset:32768
	ds_read_b128 v[124:127], v218 offset:33792
	ds_read_b128 v[128:131], v218 offset:34816
	ds_read_b128 v[132:135], v218 offset:35840
	ds_read_b128 v[144:147], v205 offset:32768
	ds_read_b128 v[148:151], v205 offset:33792
	ds_read_b128 v[152:155], v205 offset:34816
	ds_read_b128 v[156:159], v205 offset:35840
	ds_read_b128 v[160:163], v205 offset:36864
	ds_read_b128 v[164:167], v205 offset:37888
	ds_read_b128 v[178:181], v205 offset:38912
	ds_read_b128 v[182:185], v205 offset:39936
	global_load_lds_dwordx4 v168, s[12:13]
	s_mov_b32 m0, s29
	s_nop 0
	global_load_lds_dwordx4 v170, s[12:13]
	s_waitcnt lgkmcnt(8)
	s_barrier
	s_waitcnt lgkmcnt(0)
	v_mfma_f32_16x16x32_bf16 v[140:143], v[120:123], v[144:147], v[140:143]
	v_mfma_f32_16x16x32_bf16 v[136:139], v[128:131], v[144:147], v[136:139]
	v_mfma_f32_16x16x32_bf16 v[108:111], v[120:123], v[152:155], v[108:111]
	v_mfma_f32_16x16x32_bf16 v[104:107], v[128:131], v[152:155], v[104:107]
	s_add_i32 s12, 0, 0x1c000
	s_add_i32 s13, s14, s25
	v_mfma_f32_16x16x32_bf16 v[92:95], v[120:123], v[160:163], v[92:95]
	s_mov_b32 m0, s13
	v_mfma_f32_16x16x32_bf16 v[88:91], v[128:131], v[160:163], v[88:91]
	v_mfma_f32_16x16x32_bf16 v[76:79], v[120:123], v[178:181], v[76:79]
	v_mfma_f32_16x16x32_bf16 v[72:75], v[128:131], v[178:181], v[72:75]
	v_mfma_f32_16x16x32_bf16 v[140:143], v[124:127], v[148:151], v[140:143]
	v_mfma_f32_16x16x32_bf16 v[136:139], v[132:135], v[148:151], v[136:139]
	v_mfma_f32_16x16x32_bf16 v[108:111], v[124:127], v[156:159], v[108:111]
	v_mfma_f32_16x16x32_bf16 v[104:107], v[132:135], v[156:159], v[104:107]
	v_mfma_f32_16x16x32_bf16 v[92:95], v[124:127], v[164:167], v[92:95]
	v_mfma_f32_16x16x32_bf16 v[88:91], v[132:135], v[164:167], v[88:91]
	v_mfma_f32_16x16x32_bf16 v[76:79], v[124:127], v[182:185], v[76:79]
	v_mfma_f32_16x16x32_bf16 v[72:75], v[132:135], v[182:185], v[72:75]
	s_barrier
	ds_read_b128 v[186:189], v218 offset:49152
	ds_read_b128 v[196:199], v218 offset:50176
	ds_read_b128 v[206:209], v218 offset:51200
	ds_read_b128 v[214:217], v218 offset:52224
	global_load_lds_dwordx4 v192, s[68:69]
	s_add_i32 m0, s13, 0x2000
	s_nop 0
	global_load_lds_dwordx4 v172, s[68:69]
	s_barrier
	s_waitcnt lgkmcnt(0)
	v_mfma_f32_16x16x32_bf16 v[116:119], v[186:189], v[144:147], v[116:119]
	v_mfma_f32_16x16x32_bf16 v[112:115], v[206:209], v[144:147], v[112:115]
	v_mfma_f32_16x16x32_bf16 v[100:103], v[186:189], v[152:155], v[100:103]
	v_mfma_f32_16x16x32_bf16 v[96:99], v[206:209], v[152:155], v[96:99]
	s_mov_b32 m0, s34
	v_mfma_f32_16x16x32_bf16 v[84:87], v[186:189], v[160:163], v[84:87]
	v_mfma_f32_16x16x32_bf16 v[80:83], v[206:209], v[160:163], v[80:83]
	v_mfma_f32_16x16x32_bf16 v[68:71], v[186:189], v[178:181], v[68:71]
	v_mfma_f32_16x16x32_bf16 v[64:67], v[206:209], v[178:181], v[64:67]
	v_mfma_f32_16x16x32_bf16 v[116:119], v[196:199], v[148:151], v[116:119]
	v_mfma_f32_16x16x32_bf16 v[112:115], v[214:217], v[148:151], v[112:115]
	v_mfma_f32_16x16x32_bf16 v[100:103], v[196:199], v[156:159], v[100:103]
	v_mfma_f32_16x16x32_bf16 v[96:99], v[214:217], v[156:159], v[96:99]
	v_mfma_f32_16x16x32_bf16 v[84:87], v[196:199], v[164:167], v[84:87]
	v_mfma_f32_16x16x32_bf16 v[80:83], v[214:217], v[164:167], v[80:83]
	v_mfma_f32_16x16x32_bf16 v[68:71], v[196:199], v[182:185], v[68:71]
	v_mfma_f32_16x16x32_bf16 v[64:67], v[214:217], v[182:185], v[64:67]
	s_barrier
	ds_read_b128 v[144:147], v205 offset:49152
	ds_read_b128 v[148:151], v205 offset:50176
	ds_read_b128 v[152:155], v205 offset:51200
	ds_read_b128 v[156:159], v205 offset:52224
	ds_read_b128 v[160:163], v205 offset:53248
	ds_read_b128 v[164:167], v205 offset:54272
	ds_read_b128 v[178:181], v205 offset:55296
	ds_read_b128 v[182:185], v205 offset:56320
	global_load_lds_dwordx4 v168, s[70:71]
	s_mov_b32 m0, s35
	s_nop 0
	global_load_lds_dwordx4 v170, s[70:71]
	s_barrier
	s_waitcnt lgkmcnt(0)
	v_mfma_f32_16x16x32_bf16 v[60:63], v[120:123], v[144:147], v[60:63]
	v_mfma_f32_16x16x32_bf16 v[56:59], v[128:131], v[144:147], v[56:59]
	v_mfma_f32_16x16x32_bf16 v[44:47], v[120:123], v[152:155], v[44:47]
	v_mfma_f32_16x16x32_bf16 v[40:43], v[128:131], v[152:155], v[40:43]
	s_add_i32 s12, s12, s25
	v_mfma_f32_16x16x32_bf16 v[28:31], v[120:123], v[160:163], v[28:31]
	s_add_u32 s68, s68, s52
	s_addc_u32 s69, s69, 0
	v_mfma_f32_16x16x32_bf16 v[24:27], v[128:131], v[160:163], v[24:27]
	s_mov_b32 m0, s12
	v_mfma_f32_16x16x32_bf16 v[12:15], v[120:123], v[178:181], v[12:15]
	v_mfma_f32_16x16x32_bf16 v[8:11], v[128:131], v[178:181], v[8:11]
	v_mfma_f32_16x16x32_bf16 v[60:63], v[124:127], v[148:151], v[60:63]
	v_mfma_f32_16x16x32_bf16 v[56:59], v[132:135], v[148:151], v[56:59]
	v_mfma_f32_16x16x32_bf16 v[44:47], v[124:127], v[156:159], v[44:47]
	v_mfma_f32_16x16x32_bf16 v[40:43], v[132:135], v[156:159], v[40:43]
	v_mfma_f32_16x16x32_bf16 v[28:31], v[124:127], v[164:167], v[28:31]
	v_mfma_f32_16x16x32_bf16 v[24:27], v[132:135], v[164:167], v[24:27]
	v_mfma_f32_16x16x32_bf16 v[12:15], v[124:127], v[182:185], v[12:15]
	v_mfma_f32_16x16x32_bf16 v[8:11], v[132:135], v[182:185], v[8:11]
	s_barrier
	global_load_lds_dwordx4 v192, s[68:69]
	s_add_i32 m0, s12, 0x2000
	s_nop 0
	global_load_lds_dwordx4 v172, s[68:69]
	s_waitcnt vmcnt(6)
	s_barrier
	v_mfma_f32_16x16x32_bf16 v[52:55], v[186:189], v[144:147], v[52:55]
	v_mfma_f32_16x16x32_bf16 v[48:51], v[206:209], v[144:147], v[48:51]
	v_mfma_f32_16x16x32_bf16 v[36:39], v[186:189], v[152:155], v[36:39]
	v_mfma_f32_16x16x32_bf16 v[32:35], v[206:209], v[152:155], v[32:35]
	s_add_u32 s10, s10, 0x100
	s_addc_u32 s11, s11, 0
	v_mfma_f32_16x16x32_bf16 v[20:23], v[186:189], v[160:163], v[20:23]
	s_add_u32 s42, s42, 0x100
	s_addc_u32 s43, s43, 0
	v_mfma_f32_16x16x32_bf16 v[16:19], v[206:209], v[160:163], v[16:19]
	s_mov_b32 s12, s44
	v_mfma_f32_16x16x32_bf16 v[4:7], v[186:189], v[178:181], v[4:7]
	v_mfma_f32_16x16x32_bf16 v[0:3], v[206:209], v[178:181], v[0:3]
	v_mfma_f32_16x16x32_bf16 v[52:55], v[196:199], v[148:151], v[52:55]
	v_mfma_f32_16x16x32_bf16 v[48:51], v[214:217], v[148:151], v[48:51]
	v_mfma_f32_16x16x32_bf16 v[36:39], v[196:199], v[156:159], v[36:39]
	v_mfma_f32_16x16x32_bf16 v[32:35], v[214:217], v[156:159], v[32:35]
	v_mfma_f32_16x16x32_bf16 v[20:23], v[196:199], v[164:167], v[20:23]
	v_mfma_f32_16x16x32_bf16 v[16:19], v[214:217], v[164:167], v[16:19]
	v_mfma_f32_16x16x32_bf16 v[4:7], v[196:199], v[182:185], v[4:7]
	v_mfma_f32_16x16x32_bf16 v[0:3], v[214:217], v[182:185], v[0:3]
	s_cmp_ge_u32 s44, s33
	s_cbranch_scc0 .Lrot_246
	s_barrier
	v_lshl_or_b32 v144, s41, 8, v204
	s_ashr_i32 s10, s40, 4
	s_mul_hi_i32 s11, s10, 0xc000
	s_mul_i32 s10, s10, 0xc000
	v_ashrrev_i32_e32 v145, 31, v144
	v_lshl_add_u32 v146, s40, 8, v190
	s_add_u32 s10, s30, s10
	v_lshlrev_b64 v[178:179], 1, v[144:145]
	v_ashrrev_i32_e32 v147, 31, v146
	s_addc_u32 s11, s31, s11
	v_lshl_add_u64 v[180:181], s[2:3], 0, v[178:179]
	v_lshlrev_b64 v[182:183], 12, v[146:147]
	v_lshl_add_u64 v[124:125], v[144:145], 2, s[10:11]
	v_lshl_add_u64 v[144:145], v[180:181], 0, v[182:183]
	global_load_dwordx4 v[128:131], v[124:125], off offset:16
	global_load_dwordx4 v[132:135], v[124:125], off
	global_load_dwordx4 v[120:123], v[124:125], off offset:528
	s_nop 0
	global_load_dwordx4 v[124:127], v[124:125], off offset:512
	s_nop 0
	global_load_dwordx4 v[196:199], v[144:145], off
	global_load_dwordx4 v[206:209], v[144:145], off offset:256
	v_or_b32_e32 v144, 16, v146
	v_ashrrev_i32_e32 v145, 31, v144
	v_lshlrev_b64 v[188:189], 12, v[144:145]
	v_lshl_add_u64 v[144:145], v[180:181], 0, v[188:189]
	global_load_dwordx4 v[164:167], v[144:145], off
	global_load_dwordx4 v[160:163], v[144:145], off offset:256
	v_or_b32_e32 v144, 32, v146
	v_ashrrev_i32_e32 v145, 31, v144
	v_lshlrev_b64 v[186:187], 12, v[144:145]
	v_lshl_add_u64 v[144:145], v[180:181], 0, v[186:187]
	global_load_dwordx4 v[156:159], v[144:145], off
	global_load_dwordx4 v[152:155], v[144:145], off offset:256
	v_or_b32_e32 v144, 48, v146
	v_ashrrev_i32_e32 v145, 31, v144
	v_lshlrev_b64 v[184:185], 12, v[144:145]
	v_lshl_add_u64 v[144:145], v[180:181], 0, v[184:185]
	global_load_dwordx4 v[148:151], v[144:145], off
	s_nop 0
	global_load_dwordx4 v[144:147], v[144:145], off offset:256
	s_mov_b64 s[10:11], 0x80000
	s_and_b64 vcc, exec, s[0:1]
	s_mov_b32 s41, s38
	s_mov_b32 s40, s39
	s_mov_b64 s[12:13], s[6:7]
	v_readlane_b32 s14, v254, 21
	s_movk_i32 s15, 0x2000
	s_waitcnt vmcnt(0)
	v_lshlrev_b32_e32 v210, 16, v196
	v_and_b32_e32 v211, 0xffff0000, v196
	v_lshlrev_b32_e32 v196, 16, v197
	v_and_b32_e32 v197, 0xffff0000, v197
	v_lshlrev_b32_e32 v214, 16, v198
	v_and_b32_e32 v215, 0xffff0000, v198
	v_lshlrev_b32_e32 v198, 16, v199
	v_and_b32_e32 v199, 0xffff0000, v199
	v_pk_fma_f32 v[140:141], v[140:141], v[132:133], v[210:211]
	v_pk_fma_f32 v[142:143], v[142:143], v[134:135], v[196:197]
	v_pk_fma_f32 v[196:197], v[138:139], v[130:131], v[198:199]
	v_pk_fma_f32 v[138:139], v[136:137], v[128:129], v[214:215]
	v_cvt_pk_bf16_f32 v136, v140, v141
	v_lshl_add_u64 v[140:141], s[8:9], 0, v[182:183]
	v_cvt_pk_bf16_f32 v137, v142, v143
	v_cvt_pk_bf16_f32 v138, v138, v139
	v_cvt_pk_bf16_f32 v139, v196, v197
	v_lshl_add_u64 v[140:141], v[140:141], 0, v[178:179]
	global_store_dwordx4 v[140:141], v[136:139], off
	v_lshlrev_b32_e32 v142, 16, v208
	v_and_b32_e32 v143, 0xffff0000, v208
	v_lshlrev_b32_e32 v136, 16, v206
	v_and_b32_e32 v137, 0xffff0000, v206
	v_lshlrev_b32_e32 v138, 16, v207
	v_and_b32_e32 v139, 0xffff0000, v207
	v_lshlrev_b32_e32 v196, 16, v209
	v_and_b32_e32 v197, 0xffff0000, v209
	v_pk_fma_f32 v[118:119], v[118:119], v[126:127], v[138:139]
	v_pk_fma_f32 v[116:117], v[116:117], v[124:125], v[136:137]
	v_pk_fma_f32 v[136:137], v[114:115], v[122:123], v[196:197]
	v_pk_fma_f32 v[114:115], v[112:113], v[120:121], v[142:143]
	v_cvt_pk_bf16_f32 v112, v116, v117
	v_cvt_pk_bf16_f32 v113, v118, v119
	v_lshlrev_b32_e32 v116, 16, v166
	v_cvt_pk_bf16_f32 v114, v114, v115
	v_cvt_pk_bf16_f32 v115, v136, v137
	global_store_dwordx4 v[140:141], v[112:115], off offset:256
	v_and_b32_e32 v117, 0xffff0000, v166
	v_lshlrev_b32_e32 v118, 16, v167
	v_lshlrev_b32_e32 v112, 16, v164
	v_and_b32_e32 v113, 0xffff0000, v164
	v_and_b32_e32 v119, 0xffff0000, v167
	v_pk_fma_f32 v[108:109], v[108:109], v[132:133], v[112:113]
	v_lshlrev_b32_e32 v114, 16, v165
	v_and_b32_e32 v115, 0xffff0000, v165
	v_pk_fma_f32 v[112:113], v[106:107], v[130:131], v[118:119]
	v_pk_fma_f32 v[106:107], v[104:105], v[128:129], v[116:117]
	v_cvt_pk_bf16_f32 v104, v108, v109
	v_lshl_add_u64 v[108:109], s[8:9], 0, v[188:189]
	v_pk_fma_f32 v[110:111], v[110:111], v[134:135], v[114:115]
	v_lshl_add_u64 v[108:109], v[108:109], 0, v[178:179]
	v_cvt_pk_bf16_f32 v105, v110, v111
	v_cvt_pk_bf16_f32 v106, v106, v107
	v_cvt_pk_bf16_f32 v107, v112, v113
	global_store_dwordx4 v[108:109], v[104:107], off
	v_lshlrev_b32_e32 v110, 16, v162
	v_and_b32_e32 v111, 0xffff0000, v162
	v_lshlrev_b32_e32 v104, 16, v160
	v_and_b32_e32 v105, 0xffff0000, v160
	v_lshlrev_b32_e32 v106, 16, v161
	v_and_b32_e32 v107, 0xffff0000, v161
	v_lshlrev_b32_e32 v112, 16, v163
	v_and_b32_e32 v113, 0xffff0000, v163
	v_pk_fma_f32 v[102:103], v[102:103], v[126:127], v[106:107]
	v_pk_fma_f32 v[100:101], v[100:101], v[124:125], v[104:105]
	v_pk_fma_f32 v[104:105], v[98:99], v[122:123], v[112:113]
	v_pk_fma_f32 v[98:99], v[96:97], v[120:121], v[110:111]
	v_cvt_pk_bf16_f32 v96, v100, v101
	v_cvt_pk_bf16_f32 v97, v102, v103
	v_lshlrev_b32_e32 v100, 16, v158
	v_cvt_pk_bf16_f32 v98, v98, v99
	v_cvt_pk_bf16_f32 v99, v104, v105
	global_store_dwordx4 v[108:109], v[96:99], off offset:256
	v_and_b32_e32 v101, 0xffff0000, v158
	v_lshlrev_b32_e32 v102, 16, v159
	v_lshlrev_b32_e32 v96, 16, v156
	v_and_b32_e32 v97, 0xffff0000, v156
	v_and_b32_e32 v103, 0xffff0000, v159
	v_pk_fma_f32 v[92:93], v[92:93], v[132:133], v[96:97]
	v_lshlrev_b32_e32 v98, 16, v157
	v_and_b32_e32 v99, 0xffff0000, v157
	v_pk_fma_f32 v[96:97], v[90:91], v[130:131], v[102:103]
	v_pk_fma_f32 v[90:91], v[88:89], v[128:129], v[100:101]
	v_cvt_pk_bf16_f32 v88, v92, v93
	v_lshl_add_u64 v[92:93], s[8:9], 0, v[186:187]
	v_pk_fma_f32 v[94:95], v[94:95], v[134:135], v[98:99]
	v_lshl_add_u64 v[92:93], v[92:93], 0, v[178:179]
	v_cvt_pk_bf16_f32 v89, v94, v95
	v_cvt_pk_bf16_f32 v90, v90, v91
	v_cvt_pk_bf16_f32 v91, v96, v97
	global_store_dwordx4 v[92:93], v[88:91], off
	v_lshlrev_b32_e32 v94, 16, v154
	v_and_b32_e32 v95, 0xffff0000, v154
	v_lshlrev_b32_e32 v88, 16, v152
	v_and_b32_e32 v89, 0xffff0000, v152
	v_lshlrev_b32_e32 v90, 16, v153
	v_and_b32_e32 v91, 0xffff0000, v153
	v_lshlrev_b32_e32 v96, 16, v155
	v_and_b32_e32 v97, 0xffff0000, v155
	v_pk_fma_f32 v[86:87], v[86:87], v[126:127], v[90:91]
	v_pk_fma_f32 v[84:85], v[84:85], v[124:125], v[88:89]
	v_pk_fma_f32 v[88:89], v[82:83], v[122:123], v[96:97]
	v_pk_fma_f32 v[82:83], v[80:81], v[120:121], v[94:95]
	v_cvt_pk_bf16_f32 v80, v84, v85
	v_cvt_pk_bf16_f32 v81, v86, v87
	v_lshlrev_b32_e32 v84, 16, v150
	v_cvt_pk_bf16_f32 v82, v82, v83
	v_cvt_pk_bf16_f32 v83, v88, v89
	global_store_dwordx4 v[92:93], v[80:83], off offset:256
	v_and_b32_e32 v85, 0xffff0000, v150
	v_lshlrev_b32_e32 v86, 16, v151
	v_lshlrev_b32_e32 v80, 16, v148
	v_and_b32_e32 v81, 0xffff0000, v148
	v_and_b32_e32 v87, 0xffff0000, v151
	v_pk_fma_f32 v[76:77], v[76:77], v[132:133], v[80:81]
	v_lshlrev_b32_e32 v82, 16, v149
	v_and_b32_e32 v83, 0xffff0000, v149
	v_pk_fma_f32 v[80:81], v[74:75], v[130:131], v[86:87]
	v_pk_fma_f32 v[74:75], v[72:73], v[128:129], v[84:85]
	v_cvt_pk_bf16_f32 v72, v76, v77
	v_lshl_add_u64 v[76:77], s[8:9], 0, v[184:185]
	v_pk_fma_f32 v[78:79], v[78:79], v[134:135], v[82:83]
	v_lshl_add_u64 v[76:77], v[76:77], 0, v[178:179]
	v_cvt_pk_bf16_f32 v73, v78, v79
	v_cvt_pk_bf16_f32 v74, v74, v75
	v_cvt_pk_bf16_f32 v75, v80, v81
	global_store_dwordx4 v[76:77], v[72:75], off
	v_lshlrev_b32_e32 v78, 16, v146
	v_and_b32_e32 v79, 0xffff0000, v146
	v_lshlrev_b32_e32 v72, 16, v144
	v_and_b32_e32 v73, 0xffff0000, v144
	v_lshlrev_b32_e32 v74, 16, v145
	v_and_b32_e32 v75, 0xffff0000, v145
	v_lshlrev_b32_e32 v80, 16, v147
	v_and_b32_e32 v81, 0xffff0000, v147
	v_pk_fma_f32 v[70:71], v[70:71], v[126:127], v[74:75]
	v_pk_fma_f32 v[68:69], v[68:69], v[124:125], v[72:73]
	v_pk_fma_f32 v[72:73], v[66:67], v[122:123], v[80:81]
	v_pk_fma_f32 v[66:67], v[64:65], v[120:121], v[78:79]
	v_cvt_pk_bf16_f32 v64, v68, v69
	v_cvt_pk_bf16_f32 v65, v70, v71
	v_lshl_add_u64 v[98:99], v[182:183], 0, s[10:11]
	v_cvt_pk_bf16_f32 v66, v66, v67
	v_cvt_pk_bf16_f32 v67, v72, v73
	global_store_dwordx4 v[76:77], v[64:67], off offset:256
	s_mov_b64 s[10:11], 0x90000
	v_lshl_add_u64 v[100:101], v[182:183], 0, s[10:11]
	v_lshl_add_u64 v[64:65], v[180:181], 0, v[98:99]
	global_load_dwordx4 v[74:77], v[64:65], off
	global_load_dwordx4 v[78:81], v[64:65], off offset:256
	v_lshl_add_u64 v[64:65], v[180:181], 0, v[100:101]
	global_load_dwordx4 v[82:85], v[64:65], off
	global_load_dwordx4 v[86:89], v[64:65], off offset:256
	s_mov_b64 s[10:11], 0xa0000
	v_lshl_add_u64 v[102:103], v[182:183], 0, s[10:11]
	v_lshl_add_u64 v[64:65], v[180:181], 0, v[102:103]
	global_load_dwordx4 v[90:93], v[64:65], off
	global_load_dwordx4 v[94:97], v[64:65], off offset:256
	s_mov_b64 s[10:11], 0xb0000
	v_lshl_add_u64 v[72:73], v[182:183], 0, s[10:11]
	v_lshl_add_u64 v[64:65], v[180:181], 0, v[72:73]
	global_load_dwordx4 v[68:71], v[64:65], off
	s_nop 0
	global_load_dwordx4 v[64:67], v[64:65], off offset:256
	s_mov_b64 s[10:11], s[4:5]
	s_waitcnt vmcnt(0)
	v_lshlrev_b32_e32 v104, 16, v74
	v_and_b32_e32 v105, 0xffff0000, v74
	v_lshlrev_b32_e32 v74, 16, v75
	v_and_b32_e32 v75, 0xffff0000, v75
	v_lshlrev_b32_e32 v106, 16, v76
	v_and_b32_e32 v107, 0xffff0000, v76
	v_lshlrev_b32_e32 v76, 16, v77
	v_and_b32_e32 v77, 0xffff0000, v77
	v_pk_fma_f32 v[60:61], v[60:61], v[132:133], v[104:105]
	v_pk_fma_f32 v[62:63], v[62:63], v[134:135], v[74:75]
	v_pk_fma_f32 v[74:75], v[58:59], v[130:131], v[76:77]
	v_pk_fma_f32 v[58:59], v[56:57], v[128:129], v[106:107]
	v_cvt_pk_bf16_f32 v56, v60, v61
	v_lshl_add_u64 v[60:61], s[8:9], 0, v[98:99]
	v_cvt_pk_bf16_f32 v57, v62, v63
	v_cvt_pk_bf16_f32 v58, v58, v59
	v_cvt_pk_bf16_f32 v59, v74, v75
	v_lshl_add_u64 v[60:61], v[60:61], 0, v[178:179]
	global_store_dwordx4 v[60:61], v[56:59], off
	v_lshlrev_b32_e32 v62, 16, v80
	v_and_b32_e32 v63, 0xffff0000, v80
	v_lshlrev_b32_e32 v56, 16, v78
	v_and_b32_e32 v57, 0xffff0000, v78
	v_lshlrev_b32_e32 v58, 16, v79
	v_and_b32_e32 v59, 0xffff0000, v79
	v_lshlrev_b32_e32 v74, 16, v81
	v_and_b32_e32 v75, 0xffff0000, v81
	v_pk_fma_f32 v[54:55], v[54:55], v[126:127], v[58:59]
	v_pk_fma_f32 v[52:53], v[52:53], v[124:125], v[56:57]
	v_pk_fma_f32 v[56:57], v[50:51], v[122:123], v[74:75]
	v_pk_fma_f32 v[50:51], v[48:49], v[120:121], v[62:63]
	v_cvt_pk_bf16_f32 v48, v52, v53
	v_cvt_pk_bf16_f32 v49, v54, v55
	v_lshlrev_b32_e32 v52, 16, v84
	v_cvt_pk_bf16_f32 v50, v50, v51
	v_cvt_pk_bf16_f32 v51, v56, v57
	global_store_dwordx4 v[60:61], v[48:51], off offset:256
	v_and_b32_e32 v53, 0xffff0000, v84
	v_lshlrev_b32_e32 v54, 16, v85
	v_lshlrev_b32_e32 v48, 16, v82
	v_and_b32_e32 v49, 0xffff0000, v82
	v_and_b32_e32 v55, 0xffff0000, v85
	v_pk_fma_f32 v[44:45], v[44:45], v[132:133], v[48:49]
	v_lshlrev_b32_e32 v50, 16, v83
	v_and_b32_e32 v51, 0xffff0000, v83
	v_pk_fma_f32 v[48:49], v[42:43], v[130:131], v[54:55]
	v_pk_fma_f32 v[42:43], v[40:41], v[128:129], v[52:53]
	v_cvt_pk_bf16_f32 v40, v44, v45
	v_lshl_add_u64 v[44:45], s[8:9], 0, v[100:101]
	v_pk_fma_f32 v[46:47], v[46:47], v[134:135], v[50:51]
	v_lshl_add_u64 v[44:45], v[44:45], 0, v[178:179]
	v_cvt_pk_bf16_f32 v41, v46, v47
	v_cvt_pk_bf16_f32 v42, v42, v43
	v_cvt_pk_bf16_f32 v43, v48, v49
	global_store_dwordx4 v[44:45], v[40:43], off
	v_lshlrev_b32_e32 v46, 16, v88
	v_and_b32_e32 v47, 0xffff0000, v88
	v_lshlrev_b32_e32 v40, 16, v86
	v_and_b32_e32 v41, 0xffff0000, v86
	v_lshlrev_b32_e32 v42, 16, v87
	v_and_b32_e32 v43, 0xffff0000, v87
	v_lshlrev_b32_e32 v48, 16, v89
	v_and_b32_e32 v49, 0xffff0000, v89
	v_pk_fma_f32 v[38:39], v[38:39], v[126:127], v[42:43]
	v_pk_fma_f32 v[36:37], v[36:37], v[124:125], v[40:41]
	v_pk_fma_f32 v[40:41], v[34:35], v[122:123], v[48:49]
	v_pk_fma_f32 v[34:35], v[32:33], v[120:121], v[46:47]
	v_cvt_pk_bf16_f32 v32, v36, v37
	v_cvt_pk_bf16_f32 v33, v38, v39
	v_lshlrev_b32_e32 v36, 16, v92
	v_cvt_pk_bf16_f32 v34, v34, v35
	v_cvt_pk_bf16_f32 v35, v40, v41
	global_store_dwordx4 v[44:45], v[32:35], off offset:256
	v_and_b32_e32 v37, 0xffff0000, v92
	v_lshlrev_b32_e32 v38, 16, v93
	v_lshlrev_b32_e32 v32, 16, v90
	v_and_b32_e32 v33, 0xffff0000, v90
	v_and_b32_e32 v39, 0xffff0000, v93
	v_pk_fma_f32 v[28:29], v[28:29], v[132:133], v[32:33]
	v_lshlrev_b32_e32 v34, 16, v91
	v_and_b32_e32 v35, 0xffff0000, v91
	v_pk_fma_f32 v[32:33], v[26:27], v[130:131], v[38:39]
	v_pk_fma_f32 v[26:27], v[24:25], v[128:129], v[36:37]
	v_cvt_pk_bf16_f32 v24, v28, v29
	v_lshl_add_u64 v[28:29], s[8:9], 0, v[102:103]
	v_pk_fma_f32 v[30:31], v[30:31], v[134:135], v[34:35]
	v_lshl_add_u64 v[28:29], v[28:29], 0, v[178:179]
	v_cvt_pk_bf16_f32 v25, v30, v31
	v_cvt_pk_bf16_f32 v26, v26, v27
	v_cvt_pk_bf16_f32 v27, v32, v33
	global_store_dwordx4 v[28:29], v[24:27], off
	v_lshlrev_b32_e32 v30, 16, v96
	v_and_b32_e32 v31, 0xffff0000, v96
	v_lshlrev_b32_e32 v24, 16, v94
	v_and_b32_e32 v25, 0xffff0000, v94
	v_lshlrev_b32_e32 v26, 16, v95
	v_and_b32_e32 v27, 0xffff0000, v95
	v_lshlrev_b32_e32 v32, 16, v97
	v_and_b32_e32 v33, 0xffff0000, v97
	v_pk_fma_f32 v[22:23], v[22:23], v[126:127], v[26:27]
	v_pk_fma_f32 v[20:21], v[20:21], v[124:125], v[24:25]
	v_pk_fma_f32 v[24:25], v[18:19], v[122:123], v[32:33]
	v_pk_fma_f32 v[18:19], v[16:17], v[120:121], v[30:31]
	v_cvt_pk_bf16_f32 v16, v20, v21
	v_cvt_pk_bf16_f32 v17, v22, v23
	v_lshlrev_b32_e32 v20, 16, v70
	v_cvt_pk_bf16_f32 v18, v18, v19
	v_cvt_pk_bf16_f32 v19, v24, v25
	global_store_dwordx4 v[28:29], v[16:19], off offset:256
	v_and_b32_e32 v21, 0xffff0000, v70
	v_lshlrev_b32_e32 v22, 16, v71
	v_lshlrev_b32_e32 v16, 16, v68
	v_and_b32_e32 v17, 0xffff0000, v68
	v_and_b32_e32 v23, 0xffff0000, v71
	v_pk_fma_f32 v[12:13], v[12:13], v[132:133], v[16:17]
	v_lshlrev_b32_e32 v18, 16, v69
	v_and_b32_e32 v19, 0xffff0000, v69
	v_pk_fma_f32 v[16:17], v[10:11], v[130:131], v[22:23]
	v_pk_fma_f32 v[10:11], v[8:9], v[128:129], v[20:21]
	v_cvt_pk_bf16_f32 v8, v12, v13
	v_lshl_add_u64 v[12:13], s[8:9], 0, v[72:73]
	v_pk_fma_f32 v[14:15], v[14:15], v[134:135], v[18:19]
	v_lshl_add_u64 v[12:13], v[12:13], 0, v[178:179]
	v_cvt_pk_bf16_f32 v9, v14, v15
	v_cvt_pk_bf16_f32 v10, v10, v11
	v_cvt_pk_bf16_f32 v11, v16, v17
	global_store_dwordx4 v[12:13], v[8:11], off
	v_lshlrev_b32_e32 v14, 16, v66
	v_and_b32_e32 v15, 0xffff0000, v66
	v_lshlrev_b32_e32 v8, 16, v64
	v_and_b32_e32 v9, 0xffff0000, v64
	v_lshlrev_b32_e32 v16, 16, v67
	v_and_b32_e32 v17, 0xffff0000, v67
	v_lshlrev_b32_e32 v10, 16, v65
	v_and_b32_e32 v11, 0xffff0000, v65
	v_pk_fma_f32 v[4:5], v[4:5], v[124:125], v[8:9]
	v_pk_fma_f32 v[8:9], v[2:3], v[122:123], v[16:17]
	v_pk_fma_f32 v[2:3], v[0:1], v[120:121], v[14:15]
	v_pk_fma_f32 v[6:7], v[6:7], v[126:127], v[10:11]
	v_cvt_pk_bf16_f32 v0, v4, v5
	s_nop 0
	v_cvt_pk_bf16_f32 v1, v6, v7
	v_cvt_pk_bf16_f32 v2, v2, v3
	v_cvt_pk_bf16_f32 v3, v8, v9
	global_store_dwordx4 v[12:13], v[0:3], off offset:256
	s_cbranch_vccz .LBB0_235
	s_waitcnt vmcnt(0)
	s_cmpk_gt_u32 s16, 0xff
	s_cbranch_scc1 .LBB0_250
	s_barrier

.LBB0_272:
	ds_read_b128 v[108:111], v220 offset:0
	ds_read_b128 v[112:115], v220 offset:1024
	ds_read_b128 v[116:119], v220 offset:2048
	ds_read_b128 v[120:123], v220 offset:3072
	ds_read_b128 v[144:147], v189
	ds_read_b128 v[148:151], v189 offset:1024
	ds_read_b128 v[152:155], v189 offset:2048
	ds_read_b128 v[156:159], v189 offset:3072
	ds_read_b128 v[160:163], v189 offset:4096
	ds_read_b128 v[174:177], v189 offset:5120
	ds_read_b128 v[178:181], v189 offset:6144
	ds_read_b128 v[182:185], v189 offset:7168
	global_load_lds_dwordx4 v170, s[8:9]
	s_add_i32 m0, s25, 0xe000
	s_nop 0
	global_load_lds_dwordx4 v172, s[8:9]
	s_waitcnt lgkmcnt(8)
	s_barrier
	s_waitcnt lgkmcnt(0)
	v_mfma_f32_16x16x32_bf16 v[140:143], v[108:111], v[144:147], v[140:143]
	v_mfma_f32_16x16x32_bf16 v[136:139], v[116:119], v[144:147], v[136:139]
	v_mfma_f32_16x16x32_bf16 v[132:135], v[108:111], v[152:155], v[132:135]
	v_mfma_f32_16x16x32_bf16 v[104:107], v[116:119], v[152:155], v[104:107]
	s_add_i32 s43, 0, 0x14000
	s_add_i32 s8, s42, s19
	v_mfma_f32_16x16x32_bf16 v[96:99], v[108:111], v[160:163], v[96:99]
	s_mov_b32 m0, s8
	v_mfma_f32_16x16x32_bf16 v[88:91], v[116:119], v[160:163], v[88:91]
	v_mfma_f32_16x16x32_bf16 v[80:83], v[108:111], v[178:181], v[80:83]
	v_mfma_f32_16x16x32_bf16 v[72:75], v[116:119], v[178:181], v[72:75]
	v_mfma_f32_16x16x32_bf16 v[140:143], v[112:115], v[148:151], v[140:143]
	v_mfma_f32_16x16x32_bf16 v[136:139], v[120:123], v[148:151], v[136:139]
	v_mfma_f32_16x16x32_bf16 v[132:135], v[112:115], v[156:159], v[132:135]
	v_mfma_f32_16x16x32_bf16 v[104:107], v[120:123], v[156:159], v[104:107]
	v_mfma_f32_16x16x32_bf16 v[96:99], v[112:115], v[174:177], v[96:99]
	v_mfma_f32_16x16x32_bf16 v[88:91], v[120:123], v[174:177], v[88:91]
	v_mfma_f32_16x16x32_bf16 v[80:83], v[112:115], v[182:185], v[80:83]
	v_mfma_f32_16x16x32_bf16 v[72:75], v[120:123], v[182:185], v[72:75]
	s_barrier
	ds_read_b128 v[196:199], v220 offset:16384
	ds_read_b128 v[204:207], v220 offset:17408
	ds_read_b128 v[208:211], v220 offset:18432
	ds_read_b128 v[214:217], v220 offset:19456
	global_load_lds_dwordx4 v192, s[12:13]
	s_add_i32 m0, s8, 0x2000
	s_nop 0
	global_load_lds_dwordx4 v168, s[12:13]
	s_barrier
	s_waitcnt lgkmcnt(0)
	v_mfma_f32_16x16x32_bf16 v[128:131], v[196:199], v[144:147], v[128:131]
	v_mfma_f32_16x16x32_bf16 v[124:127], v[208:211], v[144:147], v[124:127]
	v_mfma_f32_16x16x32_bf16 v[100:103], v[196:199], v[152:155], v[100:103]
	v_mfma_f32_16x16x32_bf16 v[92:95], v[208:211], v[152:155], v[92:95]
	s_mov_b32 m0, s25
	v_mfma_f32_16x16x32_bf16 v[84:87], v[196:199], v[160:163], v[84:87]
	s_add_u32 s44, s14, 0x80
	s_addc_u32 s45, s15, 0
	v_mfma_f32_16x16x32_bf16 v[76:79], v[208:211], v[160:163], v[76:79]
	v_mfma_f32_16x16x32_bf16 v[68:71], v[196:199], v[178:181], v[68:71]
	v_mfma_f32_16x16x32_bf16 v[64:67], v[208:211], v[178:181], v[64:67]
	v_mfma_f32_16x16x32_bf16 v[128:131], v[204:207], v[148:151], v[128:131]
	v_mfma_f32_16x16x32_bf16 v[124:127], v[214:217], v[148:151], v[124:127]
	v_mfma_f32_16x16x32_bf16 v[100:103], v[204:207], v[156:159], v[100:103]
	v_mfma_f32_16x16x32_bf16 v[92:95], v[214:217], v[156:159], v[92:95]
	v_mfma_f32_16x16x32_bf16 v[84:87], v[204:207], v[174:177], v[84:87]
	v_mfma_f32_16x16x32_bf16 v[76:79], v[214:217], v[174:177], v[76:79]
	v_mfma_f32_16x16x32_bf16 v[68:71], v[204:207], v[182:185], v[68:71]
	v_mfma_f32_16x16x32_bf16 v[64:67], v[214:217], v[182:185], v[64:67]
	s_barrier
	ds_read_b128 v[144:147], v189 offset:16384
	ds_read_b128 v[148:151], v189 offset:17408
	ds_read_b128 v[152:155], v189 offset:18432
	ds_read_b128 v[156:159], v189 offset:19456
	ds_read_b128 v[160:163], v189 offset:20480
	ds_read_b128 v[174:177], v189 offset:21504
	ds_read_b128 v[178:181], v189 offset:22528
	ds_read_b128 v[182:185], v189 offset:23552
	global_load_lds_dwordx4 v164, s[14:15]
	s_mov_b32 m0, s26
	s_nop 0
	global_load_lds_dwordx4 v166, s[14:15]
	s_barrier
	s_waitcnt lgkmcnt(0)
	v_mfma_f32_16x16x32_bf16 v[60:63], v[108:111], v[144:147], v[60:63]
	v_mfma_f32_16x16x32_bf16 v[56:59], v[116:119], v[144:147], v[56:59]
	v_mfma_f32_16x16x32_bf16 v[48:51], v[108:111], v[152:155], v[48:51]
	v_mfma_f32_16x16x32_bf16 v[40:43], v[116:119], v[152:155], v[40:43]
	s_add_u32 s8, s12, 0x160000
	s_addc_u32 s9, s13, 0
	v_mfma_f32_16x16x32_bf16 v[32:35], v[108:111], v[160:163], v[32:35]
	s_add_i32 s42, s43, s19
	s_mov_b32 m0, s42
	v_mfma_f32_16x16x32_bf16 v[24:27], v[116:119], v[160:163], v[24:27]
	v_mfma_f32_16x16x32_bf16 v[16:19], v[108:111], v[178:181], v[16:19]
	v_mfma_f32_16x16x32_bf16 v[8:11], v[116:119], v[178:181], v[8:11]
	v_mfma_f32_16x16x32_bf16 v[60:63], v[112:115], v[148:151], v[60:63]
	v_mfma_f32_16x16x32_bf16 v[56:59], v[120:123], v[148:151], v[56:59]
	v_mfma_f32_16x16x32_bf16 v[48:51], v[112:115], v[156:159], v[48:51]
	v_mfma_f32_16x16x32_bf16 v[40:43], v[120:123], v[156:159], v[40:43]
	v_mfma_f32_16x16x32_bf16 v[32:35], v[112:115], v[174:177], v[32:35]
	v_mfma_f32_16x16x32_bf16 v[24:27], v[120:123], v[174:177], v[24:27]
	v_mfma_f32_16x16x32_bf16 v[16:19], v[112:115], v[182:185], v[16:19]
	v_mfma_f32_16x16x32_bf16 v[8:11], v[120:123], v[182:185], v[8:11]
	s_barrier
	global_load_lds_dwordx4 v192, s[8:9]
	s_add_i32 m0, s42, 0x2000
	s_nop 0
	global_load_lds_dwordx4 v168, s[8:9]
	s_waitcnt vmcnt(6)
	s_barrier
	v_mfma_f32_16x16x32_bf16 v[52:55], v[196:199], v[144:147], v[52:55]
	v_mfma_f32_16x16x32_bf16 v[44:47], v[208:211], v[144:147], v[44:47]
	v_mfma_f32_16x16x32_bf16 v[36:39], v[196:199], v[152:155], v[36:39]
	v_mfma_f32_16x16x32_bf16 v[28:31], v[208:211], v[152:155], v[28:31]
	s_add_i32 s42, 0, 0x18000
	v_mfma_f32_16x16x32_bf16 v[20:23], v[196:199], v[160:163], v[20:23]
	s_add_u32 s8, s14, 0x160000
	s_addc_u32 s9, s15, 0
	v_mfma_f32_16x16x32_bf16 v[12:15], v[208:211], v[160:163], v[12:15]
	s_mov_b32 m0, s27
	v_mfma_f32_16x16x32_bf16 v[4:7], v[196:199], v[178:181], v[4:7]
	v_mfma_f32_16x16x32_bf16 v[0:3], v[208:211], v[178:181], v[0:3]
	v_mfma_f32_16x16x32_bf16 v[52:55], v[204:207], v[148:151], v[52:55]
	v_mfma_f32_16x16x32_bf16 v[44:47], v[214:217], v[148:151], v[44:47]
	v_mfma_f32_16x16x32_bf16 v[36:39], v[204:207], v[156:159], v[36:39]
	v_mfma_f32_16x16x32_bf16 v[28:31], v[214:217], v[156:159], v[28:31]
	v_mfma_f32_16x16x32_bf16 v[20:23], v[204:207], v[174:177], v[20:23]
	v_mfma_f32_16x16x32_bf16 v[12:15], v[214:217], v[174:177], v[12:15]
	v_mfma_f32_16x16x32_bf16 v[4:7], v[204:207], v[182:185], v[4:7]
	v_mfma_f32_16x16x32_bf16 v[0:3], v[214:217], v[182:185], v[0:3]
	s_barrier
	ds_read_b128 v[108:111], v220 offset:32768
	ds_read_b128 v[112:115], v220 offset:33792
	ds_read_b128 v[116:119], v220 offset:34816
	ds_read_b128 v[120:123], v220 offset:35840
	ds_read_b128 v[144:147], v189 offset:32768
	ds_read_b128 v[148:151], v189 offset:33792
	ds_read_b128 v[152:155], v189 offset:34816
	ds_read_b128 v[156:159], v189 offset:35840
	ds_read_b128 v[160:163], v189 offset:36864
	ds_read_b128 v[174:177], v189 offset:37888
	ds_read_b128 v[178:181], v189 offset:38912
	ds_read_b128 v[182:185], v189 offset:39936
	global_load_lds_dwordx4 v164, s[8:9]
	s_mov_b32 m0, s28
	s_nop 0
	global_load_lds_dwordx4 v166, s[8:9]
	s_waitcnt lgkmcnt(8)
	s_barrier
	s_waitcnt lgkmcnt(0)
	v_mfma_f32_16x16x32_bf16 v[140:143], v[108:111], v[144:147], v[140:143]
	v_mfma_f32_16x16x32_bf16 v[136:139], v[116:119], v[144:147], v[136:139]
	v_mfma_f32_16x16x32_bf16 v[132:135], v[108:111], v[152:155], v[132:135]
	v_mfma_f32_16x16x32_bf16 v[104:107], v[116:119], v[152:155], v[104:107]
	s_add_i32 s14, 0, 0x1c000
	s_add_i32 s8, s42, s19
	v_mfma_f32_16x16x32_bf16 v[96:99], v[108:111], v[160:163], v[96:99]
	s_add_i32 m0, s8, 0xffffff80
	v_mfma_f32_16x16x32_bf16 v[88:91], v[116:119], v[160:163], v[88:91]
	v_mfma_f32_16x16x32_bf16 v[80:83], v[108:111], v[178:181], v[80:83]
	v_mfma_f32_16x16x32_bf16 v[72:75], v[116:119], v[178:181], v[72:75]
	v_mfma_f32_16x16x32_bf16 v[140:143], v[112:115], v[148:151], v[140:143]
	v_mfma_f32_16x16x32_bf16 v[136:139], v[120:123], v[148:151], v[136:139]
	v_mfma_f32_16x16x32_bf16 v[132:135], v[112:115], v[156:159], v[132:135]
	v_mfma_f32_16x16x32_bf16 v[104:107], v[120:123], v[156:159], v[104:107]
	v_mfma_f32_16x16x32_bf16 v[96:99], v[112:115], v[174:177], v[96:99]
	v_mfma_f32_16x16x32_bf16 v[88:91], v[120:123], v[174:177], v[88:91]
	v_mfma_f32_16x16x32_bf16 v[80:83], v[112:115], v[182:185], v[80:83]
	v_mfma_f32_16x16x32_bf16 v[72:75], v[120:123], v[182:185], v[72:75]
	s_barrier
	ds_read_b128 v[196:199], v220 offset:49152
	ds_read_b128 v[204:207], v220 offset:50176
	ds_read_b128 v[208:211], v220 offset:51200
	ds_read_b128 v[214:217], v220 offset:52224
	global_load_lds_dwordx4 v192, s[12:13] offset:128
	s_add_i32 m0, s8, 0x1f80
	s_nop 0
	global_load_lds_dwordx4 v168, s[12:13] offset:128
	s_barrier
	s_waitcnt lgkmcnt(0)
	v_mfma_f32_16x16x32_bf16 v[128:131], v[196:199], v[144:147], v[128:131]
	v_mfma_f32_16x16x32_bf16 v[124:127], v[208:211], v[144:147], v[124:127]
	v_mfma_f32_16x16x32_bf16 v[100:103], v[196:199], v[152:155], v[100:103]
	v_mfma_f32_16x16x32_bf16 v[92:95], v[208:211], v[152:155], v[92:95]
	s_mov_b32 m0, s31
	v_mfma_f32_16x16x32_bf16 v[84:87], v[196:199], v[160:163], v[84:87]
	v_mfma_f32_16x16x32_bf16 v[76:79], v[208:211], v[160:163], v[76:79]
	v_mfma_f32_16x16x32_bf16 v[68:71], v[196:199], v[178:181], v[68:71]
	v_mfma_f32_16x16x32_bf16 v[64:67], v[208:211], v[178:181], v[64:67]
	v_mfma_f32_16x16x32_bf16 v[128:131], v[204:207], v[148:151], v[128:131]
	v_mfma_f32_16x16x32_bf16 v[124:127], v[214:217], v[148:151], v[124:127]
	v_mfma_f32_16x16x32_bf16 v[100:103], v[204:207], v[156:159], v[100:103]
	v_mfma_f32_16x16x32_bf16 v[92:95], v[214:217], v[156:159], v[92:95]
	v_mfma_f32_16x16x32_bf16 v[84:87], v[204:207], v[174:177], v[84:87]
	v_mfma_f32_16x16x32_bf16 v[76:79], v[214:217], v[174:177], v[76:79]
	v_mfma_f32_16x16x32_bf16 v[68:71], v[204:207], v[182:185], v[68:71]
	v_mfma_f32_16x16x32_bf16 v[64:67], v[214:217], v[182:185], v[64:67]
	s_barrier
	ds_read_b128 v[144:147], v189 offset:49152
	ds_read_b128 v[148:151], v189 offset:50176
	ds_read_b128 v[152:155], v189 offset:51200
	ds_read_b128 v[156:159], v189 offset:52224
	ds_read_b128 v[160:163], v189 offset:53248
	ds_read_b128 v[174:177], v189 offset:54272
	ds_read_b128 v[178:181], v189 offset:55296
	ds_read_b128 v[182:185], v189 offset:56320
	global_load_lds_dwordx4 v164, s[44:45]
	s_mov_b32 m0, s33
	s_nop 0
	global_load_lds_dwordx4 v166, s[44:45]
	s_barrier
	s_waitcnt lgkmcnt(0)
	v_mfma_f32_16x16x32_bf16 v[60:63], v[108:111], v[144:147], v[60:63]
	v_mfma_f32_16x16x32_bf16 v[56:59], v[116:119], v[144:147], v[56:59]
	v_mfma_f32_16x16x32_bf16 v[48:51], v[108:111], v[152:155], v[48:51]
	v_mfma_f32_16x16x32_bf16 v[40:43], v[116:119], v[152:155], v[40:43]
	s_add_u32 s8, s12, 0x160080
	s_addc_u32 s9, s13, 0
	v_mfma_f32_16x16x32_bf16 v[32:35], v[108:111], v[160:163], v[32:35]
	s_add_i32 s12, s14, s19
	s_mov_b32 m0, s12
	v_mfma_f32_16x16x32_bf16 v[24:27], v[116:119], v[160:163], v[24:27]
	v_mfma_f32_16x16x32_bf16 v[16:19], v[108:111], v[178:181], v[16:19]
	v_mfma_f32_16x16x32_bf16 v[8:11], v[116:119], v[178:181], v[8:11]
	v_mfma_f32_16x16x32_bf16 v[60:63], v[112:115], v[148:151], v[60:63]
	v_mfma_f32_16x16x32_bf16 v[56:59], v[120:123], v[148:151], v[56:59]
	v_mfma_f32_16x16x32_bf16 v[48:51], v[112:115], v[156:159], v[48:51]
	v_mfma_f32_16x16x32_bf16 v[40:43], v[120:123], v[156:159], v[40:43]
	v_mfma_f32_16x16x32_bf16 v[32:35], v[112:115], v[174:177], v[32:35]
	v_mfma_f32_16x16x32_bf16 v[24:27], v[120:123], v[174:177], v[24:27]
	v_mfma_f32_16x16x32_bf16 v[16:19], v[112:115], v[182:185], v[16:19]
	v_mfma_f32_16x16x32_bf16 v[8:11], v[120:123], v[182:185], v[8:11]
	s_barrier
	global_load_lds_dwordx4 v192, s[8:9]
	s_add_i32 m0, s12, 0x2000
	s_nop 0
	global_load_lds_dwordx4 v168, s[8:9]
	s_waitcnt vmcnt(6)
	s_barrier
	v_mfma_f32_16x16x32_bf16 v[52:55], v[196:199], v[144:147], v[52:55]
	v_mfma_f32_16x16x32_bf16 v[44:47], v[208:211], v[144:147], v[44:47]
	v_mfma_f32_16x16x32_bf16 v[36:39], v[196:199], v[152:155], v[36:39]
	v_mfma_f32_16x16x32_bf16 v[28:31], v[208:211], v[152:155], v[28:31]
	s_add_i32 s41, s41, 2
	v_mfma_f32_16x16x32_bf16 v[20:23], v[196:199], v[160:163], v[20:23]
	s_add_u32 s39, s39, 0x100
	s_addc_u32 s40, s40, 0
	v_mfma_f32_16x16x32_bf16 v[12:15], v[208:211], v[160:163], v[12:15]
	s_mov_b64 s[8:9], s[10:11]
	v_mfma_f32_16x16x32_bf16 v[4:7], v[196:199], v[178:181], v[4:7]
	s_add_u32 s10, s8, 0x100
	s_addc_u32 s11, s9, 0
	v_mfma_f32_16x16x32_bf16 v[0:3], v[208:211], v[178:181], v[0:3]
	s_add_i32 s42, 0, 0x10000
	s_cmpk_eq_i32 s41, 0x54
	v_mfma_f32_16x16x32_bf16 v[52:55], v[204:207], v[148:151], v[52:55]
	s_cselect_b32 s15, s5, s11
	s_cselect_b32 s14, s4, s10
	v_mfma_f32_16x16x32_bf16 v[44:47], v[214:217], v[148:151], v[44:47]
	s_cselect_b32 s13, s7, s40
	s_cselect_b32 s12, s6, s39
	v_mfma_f32_16x16x32_bf16 v[36:39], v[204:207], v[156:159], v[36:39]
	s_add_i32 m0, s25, 0xc000
	v_mfma_f32_16x16x32_bf16 v[28:31], v[214:217], v[156:159], v[28:31]
	v_mfma_f32_16x16x32_bf16 v[20:23], v[204:207], v[174:177], v[20:23]
	v_mfma_f32_16x16x32_bf16 v[12:15], v[214:217], v[174:177], v[12:15]
	v_mfma_f32_16x16x32_bf16 v[4:7], v[204:207], v[182:185], v[4:7]
	v_mfma_f32_16x16x32_bf16 v[0:3], v[214:217], v[182:185], v[0:3]
	s_cmpk_gt_u32 s41, 0x55
	s_cbranch_scc0 .Lrot_272
	s_barrier
	s_ashr_i32 s8, s37, 4
	v_lshl_or_b32 v144, s38, 8, v188
	s_mul_hi_i32 s9, s8, 0xc000
	s_mul_i32 s8, s8, 0xc000
	v_lshl_add_u32 v178, s37, 8, v186
	s_add_u32 s8, s29, s8
	v_ashrrev_i32_e32 v145, 31, v144
	v_ashrrev_i32_e32 v179, 31, v178
	s_addc_u32 s9, s30, s9
	v_lshlrev_b64 v[174:175], 2, v[144:145]
	v_lshl_add_u64 v[176:177], v[144:145], 1, s[2:3]
	v_lshlrev_b64 v[144:145], 12, v[178:179]
	v_lshl_add_u64 v[112:113], s[8:9], 0, v[174:175]
	v_lshl_add_u64 v[144:145], v[176:177], 0, v[144:145]
	global_load_dwordx4 v[116:119], v[112:113], off offset:16
	global_load_dwordx4 v[120:123], v[112:113], off
	global_load_dwordx4 v[108:111], v[112:113], off offset:528
	s_nop 0
	global_load_dwordx4 v[112:115], v[112:113], off offset:512
	s_nop 0
	global_load_dwordx4 v[196:199], v[144:145], off
	global_load_dwordx4 v[204:207], v[144:145], off offset:256
	v_or_b32_e32 v184, 16, v178
	v_ashrrev_i32_e32 v185, 31, v184
	v_lshlrev_b64 v[144:145], 12, v[184:185]
	v_lshl_add_u64 v[144:145], v[176:177], 0, v[144:145]
	global_load_dwordx4 v[208:211], v[144:145], off
	global_load_dwordx4 v[160:163], v[144:145], off offset:256
	v_or_b32_e32 v182, 32, v178
	v_ashrrev_i32_e32 v183, 31, v182
	v_lshlrev_b64 v[144:145], 12, v[182:183]
	v_lshl_add_u64 v[144:145], v[176:177], 0, v[144:145]
	global_load_dwordx4 v[156:159], v[144:145], off
	global_load_dwordx4 v[152:155], v[144:145], off offset:256
	v_or_b32_e32 v180, 48, v178
	v_ashrrev_i32_e32 v181, 31, v180
	v_lshlrev_b64 v[144:145], 12, v[180:181]
	v_lshl_add_u64 v[144:145], v[176:177], 0, v[144:145]
	global_load_dwordx4 v[148:151], v[144:145], off
	s_nop 0
	global_load_dwordx4 v[144:147], v[144:145], off offset:256
	v_readlane_b32 s52, v254, 39
	v_readlane_b32 s66, v254, 53
	v_readlane_b32 s67, v254, 54
	s_and_b64 vcc, exec, s[0:1]
	s_mov_b32 s38, s35
	s_mov_b32 s37, s36
	s_mov_b64 s[10:11], s[6:7]
	s_mov_b64 s[8:9], s[4:5]
	v_readlane_b32 s14, v254, 21
	s_movk_i32 s15, 0x2000
	v_readlane_b32 s53, v254, 40
	v_readlane_b32 s54, v254, 41
	v_readlane_b32 s55, v254, 42
	v_readlane_b32 s56, v254, 43
	v_readlane_b32 s57, v254, 44
	v_readlane_b32 s58, v254, 45
	v_readlane_b32 s59, v254, 46
	v_readlane_b32 s60, v254, 47
	v_readlane_b32 s61, v254, 48
	v_readlane_b32 s62, v254, 49
	v_readlane_b32 s63, v254, 50
	v_readlane_b32 s64, v254, 51
	v_readlane_b32 s65, v254, 52
	s_waitcnt vmcnt(0)
	v_lshlrev_b32_e32 v190, 16, v196
	v_and_b32_e32 v191, 0xffff0000, v196
	v_pk_fma_f32 v[140:141], v[140:141], v[120:121], v[190:191]
	v_lshlrev_b64 v[190:191], 13, v[178:179]
	v_lshlrev_b32_e32 v196, 16, v197
	v_and_b32_e32 v197, 0xffff0000, v197
	v_lshl_add_u64 v[190:191], s[66:67], 0, v[190:191]
	v_pk_fma_f32 v[142:143], v[142:143], v[122:123], v[196:197]
	v_lshl_add_u64 v[190:191], v[190:191], 0, v[174:175]
	global_store_dwordx4 v[190:191], v[140:143], off
	v_lshlrev_b32_e32 v214, 16, v198
	v_and_b32_e32 v215, 0xffff0000, v198
	v_lshlrev_b32_e32 v140, 16, v206
	v_and_b32_e32 v141, 0xffff0000, v206
	v_lshlrev_b32_e32 v142, 16, v207
	v_and_b32_e32 v143, 0xffff0000, v207
	v_pk_fma_f32 v[126:127], v[126:127], v[110:111], v[142:143]
	v_pk_fma_f32 v[124:125], v[124:125], v[108:109], v[140:141]
	global_store_dwordx4 v[190:191], v[124:127], off offset:528
	v_lshlrev_b32_e32 v198, 16, v199
	v_and_b32_e32 v199, 0xffff0000, v199
	v_lshlrev_b32_e32 v124, 16, v208
	v_and_b32_e32 v125, 0xffff0000, v208
	v_pk_fma_f32 v[124:125], v[132:133], v[120:121], v[124:125]
	v_lshlrev_b64 v[132:133], 13, v[184:185]
	v_lshlrev_b32_e32 v126, 16, v209
	v_and_b32_e32 v127, 0xffff0000, v209
	v_lshl_add_u64 v[132:133], s[66:67], 0, v[132:133]
	v_pk_fma_f32 v[126:127], v[134:135], v[122:123], v[126:127]
	v_lshl_add_u64 v[132:133], v[132:133], 0, v[174:175]
	v_pk_fma_f32 v[138:139], v[138:139], v[118:119], v[198:199]
	v_pk_fma_f32 v[136:137], v[136:137], v[116:117], v[214:215]
	global_store_dwordx4 v[132:133], v[124:127], off
	global_store_dwordx4 v[190:191], v[136:139], off offset:16
	s_nop 0
	v_lshlrev_b32_e32 v124, 16, v162
	v_and_b32_e32 v125, 0xffff0000, v162
	v_lshlrev_b32_e32 v126, 16, v163
	v_and_b32_e32 v127, 0xffff0000, v163
	v_lshlrev_b32_e32 v136, 16, v204
	v_and_b32_e32 v137, 0xffff0000, v204
	v_lshlrev_b32_e32 v138, 16, v205
	v_and_b32_e32 v139, 0xffff0000, v205
	v_pk_fma_f32 v[94:95], v[94:95], v[110:111], v[126:127]
	v_pk_fma_f32 v[92:93], v[92:93], v[108:109], v[124:125]
	v_pk_fma_f32 v[130:131], v[130:131], v[114:115], v[138:139]
	v_pk_fma_f32 v[128:129], v[128:129], v[112:113], v[136:137]
	global_store_dwordx4 v[132:133], v[92:95], off offset:528
	global_store_dwordx4 v[190:191], v[128:131], off offset:512
	s_nop 0
	v_lshlrev_b32_e32 v92, 16, v156
	v_and_b32_e32 v93, 0xffff0000, v156
	v_lshlrev_b32_e32 v128, 16, v210
	v_and_b32_e32 v129, 0xffff0000, v210
	v_lshlrev_b32_e32 v130, 16, v211
	v_and_b32_e32 v131, 0xffff0000, v211
	v_pk_fma_f32 v[92:93], v[96:97], v[120:121], v[92:93]
	v_lshlrev_b64 v[96:97], 13, v[182:183]
	v_pk_fma_f32 v[106:107], v[106:107], v[118:119], v[130:131]
	v_pk_fma_f32 v[104:105], v[104:105], v[116:117], v[128:129]
	v_lshlrev_b32_e32 v94, 16, v157
	v_and_b32_e32 v95, 0xffff0000, v157
	v_lshl_add_u64 v[96:97], s[66:67], 0, v[96:97]
	global_store_dwordx4 v[132:133], v[104:107], off offset:16
	v_pk_fma_f32 v[94:95], v[98:99], v[122:123], v[94:95]
	v_lshl_add_u64 v[96:97], v[96:97], 0, v[174:175]
	v_lshlrev_b32_e32 v104, 16, v160
	v_and_b32_e32 v105, 0xffff0000, v160
	v_lshlrev_b32_e32 v106, 16, v161
	v_and_b32_e32 v107, 0xffff0000, v161
	v_pk_fma_f32 v[102:103], v[102:103], v[114:115], v[106:107]
	v_pk_fma_f32 v[100:101], v[100:101], v[112:113], v[104:105]
	global_store_dwordx4 v[96:97], v[92:95], off
	global_store_dwordx4 v[132:133], v[100:103], off offset:512
	v_add_u32_e32 v98, 0x90, v178
	v_lshlrev_b32_e32 v92, 16, v154
	v_and_b32_e32 v93, 0xffff0000, v154
	v_lshlrev_b32_e32 v94, 16, v155
	v_and_b32_e32 v95, 0xffff0000, v155
	v_lshlrev_b32_e32 v100, 16, v158
	v_and_b32_e32 v101, 0xffff0000, v158
	v_lshlrev_b32_e32 v102, 16, v159
	v_and_b32_e32 v103, 0xffff0000, v159
	v_pk_fma_f32 v[78:79], v[78:79], v[110:111], v[94:95]
	v_pk_fma_f32 v[76:77], v[76:77], v[108:109], v[92:93]
	v_pk_fma_f32 v[90:91], v[90:91], v[118:119], v[102:103]
	v_pk_fma_f32 v[88:89], v[88:89], v[116:117], v[100:101]
	global_store_dwordx4 v[96:97], v[76:79], off offset:528
	global_store_dwordx4 v[96:97], v[88:91], off offset:16
	v_ashrrev_i32_e32 v99, 31, v98
	v_lshlrev_b32_e32 v76, 16, v148
	v_and_b32_e32 v77, 0xffff0000, v148
	v_lshlrev_b32_e32 v88, 16, v152
	v_and_b32_e32 v89, 0xffff0000, v152
	v_lshlrev_b32_e32 v90, 16, v153
	v_and_b32_e32 v91, 0xffff0000, v153
	v_pk_fma_f32 v[76:77], v[80:81], v[120:121], v[76:77]
	v_lshlrev_b64 v[80:81], 13, v[180:181]
	v_pk_fma_f32 v[86:87], v[86:87], v[114:115], v[90:91]
	v_pk_fma_f32 v[84:85], v[84:85], v[112:113], v[88:89]
	v_lshlrev_b32_e32 v78, 16, v149
	v_and_b32_e32 v79, 0xffff0000, v149
	v_lshl_add_u64 v[80:81], s[66:67], 0, v[80:81]
	global_store_dwordx4 v[96:97], v[84:87], off offset:512
	v_pk_fma_f32 v[78:79], v[82:83], v[122:123], v[78:79]
	v_lshl_add_u64 v[80:81], v[80:81], 0, v[174:175]
	v_lshlrev_b32_e32 v84, 16, v150
	v_and_b32_e32 v85, 0xffff0000, v150
	v_lshlrev_b32_e32 v86, 16, v151
	v_and_b32_e32 v87, 0xffff0000, v151
	global_store_dwordx4 v[80:81], v[76:79], off
	v_pk_fma_f32 v[74:75], v[74:75], v[118:119], v[86:87]
	v_pk_fma_f32 v[72:73], v[72:73], v[116:117], v[84:85]
	v_lshlrev_b32_e32 v76, 16, v146
	v_and_b32_e32 v77, 0xffff0000, v146
	v_lshlrev_b32_e32 v78, 16, v147
	v_and_b32_e32 v79, 0xffff0000, v147
	v_add_u32_e32 v96, 0x80, v178
	global_store_dwordx4 v[80:81], v[72:75], off offset:16
	v_pk_fma_f32 v[66:67], v[66:67], v[110:111], v[78:79]
	v_pk_fma_f32 v[64:65], v[64:65], v[108:109], v[76:77]
	v_lshlrev_b32_e32 v72, 16, v144
	v_and_b32_e32 v73, 0xffff0000, v144
	v_lshlrev_b32_e32 v74, 16, v145
	v_and_b32_e32 v75, 0xffff0000, v145
	v_ashrrev_i32_e32 v97, 31, v96
	v_pk_fma_f32 v[70:71], v[70:71], v[114:115], v[74:75]
	v_pk_fma_f32 v[68:69], v[68:69], v[112:113], v[72:73]
	global_store_dwordx4 v[80:81], v[64:67], off offset:528
	global_store_dwordx4 v[80:81], v[68:71], off offset:512
	v_add_u32_e32 v100, 0xa0, v178
	v_lshlrev_b64 v[64:65], 12, v[96:97]
	v_lshl_add_u64 v[64:65], v[176:177], 0, v[64:65]
	global_load_dwordx4 v[68:71], v[64:65], off
	global_load_dwordx4 v[72:75], v[64:65], off offset:256
	v_lshlrev_b64 v[64:65], 12, v[98:99]
	v_lshl_add_u64 v[64:65], v[176:177], 0, v[64:65]
	global_load_dwordx4 v[76:79], v[64:65], off
	global_load_dwordx4 v[80:83], v[64:65], off offset:256
	v_ashrrev_i32_e32 v101, 31, v100
	v_lshlrev_b64 v[64:65], 12, v[100:101]
	v_lshl_add_u64 v[64:65], v[176:177], 0, v[64:65]
	global_load_dwordx4 v[84:87], v[64:65], off
	global_load_dwordx4 v[88:91], v[64:65], off offset:256
	v_add_u32_e32 v102, 0xb0, v178
	v_ashrrev_i32_e32 v103, 31, v102
	v_lshlrev_b64 v[64:65], 12, v[102:103]
	v_lshl_add_u64 v[64:65], v[176:177], 0, v[64:65]
	global_load_dwordx4 v[92:95], v[64:65], off
	s_nop 0
	global_load_dwordx4 v[64:67], v[64:65], off offset:256
	s_waitcnt vmcnt(0)
	v_lshlrev_b32_e32 v104, 16, v68
	v_and_b32_e32 v105, 0xffff0000, v68
	v_lshlrev_b32_e32 v68, 16, v69
	v_and_b32_e32 v69, 0xffff0000, v69
	v_pk_fma_f32 v[62:63], v[62:63], v[122:123], v[68:69]
	v_lshlrev_b64 v[68:69], 13, v[96:97]
	v_lshl_add_u64 v[68:69], s[66:67], 0, v[68:69]
	v_pk_fma_f32 v[60:61], v[60:61], v[120:121], v[104:105]
	v_lshl_add_u64 v[68:69], v[68:69], 0, v[174:175]
	global_store_dwordx4 v[68:69], v[60:63], off
	v_lshlrev_b32_e32 v106, 16, v70
	v_and_b32_e32 v107, 0xffff0000, v70
	v_lshlrev_b32_e32 v60, 16, v74
	v_and_b32_e32 v61, 0xffff0000, v74
	v_lshlrev_b32_e32 v62, 16, v75
	v_and_b32_e32 v63, 0xffff0000, v75
	v_pk_fma_f32 v[46:47], v[46:47], v[110:111], v[62:63]
	v_pk_fma_f32 v[44:45], v[44:45], v[108:109], v[60:61]
	global_store_dwordx4 v[68:69], v[44:47], off offset:528
	v_lshlrev_b32_e32 v70, 16, v71
	v_and_b32_e32 v71, 0xffff0000, v71
	v_lshlrev_b32_e32 v44, 16, v76
	v_and_b32_e32 v45, 0xffff0000, v76
	v_pk_fma_f32 v[44:45], v[48:49], v[120:121], v[44:45]
	v_lshlrev_b64 v[48:49], 13, v[98:99]
	v_lshlrev_b32_e32 v46, 16, v77
	v_and_b32_e32 v47, 0xffff0000, v77
	v_lshl_add_u64 v[48:49], s[66:67], 0, v[48:49]
	v_pk_fma_f32 v[58:59], v[58:59], v[118:119], v[70:71]
	v_pk_fma_f32 v[56:57], v[56:57], v[116:117], v[106:107]
	v_pk_fma_f32 v[46:47], v[50:51], v[122:123], v[46:47]
	v_lshl_add_u64 v[48:49], v[48:49], 0, v[174:175]
	global_store_dwordx4 v[68:69], v[56:59], off offset:16
	global_store_dwordx4 v[48:49], v[44:47], off
	s_nop 0
	v_lshlrev_b32_e32 v56, 16, v72
	v_and_b32_e32 v57, 0xffff0000, v72
	v_lshlrev_b32_e32 v58, 16, v73
	v_and_b32_e32 v59, 0xffff0000, v73
	v_lshlrev_b32_e32 v44, 16, v82
	v_and_b32_e32 v45, 0xffff0000, v82
	v_lshlrev_b32_e32 v46, 16, v83
	v_and_b32_e32 v47, 0xffff0000, v83
	v_pk_fma_f32 v[54:55], v[54:55], v[114:115], v[58:59]
	v_pk_fma_f32 v[52:53], v[52:53], v[112:113], v[56:57]
	v_pk_fma_f32 v[30:31], v[30:31], v[110:111], v[46:47]
	v_pk_fma_f32 v[28:29], v[28:29], v[108:109], v[44:45]
	global_store_dwordx4 v[68:69], v[52:55], off offset:512
	global_store_dwordx4 v[48:49], v[28:31], off offset:528
	s_nop 0
	v_lshlrev_b32_e32 v52, 16, v78
	v_and_b32_e32 v53, 0xffff0000, v78
	v_lshlrev_b32_e32 v54, 16, v79
	v_and_b32_e32 v55, 0xffff0000, v79
	v_lshlrev_b32_e32 v28, 16, v84
	v_and_b32_e32 v29, 0xffff0000, v84
	v_pk_fma_f32 v[42:43], v[42:43], v[118:119], v[54:55]
	v_pk_fma_f32 v[40:41], v[40:41], v[116:117], v[52:53]
	v_pk_fma_f32 v[28:29], v[32:33], v[120:121], v[28:29]
	v_lshlrev_b64 v[32:33], 13, v[100:101]
	global_store_dwordx4 v[48:49], v[40:43], off offset:16
	v_lshlrev_b32_e32 v30, 16, v85
	v_and_b32_e32 v31, 0xffff0000, v85
	v_lshlrev_b32_e32 v40, 16, v80
	v_and_b32_e32 v41, 0xffff0000, v80
	v_lshlrev_b32_e32 v42, 16, v81
	v_and_b32_e32 v43, 0xffff0000, v81
	v_lshl_add_u64 v[32:33], s[66:67], 0, v[32:33]
	v_pk_fma_f32 v[38:39], v[38:39], v[114:115], v[42:43]
	v_pk_fma_f32 v[36:37], v[36:37], v[112:113], v[40:41]
	v_pk_fma_f32 v[30:31], v[34:35], v[122:123], v[30:31]
	v_lshl_add_u64 v[32:33], v[32:33], 0, v[174:175]
	global_store_dwordx4 v[48:49], v[36:39], off offset:512
	global_store_dwordx4 v[32:33], v[28:31], off
	s_nop 0
	v_lshlrev_b32_e32 v36, 16, v86
	v_and_b32_e32 v37, 0xffff0000, v86
	v_lshlrev_b32_e32 v38, 16, v87
	v_and_b32_e32 v39, 0xffff0000, v87
	v_lshlrev_b32_e32 v28, 16, v90
	v_and_b32_e32 v29, 0xffff0000, v90
	v_lshlrev_b32_e32 v30, 16, v91
	v_and_b32_e32 v31, 0xffff0000, v91
	v_pk_fma_f32 v[26:27], v[26:27], v[118:119], v[38:39]
	v_pk_fma_f32 v[24:25], v[24:25], v[116:117], v[36:37]
	v_pk_fma_f32 v[14:15], v[14:15], v[110:111], v[30:31]
	v_pk_fma_f32 v[12:13], v[12:13], v[108:109], v[28:29]
	global_store_dwordx4 v[32:33], v[24:27], off offset:16
	global_store_dwordx4 v[32:33], v[12:15], off offset:528
	s_nop 0
	v_lshlrev_b32_e32 v24, 16, v88
	v_and_b32_e32 v25, 0xffff0000, v88
	v_lshlrev_b32_e32 v26, 16, v89
	v_and_b32_e32 v27, 0xffff0000, v89
	v_lshlrev_b32_e32 v12, 16, v92
	v_and_b32_e32 v13, 0xffff0000, v92
	v_pk_fma_f32 v[22:23], v[22:23], v[114:115], v[26:27]
	v_pk_fma_f32 v[20:21], v[20:21], v[112:113], v[24:25]
	v_pk_fma_f32 v[12:13], v[16:17], v[120:121], v[12:13]
	v_lshlrev_b64 v[16:17], 13, v[102:103]
	global_store_dwordx4 v[32:33], v[20:23], off offset:512
	v_lshlrev_b32_e32 v14, 16, v93
	v_and_b32_e32 v15, 0xffff0000, v93
	v_lshlrev_b32_e32 v20, 16, v94
	v_and_b32_e32 v21, 0xffff0000, v94
	v_lshlrev_b32_e32 v22, 16, v95
	v_and_b32_e32 v23, 0xffff0000, v95
	v_lshl_add_u64 v[16:17], s[66:67], 0, v[16:17]
	v_pk_fma_f32 v[14:15], v[18:19], v[122:123], v[14:15]
	v_lshl_add_u64 v[16:17], v[16:17], 0, v[174:175]
	v_pk_fma_f32 v[10:11], v[10:11], v[118:119], v[22:23]
	v_pk_fma_f32 v[8:9], v[8:9], v[116:117], v[20:21]
	global_store_dwordx4 v[16:17], v[12:15], off
	global_store_dwordx4 v[16:17], v[8:11], off offset:16
	s_nop 0
	v_lshlrev_b32_e32 v12, 16, v66
	v_lshlrev_b32_e32 v8, 16, v64
	v_and_b32_e32 v9, 0xffff0000, v64
	v_lshlrev_b32_e32 v10, 16, v65
	v_and_b32_e32 v11, 0xffff0000, v65
	v_and_b32_e32 v13, 0xffff0000, v66
	v_lshlrev_b32_e32 v14, 16, v67
	v_and_b32_e32 v15, 0xffff0000, v67
	v_pk_fma_f32 v[6:7], v[6:7], v[114:115], v[10:11]
	v_pk_fma_f32 v[4:5], v[4:5], v[112:113], v[8:9]
	v_pk_fma_f32 v[2:3], v[2:3], v[110:111], v[14:15]
	v_pk_fma_f32 v[0:1], v[0:1], v[108:109], v[12:13]
	global_store_dwordx4 v[16:17], v[4:7], off offset:512
	global_store_dwordx4 v[16:17], v[0:3], off offset:528
	s_cbranch_vccz .LBB0_261
	s_waitcnt vmcnt(0)
	s_cmpk_gt_u32 s16, 0xff
	s_cbranch_scc1 .LBB0_276
	s_barrier

.LBB0_294:
	ds_read_b128 v[64:67], v220 offset:0
	ds_read_b128 v[68:71], v220 offset:1024
	ds_read_b128 v[72:75], v220 offset:2048
	ds_read_b128 v[76:79], v220 offset:3072
	ds_read_b128 v[154:157], v161
	ds_read_b128 v[162:165], v161 offset:1024
	ds_read_b128 v[166:169], v161 offset:2048
	ds_read_b128 v[170:173], v161 offset:3072
	ds_read_b128 v[174:177], v161 offset:4096
	ds_read_b128 v[178:181], v161 offset:5120
	ds_read_b128 v[182:185], v161 offset:6144
	ds_read_b128 v[186:189], v161 offset:7168
	global_load_lds_dwordx4 v150, s[14:15]
	s_add_i32 m0, s13, 0xe000
	s_nop 0
	global_load_lds_dwordx4 v152, s[14:15]
	s_waitcnt lgkmcnt(8)
	s_barrier
	s_waitcnt lgkmcnt(0)
	v_mfma_f32_16x16x32_bf16 v[140:143], v[64:67], v[154:157], v[140:143]
	v_mfma_f32_16x16x32_bf16 v[136:139], v[72:75], v[154:157], v[136:139]
	v_mfma_f32_16x16x32_bf16 v[132:135], v[64:67], v[166:169], v[132:135]
	v_mfma_f32_16x16x32_bf16 v[128:131], v[72:75], v[166:169], v[128:131]
	s_add_i32 s46, 0, 0x14000
	s_add_i32 s43, s43, s27
	v_mfma_f32_16x16x32_bf16 v[108:111], v[64:67], v[174:177], v[108:111]
	s_mov_b32 m0, s43
	v_mfma_f32_16x16x32_bf16 v[104:107], v[72:75], v[174:177], v[104:107]
	v_mfma_f32_16x16x32_bf16 v[100:103], v[64:67], v[182:185], v[100:103]
	v_mfma_f32_16x16x32_bf16 v[96:99], v[72:75], v[182:185], v[96:99]
	v_mfma_f32_16x16x32_bf16 v[140:143], v[68:71], v[162:165], v[140:143]
	v_mfma_f32_16x16x32_bf16 v[136:139], v[76:79], v[162:165], v[136:139]
	v_mfma_f32_16x16x32_bf16 v[132:135], v[68:71], v[170:173], v[132:135]
	v_mfma_f32_16x16x32_bf16 v[128:131], v[76:79], v[170:173], v[128:131]
	v_mfma_f32_16x16x32_bf16 v[108:111], v[68:71], v[178:181], v[108:111]
	v_mfma_f32_16x16x32_bf16 v[104:107], v[76:79], v[178:181], v[104:107]
	v_mfma_f32_16x16x32_bf16 v[100:103], v[68:71], v[186:189], v[100:103]
	v_mfma_f32_16x16x32_bf16 v[96:99], v[76:79], v[186:189], v[96:99]
	s_barrier
	ds_read_b128 v[196:199], v220 offset:16384
	ds_read_b128 v[204:207], v220 offset:17408
	ds_read_b128 v[208:211], v220 offset:18432
	ds_read_b128 v[214:217], v220 offset:19456
	global_load_lds_dwordx4 v192, s[16:17]
	s_add_i32 m0, s43, 0x2000
	s_nop 0
	global_load_lds_dwordx4 v148, s[16:17]
	s_barrier
	s_waitcnt lgkmcnt(0)
	v_mfma_f32_16x16x32_bf16 v[124:127], v[196:199], v[154:157], v[124:127]
	v_mfma_f32_16x16x32_bf16 v[120:123], v[208:211], v[154:157], v[120:123]
	v_mfma_f32_16x16x32_bf16 v[116:119], v[196:199], v[166:169], v[116:119]
	v_mfma_f32_16x16x32_bf16 v[112:115], v[208:211], v[166:169], v[112:115]
	s_mov_b32 m0, s13
	v_mfma_f32_16x16x32_bf16 v[92:95], v[196:199], v[174:177], v[92:95]
	s_add_u32 s48, s18, 0x80
	s_addc_u32 s49, s19, 0
	v_mfma_f32_16x16x32_bf16 v[88:91], v[208:211], v[174:177], v[88:91]
	v_mfma_f32_16x16x32_bf16 v[84:87], v[196:199], v[182:185], v[84:87]
	v_mfma_f32_16x16x32_bf16 v[80:83], v[208:211], v[182:185], v[80:83]
	v_mfma_f32_16x16x32_bf16 v[124:127], v[204:207], v[162:165], v[124:127]
	v_mfma_f32_16x16x32_bf16 v[120:123], v[214:217], v[162:165], v[120:123]
	v_mfma_f32_16x16x32_bf16 v[116:119], v[204:207], v[170:173], v[116:119]
	v_mfma_f32_16x16x32_bf16 v[112:115], v[214:217], v[170:173], v[112:115]
	v_mfma_f32_16x16x32_bf16 v[92:95], v[204:207], v[178:181], v[92:95]
	v_mfma_f32_16x16x32_bf16 v[88:91], v[214:217], v[178:181], v[88:91]
	v_mfma_f32_16x16x32_bf16 v[84:87], v[204:207], v[186:189], v[84:87]
	v_mfma_f32_16x16x32_bf16 v[80:83], v[214:217], v[186:189], v[80:83]
	s_barrier
	ds_read_b128 v[154:157], v161 offset:16384
	ds_read_b128 v[162:165], v161 offset:17408
	ds_read_b128 v[166:169], v161 offset:18432
	ds_read_b128 v[170:173], v161 offset:19456
	ds_read_b128 v[174:177], v161 offset:20480
	ds_read_b128 v[178:181], v161 offset:21504
	ds_read_b128 v[182:185], v161 offset:22528
	ds_read_b128 v[186:189], v161 offset:23552
	global_load_lds_dwordx4 v144, s[18:19]
	s_mov_b32 m0, s28
	s_nop 0
	global_load_lds_dwordx4 v146, s[18:19]
	s_barrier
	s_waitcnt lgkmcnt(0)
	v_mfma_f32_16x16x32_bf16 v[60:63], v[64:67], v[154:157], v[60:63]
	v_mfma_f32_16x16x32_bf16 v[56:59], v[72:75], v[154:157], v[56:59]
	v_mfma_f32_16x16x32_bf16 v[52:55], v[64:67], v[166:169], v[52:55]
	v_mfma_f32_16x16x32_bf16 v[48:51], v[72:75], v[166:169], v[48:51]
	s_add_u32 s44, s16, 0x80000
	s_addc_u32 s45, s17, 0
	v_mfma_f32_16x16x32_bf16 v[28:31], v[64:67], v[174:177], v[28:31]
	s_add_i32 s43, s46, s27
	s_mov_b32 m0, s43
	v_mfma_f32_16x16x32_bf16 v[24:27], v[72:75], v[174:177], v[24:27]
	v_mfma_f32_16x16x32_bf16 v[20:23], v[64:67], v[182:185], v[20:23]
	v_mfma_f32_16x16x32_bf16 v[16:19], v[72:75], v[182:185], v[16:19]
	v_mfma_f32_16x16x32_bf16 v[60:63], v[68:71], v[162:165], v[60:63]
	v_mfma_f32_16x16x32_bf16 v[56:59], v[76:79], v[162:165], v[56:59]
	v_mfma_f32_16x16x32_bf16 v[52:55], v[68:71], v[170:173], v[52:55]
	v_mfma_f32_16x16x32_bf16 v[48:51], v[76:79], v[170:173], v[48:51]
	v_mfma_f32_16x16x32_bf16 v[28:31], v[68:71], v[178:181], v[28:31]
	v_mfma_f32_16x16x32_bf16 v[24:27], v[76:79], v[178:181], v[24:27]
	v_mfma_f32_16x16x32_bf16 v[20:23], v[68:71], v[186:189], v[20:23]
	v_mfma_f32_16x16x32_bf16 v[16:19], v[76:79], v[186:189], v[16:19]
	s_barrier
	global_load_lds_dwordx4 v192, s[44:45]
	s_add_i32 m0, s43, 0x2000
	s_nop 0
	global_load_lds_dwordx4 v148, s[44:45]
	s_waitcnt vmcnt(6)
	s_barrier
	v_mfma_f32_16x16x32_bf16 v[44:47], v[196:199], v[154:157], v[44:47]
	v_mfma_f32_16x16x32_bf16 v[40:43], v[208:211], v[154:157], v[40:43]
	v_mfma_f32_16x16x32_bf16 v[36:39], v[196:199], v[166:169], v[36:39]
	v_mfma_f32_16x16x32_bf16 v[32:35], v[208:211], v[166:169], v[32:35]
	s_add_i32 s43, 0, 0x18000
	v_mfma_f32_16x16x32_bf16 v[12:15], v[196:199], v[174:177], v[12:15]
	s_add_u32 s18, s18, 0x80000
	s_addc_u32 s19, s19, 0
	v_mfma_f32_16x16x32_bf16 v[8:11], v[208:211], v[174:177], v[8:11]
	s_mov_b32 m0, s29
	v_mfma_f32_16x16x32_bf16 v[4:7], v[196:199], v[182:185], v[4:7]
	v_mfma_f32_16x16x32_bf16 v[0:3], v[208:211], v[182:185], v[0:3]
	v_mfma_f32_16x16x32_bf16 v[44:47], v[204:207], v[162:165], v[44:47]
	v_mfma_f32_16x16x32_bf16 v[40:43], v[214:217], v[162:165], v[40:43]
	v_mfma_f32_16x16x32_bf16 v[36:39], v[204:207], v[170:173], v[36:39]
	v_mfma_f32_16x16x32_bf16 v[32:35], v[214:217], v[170:173], v[32:35]
	v_mfma_f32_16x16x32_bf16 v[12:15], v[204:207], v[178:181], v[12:15]
	v_mfma_f32_16x16x32_bf16 v[8:11], v[214:217], v[178:181], v[8:11]
	v_mfma_f32_16x16x32_bf16 v[4:7], v[204:207], v[186:189], v[4:7]
	v_mfma_f32_16x16x32_bf16 v[0:3], v[214:217], v[186:189], v[0:3]
	s_barrier
	ds_read_b128 v[64:67], v220 offset:32768
	ds_read_b128 v[68:71], v220 offset:33792
	ds_read_b128 v[72:75], v220 offset:34816
	ds_read_b128 v[76:79], v220 offset:35840
	ds_read_b128 v[154:157], v161 offset:32768
	ds_read_b128 v[162:165], v161 offset:33792
	ds_read_b128 v[166:169], v161 offset:34816
	ds_read_b128 v[170:173], v161 offset:35840
	ds_read_b128 v[174:177], v161 offset:36864
	ds_read_b128 v[178:181], v161 offset:37888
	ds_read_b128 v[182:185], v161 offset:38912
	ds_read_b128 v[186:189], v161 offset:39936
	global_load_lds_dwordx4 v144, s[18:19]
	s_mov_b32 m0, s30
	s_nop 0
	global_load_lds_dwordx4 v146, s[18:19]
	s_waitcnt lgkmcnt(8)
	s_barrier
	s_waitcnt lgkmcnt(0)
	v_mfma_f32_16x16x32_bf16 v[140:143], v[64:67], v[154:157], v[140:143]
	v_mfma_f32_16x16x32_bf16 v[136:139], v[72:75], v[154:157], v[136:139]
	v_mfma_f32_16x16x32_bf16 v[132:135], v[64:67], v[166:169], v[132:135]
	v_mfma_f32_16x16x32_bf16 v[128:131], v[72:75], v[166:169], v[128:131]
	s_add_i32 s18, 0, 0x1c000
	s_add_i32 s19, s43, s27
	v_mfma_f32_16x16x32_bf16 v[108:111], v[64:67], v[174:177], v[108:111]
	s_add_i32 m0, s19, 0xffffff80
	v_mfma_f32_16x16x32_bf16 v[104:107], v[72:75], v[174:177], v[104:107]
	v_mfma_f32_16x16x32_bf16 v[100:103], v[64:67], v[182:185], v[100:103]
	v_mfma_f32_16x16x32_bf16 v[96:99], v[72:75], v[182:185], v[96:99]
	v_mfma_f32_16x16x32_bf16 v[140:143], v[68:71], v[162:165], v[140:143]
	v_mfma_f32_16x16x32_bf16 v[136:139], v[76:79], v[162:165], v[136:139]
	v_mfma_f32_16x16x32_bf16 v[132:135], v[68:71], v[170:173], v[132:135]
	v_mfma_f32_16x16x32_bf16 v[128:131], v[76:79], v[170:173], v[128:131]
	v_mfma_f32_16x16x32_bf16 v[108:111], v[68:71], v[178:181], v[108:111]
	v_mfma_f32_16x16x32_bf16 v[104:107], v[76:79], v[178:181], v[104:107]
	v_mfma_f32_16x16x32_bf16 v[100:103], v[68:71], v[186:189], v[100:103]
	v_mfma_f32_16x16x32_bf16 v[96:99], v[76:79], v[186:189], v[96:99]
	s_barrier
	ds_read_b128 v[196:199], v220 offset:49152
	ds_read_b128 v[204:207], v220 offset:50176
	ds_read_b128 v[208:211], v220 offset:51200
	ds_read_b128 v[214:217], v220 offset:52224
	global_load_lds_dwordx4 v192, s[16:17] offset:128
	s_add_i32 m0, s19, 0x1f80
	s_nop 0
	global_load_lds_dwordx4 v148, s[16:17] offset:128
	s_barrier
	s_waitcnt lgkmcnt(0)
	v_mfma_f32_16x16x32_bf16 v[124:127], v[196:199], v[154:157], v[124:127]
	v_mfma_f32_16x16x32_bf16 v[120:123], v[208:211], v[154:157], v[120:123]
	v_mfma_f32_16x16x32_bf16 v[116:119], v[196:199], v[166:169], v[116:119]
	v_mfma_f32_16x16x32_bf16 v[112:115], v[208:211], v[166:169], v[112:115]
	s_mov_b32 m0, s34
	v_mfma_f32_16x16x32_bf16 v[92:95], v[196:199], v[174:177], v[92:95]
	v_mfma_f32_16x16x32_bf16 v[88:91], v[208:211], v[174:177], v[88:91]
	v_mfma_f32_16x16x32_bf16 v[84:87], v[196:199], v[182:185], v[84:87]
	v_mfma_f32_16x16x32_bf16 v[80:83], v[208:211], v[182:185], v[80:83]
	v_mfma_f32_16x16x32_bf16 v[124:127], v[204:207], v[162:165], v[124:127]
	v_mfma_f32_16x16x32_bf16 v[120:123], v[214:217], v[162:165], v[120:123]
	v_mfma_f32_16x16x32_bf16 v[116:119], v[204:207], v[170:173], v[116:119]
	v_mfma_f32_16x16x32_bf16 v[112:115], v[214:217], v[170:173], v[112:115]
	v_mfma_f32_16x16x32_bf16 v[92:95], v[204:207], v[178:181], v[92:95]
	v_mfma_f32_16x16x32_bf16 v[88:91], v[214:217], v[178:181], v[88:91]
	v_mfma_f32_16x16x32_bf16 v[84:87], v[204:207], v[186:189], v[84:87]
	v_mfma_f32_16x16x32_bf16 v[80:83], v[214:217], v[186:189], v[80:83]
	s_barrier
	ds_read_b128 v[154:157], v161 offset:49152
	ds_read_b128 v[162:165], v161 offset:50176
	ds_read_b128 v[166:169], v161 offset:51200
	ds_read_b128 v[170:173], v161 offset:52224
	ds_read_b128 v[174:177], v161 offset:53248
	ds_read_b128 v[178:181], v161 offset:54272
	ds_read_b128 v[182:185], v161 offset:55296
	ds_read_b128 v[186:189], v161 offset:56320
	global_load_lds_dwordx4 v144, s[48:49]
	s_mov_b32 m0, s35
	s_nop 0
	global_load_lds_dwordx4 v146, s[48:49]
	s_barrier
	s_waitcnt lgkmcnt(0)
	v_mfma_f32_16x16x32_bf16 v[60:63], v[64:67], v[154:157], v[60:63]
	v_mfma_f32_16x16x32_bf16 v[56:59], v[72:75], v[154:157], v[56:59]
	v_mfma_f32_16x16x32_bf16 v[52:55], v[64:67], v[166:169], v[52:55]
	v_mfma_f32_16x16x32_bf16 v[48:51], v[72:75], v[166:169], v[48:51]
	s_add_u32 s16, s16, 0x80080
	s_addc_u32 s17, s17, 0
	v_mfma_f32_16x16x32_bf16 v[28:31], v[64:67], v[174:177], v[28:31]
	s_add_i32 s18, s18, s27
	s_mov_b32 m0, s18
	v_mfma_f32_16x16x32_bf16 v[24:27], v[72:75], v[174:177], v[24:27]
	v_mfma_f32_16x16x32_bf16 v[20:23], v[64:67], v[182:185], v[20:23]
	v_mfma_f32_16x16x32_bf16 v[16:19], v[72:75], v[182:185], v[16:19]
	v_mfma_f32_16x16x32_bf16 v[60:63], v[68:71], v[162:165], v[60:63]
	v_mfma_f32_16x16x32_bf16 v[56:59], v[76:79], v[162:165], v[56:59]
	v_mfma_f32_16x16x32_bf16 v[52:55], v[68:71], v[170:173], v[52:55]
	v_mfma_f32_16x16x32_bf16 v[48:51], v[76:79], v[170:173], v[48:51]
	v_mfma_f32_16x16x32_bf16 v[28:31], v[68:71], v[178:181], v[28:31]
	v_mfma_f32_16x16x32_bf16 v[24:27], v[76:79], v[178:181], v[24:27]
	v_mfma_f32_16x16x32_bf16 v[20:23], v[68:71], v[186:189], v[20:23]
	v_mfma_f32_16x16x32_bf16 v[16:19], v[76:79], v[186:189], v[16:19]
	s_barrier
	global_load_lds_dwordx4 v192, s[16:17]
	s_add_i32 m0, s18, 0x2000
	s_nop 0
	global_load_lds_dwordx4 v148, s[16:17]
	s_waitcnt vmcnt(6)
	s_barrier
	v_mfma_f32_16x16x32_bf16 v[44:47], v[196:199], v[154:157], v[44:47]
	v_mfma_f32_16x16x32_bf16 v[40:43], v[208:211], v[154:157], v[40:43]
	v_mfma_f32_16x16x32_bf16 v[36:39], v[196:199], v[166:169], v[36:39]
	v_mfma_f32_16x16x32_bf16 v[32:35], v[208:211], v[166:169], v[32:35]
	s_add_i32 s42, s42, 2
	v_mfma_f32_16x16x32_bf16 v[12:15], v[196:199], v[174:177], v[12:15]
	s_add_u32 s14, s14, 0x100
	s_addc_u32 s15, s15, 0
	v_mfma_f32_16x16x32_bf16 v[8:11], v[208:211], v[174:177], v[8:11]
	s_add_u32 s40, s40, 0x100
	s_addc_u32 s41, s41, 0
	v_mfma_f32_16x16x32_bf16 v[4:7], v[196:199], v[182:185], v[4:7]
	s_add_u32 s16, s14, 0xfff80080
	s_addc_u32 s17, s15, -1
	v_mfma_f32_16x16x32_bf16 v[0:3], v[208:211], v[182:185], v[0:3]
	s_add_i32 s43, 0, 0x10000
	s_cmp_eq_u32 s42, 28
	v_mfma_f32_16x16x32_bf16 v[44:47], v[204:207], v[162:165], v[44:47]
	s_cselect_b32 s19, s7, s17
	s_cselect_b32 s18, s38, s16
	v_mfma_f32_16x16x32_bf16 v[40:43], v[214:217], v[162:165], v[40:43]
	s_cselect_b32 s17, s5, s41
	s_cselect_b32 s16, s39, s40
	v_mfma_f32_16x16x32_bf16 v[36:39], v[204:207], v[170:173], v[36:39]
	s_add_i32 m0, s13, 0xc000
	v_mfma_f32_16x16x32_bf16 v[32:35], v[214:217], v[170:173], v[32:35]
	v_mfma_f32_16x16x32_bf16 v[12:15], v[204:207], v[178:181], v[12:15]
	v_mfma_f32_16x16x32_bf16 v[8:11], v[214:217], v[178:181], v[8:11]
	v_mfma_f32_16x16x32_bf16 v[4:7], v[204:207], v[186:189], v[4:7]
	v_mfma_f32_16x16x32_bf16 v[0:3], v[214:217], v[186:189], v[0:3]
	s_cmp_gt_u32 s42, 29
	s_cbranch_scc0 .Lrot_294
	s_barrier
	s_ashr_i32 s5, s12, 4
	v_lshl_or_b32 v190, s37, 8, v160
	s_mul_hi_i32 s7, s5, 0xc000
	s_mul_i32 s5, s5, 0xc000
	s_add_u32 s14, s31, s5
	v_ashrrev_i32_e32 v191, 31, v190
	v_lshl_add_u32 v154, s12, 8, v158
	v_readlane_b32 s52, v254, 23
	s_addc_u32 s15, s33, s7
	v_lshlrev_b64 v[156:157], 2, v[190:191]
	v_readlane_b32 s53, v254, 24
	v_ashrrev_i32_e32 v155, 31, v154
	v_lshl_add_u64 v[68:69], s[14:15], 0, v[156:157]
	v_lshl_add_u64 v[156:157], s[52:53], 0, v[156:157]
	v_lshlrev_b64 v[162:163], 13, v[154:155]
	v_lshl_add_u64 v[174:175], v[156:157], 0, v[162:163]
	global_load_dwordx4 v[72:75], v[68:69], off offset:16
	global_load_dwordx4 v[76:79], v[68:69], off
	global_load_dwordx4 v[64:67], v[68:69], off offset:528
	s_nop 0
	global_load_dwordx4 v[68:71], v[68:69], off offset:512
	s_nop 0
	global_load_dwordx4 v[162:165], v[174:175], off offset:16
	global_load_dwordx4 v[166:169], v[174:175], off
	global_load_dwordx4 v[170:173], v[174:175], off offset:528
	s_nop 0
	global_load_dwordx4 v[174:177], v[174:175], off offset:512
	v_or_b32_e32 v204, 16, v154
	v_ashrrev_i32_e32 v205, 31, v204
	v_lshlrev_b64 v[178:179], 13, v[204:205]
	v_lshl_add_u64 v[196:197], v[156:157], 0, v[178:179]
	global_load_dwordx4 v[178:181], v[196:197], off offset:16
	global_load_dwordx4 v[182:185], v[196:197], off
	global_load_dwordx4 v[186:189], v[196:197], off offset:528
	s_nop 0
	global_load_dwordx4 v[196:199], v[196:197], off offset:512
	v_lshlrev_b64 v[206:207], 12, v[154:155]
	s_and_b64 vcc, exec, s[0:1]
	s_mov_b32 s37, s4
	s_mov_b32 s12, s6
	s_mov_b64 s[16:17], s[10:11]
	s_mov_b64 s[14:15], s[8:9]
	s_mov_b32 s11, 0xc000
	v_readlane_b32 s54, v254, 25
	v_readlane_b32 s55, v254, 26
	v_readlane_b32 s56, v254, 27
	v_readlane_b32 s57, v254, 28
	v_readlane_b32 s58, v254, 29
	v_readlane_b32 s59, v254, 30
	v_readlane_b32 s60, v254, 31
	v_readlane_b32 s61, v254, 32
	v_readlane_b32 s62, v254, 33
	v_readlane_b32 s63, v254, 34
	v_readlane_b32 s64, v254, 35
	v_readlane_b32 s65, v254, 36
	v_readlane_b32 s66, v254, 37
	v_readlane_b32 s67, v254, 38
	s_waitcnt vmcnt(0)
	v_pk_fma_f32 v[136:137], v[136:137], v[72:73], v[162:163]
	v_pk_fma_f32 v[142:143], v[142:143], v[78:79], v[168:169]
	v_pk_fma_f32 v[140:141], v[140:141], v[76:77], v[166:167]
	v_pk_fma_f32 v[164:165], v[138:139], v[74:75], v[164:165]
	v_cvt_pk_bf16_f32 v138, v140, v141
	v_cvt_pk_bf16_f32 v139, v142, v143
	v_cvt_pk_bf16_f32 v140, v136, v137
	v_lshl_add_u64 v[142:143], s[2:3], 0, v[206:207]
	v_lshlrev_b64 v[136:137], 1, v[190:191]
	v_lshl_add_u64 v[142:143], v[142:143], 0, v[136:137]
	v_pk_fma_f32 v[124:125], v[124:125], v[68:69], v[174:175]
	v_cvt_pk_bf16_f32 v141, v164, v165
	global_store_dwordx4 v[142:143], v[138:141], off
	v_pk_fma_f32 v[126:127], v[126:127], v[70:71], v[176:177]
	v_pk_fma_f32 v[128:129], v[128:129], v[72:73], v[178:179]
	v_pk_fma_f32 v[138:139], v[122:123], v[66:67], v[172:173]
	v_pk_fma_f32 v[122:123], v[120:121], v[64:65], v[170:171]
	v_cvt_pk_bf16_f32 v120, v124, v125
	v_cvt_pk_bf16_f32 v121, v126, v127
	v_lshlrev_b64 v[124:125], 12, v[204:205]
	v_cvt_pk_bf16_f32 v122, v122, v123
	v_cvt_pk_bf16_f32 v123, v138, v139
	global_store_dwordx4 v[142:143], v[120:123], off offset:256
	v_lshl_add_u64 v[124:125], s[2:3], 0, v[124:125]
	v_lshl_add_u64 v[124:125], v[124:125], 0, v[136:137]
	v_pk_fma_f32 v[120:121], v[132:133], v[76:77], v[182:183]
	v_pk_fma_f32 v[122:123], v[134:135], v[78:79], v[184:185]
	v_cvt_pk_bf16_f32 v120, v120, v121
	v_or_b32_e32 v142, 32, v154
	v_cvt_pk_bf16_f32 v121, v122, v123
	v_pk_fma_f32 v[126:127], v[130:131], v[74:75], v[180:181]
	v_cvt_pk_bf16_f32 v122, v128, v129
	v_pk_fma_f32 v[118:119], v[118:119], v[70:71], v[198:199]
	v_cvt_pk_bf16_f32 v123, v126, v127
	global_store_dwordx4 v[124:125], v[120:123], off
	v_pk_fma_f32 v[116:117], v[116:117], v[68:69], v[196:197]
	v_ashrrev_i32_e32 v143, 31, v142
	v_pk_fma_f32 v[120:121], v[114:115], v[66:67], v[188:189]
	v_pk_fma_f32 v[114:115], v[112:113], v[64:65], v[186:187]
	v_cvt_pk_bf16_f32 v112, v116, v117
	v_cvt_pk_bf16_f32 v113, v118, v119
	v_or_b32_e32 v166, 48, v154
	v_cvt_pk_bf16_f32 v114, v114, v115
	v_cvt_pk_bf16_f32 v115, v120, v121
	global_store_dwordx4 v[124:125], v[112:115], off offset:256
	v_ashrrev_i32_e32 v167, 31, v166
	v_lshlrev_b64 v[128:129], 13, v[166:167]
	v_lshlrev_b64 v[112:113], 13, v[142:143]
	v_lshl_add_u64 v[124:125], v[156:157], 0, v[112:113]
	global_load_dwordx4 v[112:115], v[124:125], off offset:16
	global_load_dwordx4 v[116:119], v[124:125], off
	global_load_dwordx4 v[120:123], v[124:125], off offset:528
	s_nop 0
	global_load_dwordx4 v[124:127], v[124:125], off offset:512
	v_lshl_add_u64 v[162:163], v[156:157], 0, v[128:129]
	global_load_dwordx4 v[128:131], v[162:163], off offset:16
	global_load_dwordx4 v[132:135], v[162:163], off
	global_load_dwordx4 v[138:141], v[162:163], off offset:528
	s_nop 0
	global_load_dwordx4 v[162:165], v[162:163], off offset:512
	v_lshlrev_b64 v[142:143], 12, v[142:143]
	s_waitcnt vmcnt(0)
	v_pk_fma_f32 v[114:115], v[106:107], v[74:75], v[114:115]
	v_pk_fma_f32 v[108:109], v[108:109], v[76:77], v[116:117]
	v_pk_fma_f32 v[106:107], v[104:105], v[72:73], v[112:113]
	v_cvt_pk_bf16_f32 v104, v108, v109
	v_lshl_add_u64 v[108:109], s[2:3], 0, v[142:143]
	v_pk_fma_f32 v[110:111], v[110:111], v[78:79], v[118:119]
	v_lshl_add_u64 v[108:109], v[108:109], 0, v[136:137]
	v_cvt_pk_bf16_f32 v105, v110, v111
	v_pk_fma_f32 v[92:93], v[92:93], v[68:69], v[124:125]
	v_cvt_pk_bf16_f32 v106, v106, v107
	v_cvt_pk_bf16_f32 v107, v114, v115
	global_store_dwordx4 v[108:109], v[104:107], off
	v_pk_fma_f32 v[94:95], v[94:95], v[70:71], v[126:127]
	v_add_u32_e32 v112, 0x80, v154
	v_pk_fma_f32 v[104:105], v[90:91], v[66:67], v[122:123]
	v_pk_fma_f32 v[90:91], v[88:89], v[64:65], v[120:121]
	v_cvt_pk_bf16_f32 v88, v92, v93
	v_cvt_pk_bf16_f32 v89, v94, v95
	v_lshlrev_b64 v[92:93], 12, v[166:167]
	v_cvt_pk_bf16_f32 v90, v90, v91
	v_cvt_pk_bf16_f32 v91, v104, v105
	global_store_dwordx4 v[108:109], v[88:91], off offset:256
	v_lshl_add_u64 v[92:93], s[2:3], 0, v[92:93]
	v_lshl_add_u64 v[92:93], v[92:93], 0, v[136:137]
	v_pk_fma_f32 v[88:89], v[100:101], v[76:77], v[132:133]
	v_pk_fma_f32 v[90:91], v[102:103], v[78:79], v[134:135]
	v_cvt_pk_bf16_f32 v88, v88, v89
	v_pk_fma_f32 v[94:95], v[98:99], v[74:75], v[130:131]
	v_cvt_pk_bf16_f32 v89, v90, v91
	v_pk_fma_f32 v[96:97], v[96:97], v[72:73], v[128:129]
	v_pk_fma_f32 v[86:87], v[86:87], v[70:71], v[164:165]
	v_cvt_pk_bf16_f32 v90, v96, v97
	v_cvt_pk_bf16_f32 v91, v94, v95
	global_store_dwordx4 v[92:93], v[88:91], off
	v_pk_fma_f32 v[84:85], v[84:85], v[68:69], v[162:163]
	v_ashrrev_i32_e32 v113, 31, v112
	v_pk_fma_f32 v[88:89], v[82:83], v[66:67], v[140:141]
	v_pk_fma_f32 v[82:83], v[80:81], v[64:65], v[138:139]
	v_cvt_pk_bf16_f32 v80, v84, v85
	v_cvt_pk_bf16_f32 v81, v86, v87
	v_add_u32_e32 v114, 0x90, v154
	v_cvt_pk_bf16_f32 v82, v82, v83
	v_cvt_pk_bf16_f32 v83, v88, v89
	global_store_dwordx4 v[92:93], v[80:83], off offset:256
	v_ashrrev_i32_e32 v115, 31, v114
	v_lshlrev_b64 v[96:97], 13, v[114:115]
	v_lshlrev_b64 v[80:81], 13, v[112:113]
	v_lshl_add_u64 v[92:93], v[156:157], 0, v[80:81]
	global_load_dwordx4 v[80:83], v[92:93], off offset:16
	global_load_dwordx4 v[84:87], v[92:93], off
	global_load_dwordx4 v[88:91], v[92:93], off offset:528
	s_nop 0
	global_load_dwordx4 v[92:95], v[92:93], off offset:512
	v_lshl_add_u64 v[108:109], v[156:157], 0, v[96:97]
	global_load_dwordx4 v[96:99], v[108:109], off offset:16
	global_load_dwordx4 v[100:103], v[108:109], off
	global_load_dwordx4 v[104:107], v[108:109], off offset:528
	s_nop 0
	global_load_dwordx4 v[108:111], v[108:109], off offset:512
	v_lshlrev_b64 v[112:113], 12, v[112:113]
	s_waitcnt vmcnt(0)
	v_pk_fma_f32 v[82:83], v[58:59], v[74:75], v[82:83]
	v_pk_fma_f32 v[60:61], v[60:61], v[76:77], v[84:85]
	v_pk_fma_f32 v[58:59], v[56:57], v[72:73], v[80:81]
	v_cvt_pk_bf16_f32 v56, v60, v61
	v_lshl_add_u64 v[60:61], s[2:3], 0, v[112:113]
	v_pk_fma_f32 v[62:63], v[62:63], v[78:79], v[86:87]
	v_lshl_add_u64 v[60:61], v[60:61], 0, v[136:137]
	v_cvt_pk_bf16_f32 v57, v62, v63
	v_pk_fma_f32 v[44:45], v[44:45], v[68:69], v[92:93]
	v_cvt_pk_bf16_f32 v58, v58, v59
	v_cvt_pk_bf16_f32 v59, v82, v83
	global_store_dwordx4 v[60:61], v[56:59], off
	v_pk_fma_f32 v[46:47], v[46:47], v[70:71], v[94:95]
	v_add_u32_e32 v80, 0xa0, v154
	v_pk_fma_f32 v[56:57], v[42:43], v[66:67], v[90:91]
	v_pk_fma_f32 v[42:43], v[40:41], v[64:65], v[88:89]
	v_cvt_pk_bf16_f32 v40, v44, v45
	v_cvt_pk_bf16_f32 v41, v46, v47
	v_lshlrev_b64 v[44:45], 12, v[114:115]
	v_cvt_pk_bf16_f32 v42, v42, v43
	v_cvt_pk_bf16_f32 v43, v56, v57
	global_store_dwordx4 v[60:61], v[40:43], off offset:256
	v_lshl_add_u64 v[44:45], s[2:3], 0, v[44:45]
	v_lshl_add_u64 v[44:45], v[44:45], 0, v[136:137]
	v_pk_fma_f32 v[40:41], v[52:53], v[76:77], v[100:101]
	v_pk_fma_f32 v[42:43], v[54:55], v[78:79], v[102:103]
	v_cvt_pk_bf16_f32 v40, v40, v41
	v_pk_fma_f32 v[46:47], v[50:51], v[74:75], v[98:99]
	v_cvt_pk_bf16_f32 v41, v42, v43
	v_pk_fma_f32 v[48:49], v[48:49], v[72:73], v[96:97]
	v_pk_fma_f32 v[38:39], v[38:39], v[70:71], v[110:111]
	v_cvt_pk_bf16_f32 v42, v48, v49
	v_cvt_pk_bf16_f32 v43, v46, v47
	global_store_dwordx4 v[44:45], v[40:43], off
	v_pk_fma_f32 v[36:37], v[36:37], v[68:69], v[108:109]
	v_ashrrev_i32_e32 v81, 31, v80
	v_pk_fma_f32 v[40:41], v[34:35], v[66:67], v[106:107]
	v_pk_fma_f32 v[34:35], v[32:33], v[64:65], v[104:105]
	v_cvt_pk_bf16_f32 v32, v36, v37
	v_cvt_pk_bf16_f32 v33, v38, v39
	v_add_u32_e32 v82, 0xb0, v154
	v_cvt_pk_bf16_f32 v34, v34, v35
	v_cvt_pk_bf16_f32 v35, v40, v41
	global_store_dwordx4 v[44:45], v[32:35], off offset:256
	v_ashrrev_i32_e32 v83, 31, v82
	v_lshlrev_b64 v[48:49], 13, v[82:83]
	v_lshlrev_b64 v[32:33], 13, v[80:81]
	v_lshl_add_u64 v[44:45], v[156:157], 0, v[32:33]
	global_load_dwordx4 v[32:35], v[44:45], off offset:16
	global_load_dwordx4 v[36:39], v[44:45], off
	global_load_dwordx4 v[40:43], v[44:45], off offset:528
	s_nop 0
	global_load_dwordx4 v[44:47], v[44:45], off offset:512
	v_lshl_add_u64 v[60:61], v[156:157], 0, v[48:49]
	global_load_dwordx4 v[48:51], v[60:61], off offset:16
	global_load_dwordx4 v[52:55], v[60:61], off
	global_load_dwordx4 v[56:59], v[60:61], off offset:528
	s_nop 0
	global_load_dwordx4 v[60:63], v[60:61], off offset:512
	v_lshlrev_b64 v[80:81], 12, v[80:81]
	s_waitcnt vmcnt(0)
	v_pk_fma_f32 v[34:35], v[26:27], v[74:75], v[34:35]
	v_pk_fma_f32 v[28:29], v[28:29], v[76:77], v[36:37]
	v_pk_fma_f32 v[26:27], v[24:25], v[72:73], v[32:33]
	v_cvt_pk_bf16_f32 v24, v28, v29
	v_lshl_add_u64 v[28:29], s[2:3], 0, v[80:81]
	v_pk_fma_f32 v[30:31], v[30:31], v[78:79], v[38:39]
	v_lshl_add_u64 v[28:29], v[28:29], 0, v[136:137]
	v_cvt_pk_bf16_f32 v25, v30, v31
	v_pk_fma_f32 v[12:13], v[12:13], v[68:69], v[44:45]
	v_cvt_pk_bf16_f32 v26, v26, v27
	v_cvt_pk_bf16_f32 v27, v34, v35
	global_store_dwordx4 v[28:29], v[24:27], off
	v_pk_fma_f32 v[14:15], v[14:15], v[70:71], v[46:47]
	v_pk_fma_f32 v[16:17], v[16:17], v[72:73], v[48:49]
	v_pk_fma_f32 v[24:25], v[10:11], v[66:67], v[42:43]
	v_pk_fma_f32 v[10:11], v[8:9], v[64:65], v[40:41]
	v_cvt_pk_bf16_f32 v8, v12, v13
	v_cvt_pk_bf16_f32 v9, v14, v15
	v_lshlrev_b64 v[12:13], 12, v[82:83]
	v_cvt_pk_bf16_f32 v10, v10, v11
	v_cvt_pk_bf16_f32 v11, v24, v25
	global_store_dwordx4 v[28:29], v[8:11], off offset:256
	v_lshl_add_u64 v[12:13], s[2:3], 0, v[12:13]
	v_lshl_add_u64 v[12:13], v[12:13], 0, v[136:137]
	v_pk_fma_f32 v[8:9], v[20:21], v[76:77], v[52:53]
	v_pk_fma_f32 v[10:11], v[22:23], v[78:79], v[54:55]
	v_cvt_pk_bf16_f32 v8, v8, v9
	v_pk_fma_f32 v[14:15], v[18:19], v[74:75], v[50:51]
	v_cvt_pk_bf16_f32 v9, v10, v11
	v_cvt_pk_bf16_f32 v10, v16, v17
	v_pk_fma_f32 v[6:7], v[6:7], v[70:71], v[62:63]
	v_cvt_pk_bf16_f32 v11, v14, v15
	global_store_dwordx4 v[12:13], v[8:11], off
	v_pk_fma_f32 v[4:5], v[4:5], v[68:69], v[60:61]
	s_nop 0
	v_pk_fma_f32 v[8:9], v[2:3], v[66:67], v[58:59]
	v_pk_fma_f32 v[2:3], v[0:1], v[64:65], v[56:57]
	v_cvt_pk_bf16_f32 v0, v4, v5
	v_cvt_pk_bf16_f32 v1, v6, v7
	s_nop 0
	v_cvt_pk_bf16_f32 v2, v2, v3
	v_cvt_pk_bf16_f32 v3, v8, v9
	global_store_dwordx4 v[12:13], v[0:3], off offset:256
	s_cbranch_vccz .LBB0_287
	s_waitcnt vmcnt(0)
	s_cmpk_gt_u32 s25, 0xff
	s_cbranch_scc1 .LBB0_298
	s_barrier

.LBB0_415:
	ds_read_b128 v[146:149], v196 offset:0
	ds_read_b128 v[150:153], v196 offset:1024
	ds_read_b128 v[154:157], v196 offset:2048
	ds_read_b128 v[158:161], v196 offset:3072
	ds_read_b128 v[162:165], v145
	ds_read_b128 v[166:169], v145 offset:1024
	ds_read_b128 v[170:173], v145 offset:2048
	ds_read_b128 v[174:177], v145 offset:3072
	ds_read_b128 v[178:181], v145 offset:4096
	ds_read_b128 v[182:185], v145 offset:5120
	ds_read_b128 v[186:189], v145 offset:6144
	ds_read_b128 v[204:207], v145 offset:7168
	global_load_lds_dwordx4 v136, s[16:17]
	s_add_i32 m0, s30, 0xe000
	s_nop 0
	global_load_lds_dwordx4 v138, s[16:17]
	s_waitcnt lgkmcnt(8)
	s_barrier
	s_waitcnt lgkmcnt(0)
	v_mfma_f32_16x16x32_bf16 v[124:127], v[146:149], v[162:165], v[124:127]
	v_mfma_f32_16x16x32_bf16 v[120:123], v[154:157], v[162:165], v[120:123]
	v_mfma_f32_16x16x32_bf16 v[116:119], v[146:149], v[170:173], v[116:119]
	v_mfma_f32_16x16x32_bf16 v[108:111], v[154:157], v[170:173], v[108:111]
	s_add_i32 s46, 0, 0x14000
	s_add_i32 s43, s43, s28
	v_mfma_f32_16x16x32_bf16 v[100:103], v[146:149], v[178:181], v[100:103]
	s_mov_b32 m0, s43
	v_mfma_f32_16x16x32_bf16 v[92:95], v[154:157], v[178:181], v[92:95]
	v_mfma_f32_16x16x32_bf16 v[84:87], v[146:149], v[186:189], v[84:87]
	v_mfma_f32_16x16x32_bf16 v[76:79], v[154:157], v[186:189], v[76:79]
	v_mfma_f32_16x16x32_bf16 v[124:127], v[150:153], v[166:169], v[124:127]
	v_mfma_f32_16x16x32_bf16 v[120:123], v[158:161], v[166:169], v[120:123]
	v_mfma_f32_16x16x32_bf16 v[116:119], v[150:153], v[174:177], v[116:119]
	v_mfma_f32_16x16x32_bf16 v[108:111], v[158:161], v[174:177], v[108:111]
	v_mfma_f32_16x16x32_bf16 v[100:103], v[150:153], v[182:185], v[100:103]
	v_mfma_f32_16x16x32_bf16 v[92:95], v[158:161], v[182:185], v[92:95]
	v_mfma_f32_16x16x32_bf16 v[84:87], v[150:153], v[204:207], v[84:87]
	v_mfma_f32_16x16x32_bf16 v[76:79], v[158:161], v[204:207], v[76:79]
	s_barrier
	ds_read_b128 v[208:211], v196 offset:16384
	ds_read_b128 v[214:217], v196 offset:17408
	ds_read_b128 v[218:221], v196 offset:18432
	ds_read_b128 v[222:225], v196 offset:19456
	global_load_lds_dwordx4 v192, s[18:19]
	s_add_i32 m0, s43, 0x2000
	s_nop 0
	global_load_lds_dwordx4 v128, s[18:19]
	s_barrier
	s_waitcnt lgkmcnt(0)
	v_mfma_f32_16x16x32_bf16 v[112:115], v[208:211], v[162:165], v[112:115]
	v_mfma_f32_16x16x32_bf16 v[104:107], v[218:221], v[162:165], v[104:107]
	v_mfma_f32_16x16x32_bf16 v[96:99], v[208:211], v[170:173], v[96:99]
	v_mfma_f32_16x16x32_bf16 v[88:91], v[218:221], v[170:173], v[88:91]
	s_mov_b32 m0, s30
	v_mfma_f32_16x16x32_bf16 v[80:83], v[208:211], v[178:181], v[80:83]
	s_add_u32 s48, s20, 0x80
	s_addc_u32 s49, s21, 0
	v_mfma_f32_16x16x32_bf16 v[72:75], v[218:221], v[178:181], v[72:75]
	v_mfma_f32_16x16x32_bf16 v[68:71], v[208:211], v[186:189], v[68:71]
	v_mfma_f32_16x16x32_bf16 v[64:67], v[218:221], v[186:189], v[64:67]
	v_mfma_f32_16x16x32_bf16 v[112:115], v[214:217], v[166:169], v[112:115]
	v_mfma_f32_16x16x32_bf16 v[104:107], v[222:225], v[166:169], v[104:107]
	v_mfma_f32_16x16x32_bf16 v[96:99], v[214:217], v[174:177], v[96:99]
	v_mfma_f32_16x16x32_bf16 v[88:91], v[222:225], v[174:177], v[88:91]
	v_mfma_f32_16x16x32_bf16 v[80:83], v[214:217], v[182:185], v[80:83]
	v_mfma_f32_16x16x32_bf16 v[72:75], v[222:225], v[182:185], v[72:75]
	v_mfma_f32_16x16x32_bf16 v[68:71], v[214:217], v[204:207], v[68:71]
	v_mfma_f32_16x16x32_bf16 v[64:67], v[222:225], v[204:207], v[64:67]
	s_barrier
	ds_read_b128 v[162:165], v145 offset:16384
	ds_read_b128 v[166:169], v145 offset:17408
	ds_read_b128 v[170:173], v145 offset:18432
	ds_read_b128 v[174:177], v145 offset:19456
	ds_read_b128 v[178:181], v145 offset:20480
	ds_read_b128 v[182:185], v145 offset:21504
	ds_read_b128 v[186:189], v145 offset:22528
	ds_read_b128 v[204:207], v145 offset:23552
	global_load_lds_dwordx4 v132, s[20:21]
	s_mov_b32 m0, s31
	s_nop 0
	global_load_lds_dwordx4 v130, s[20:21]
	s_barrier
	s_waitcnt lgkmcnt(0)
	v_mfma_f32_16x16x32_bf16 v[60:63], v[146:149], v[162:165], v[60:63]
	v_mfma_f32_16x16x32_bf16 v[56:59], v[154:157], v[162:165], v[56:59]
	v_mfma_f32_16x16x32_bf16 v[52:55], v[146:149], v[170:173], v[52:55]
	v_mfma_f32_16x16x32_bf16 v[44:47], v[154:157], v[170:173], v[44:47]
	s_add_u32 s44, s18, 0x80000
	s_addc_u32 s45, s19, 0
	v_mfma_f32_16x16x32_bf16 v[36:39], v[146:149], v[178:181], v[36:39]
	s_add_i32 s43, s46, s28
	s_mov_b32 m0, s43
	v_mfma_f32_16x16x32_bf16 v[28:31], v[154:157], v[178:181], v[28:31]
	v_mfma_f32_16x16x32_bf16 v[20:23], v[146:149], v[186:189], v[20:23]
	v_mfma_f32_16x16x32_bf16 v[12:15], v[154:157], v[186:189], v[12:15]
	v_mfma_f32_16x16x32_bf16 v[60:63], v[150:153], v[166:169], v[60:63]
	v_mfma_f32_16x16x32_bf16 v[56:59], v[158:161], v[166:169], v[56:59]
	v_mfma_f32_16x16x32_bf16 v[52:55], v[150:153], v[174:177], v[52:55]
	v_mfma_f32_16x16x32_bf16 v[44:47], v[158:161], v[174:177], v[44:47]
	v_mfma_f32_16x16x32_bf16 v[36:39], v[150:153], v[182:185], v[36:39]
	v_mfma_f32_16x16x32_bf16 v[28:31], v[158:161], v[182:185], v[28:31]
	v_mfma_f32_16x16x32_bf16 v[20:23], v[150:153], v[204:207], v[20:23]
	v_mfma_f32_16x16x32_bf16 v[12:15], v[158:161], v[204:207], v[12:15]
	s_barrier
	global_load_lds_dwordx4 v192, s[44:45]
	s_add_i32 m0, s43, 0x2000
	s_nop 0
	global_load_lds_dwordx4 v128, s[44:45]
	s_waitcnt vmcnt(6)
	s_barrier
	v_mfma_f32_16x16x32_bf16 v[48:51], v[208:211], v[162:165], v[48:51]
	v_mfma_f32_16x16x32_bf16 v[40:43], v[218:221], v[162:165], v[40:43]
	v_mfma_f32_16x16x32_bf16 v[32:35], v[208:211], v[170:173], v[32:35]
	v_mfma_f32_16x16x32_bf16 v[24:27], v[218:221], v[170:173], v[24:27]
	s_add_i32 s43, 0, 0x18000
	v_mfma_f32_16x16x32_bf16 v[16:19], v[208:211], v[178:181], v[16:19]
	s_add_u32 s20, s20, 0x80000
	s_addc_u32 s21, s21, 0
	v_mfma_f32_16x16x32_bf16 v[8:11], v[218:221], v[178:181], v[8:11]
	s_mov_b32 m0, s33
	v_mfma_f32_16x16x32_bf16 v[4:7], v[208:211], v[186:189], v[4:7]
	v_mfma_f32_16x16x32_bf16 v[0:3], v[218:221], v[186:189], v[0:3]
	v_mfma_f32_16x16x32_bf16 v[48:51], v[214:217], v[166:169], v[48:51]
	v_mfma_f32_16x16x32_bf16 v[40:43], v[222:225], v[166:169], v[40:43]
	v_mfma_f32_16x16x32_bf16 v[32:35], v[214:217], v[174:177], v[32:35]
	v_mfma_f32_16x16x32_bf16 v[24:27], v[222:225], v[174:177], v[24:27]
	v_mfma_f32_16x16x32_bf16 v[16:19], v[214:217], v[182:185], v[16:19]
	v_mfma_f32_16x16x32_bf16 v[8:11], v[222:225], v[182:185], v[8:11]
	v_mfma_f32_16x16x32_bf16 v[4:7], v[214:217], v[204:207], v[4:7]
	v_mfma_f32_16x16x32_bf16 v[0:3], v[222:225], v[204:207], v[0:3]
	s_barrier
	ds_read_b128 v[146:149], v196 offset:32768
	ds_read_b128 v[150:153], v196 offset:33792
	ds_read_b128 v[154:157], v196 offset:34816
	ds_read_b128 v[158:161], v196 offset:35840
	ds_read_b128 v[162:165], v145 offset:32768
	ds_read_b128 v[166:169], v145 offset:33792
	ds_read_b128 v[170:173], v145 offset:34816
	ds_read_b128 v[174:177], v145 offset:35840
	ds_read_b128 v[178:181], v145 offset:36864
	ds_read_b128 v[182:185], v145 offset:37888
	ds_read_b128 v[186:189], v145 offset:38912
	ds_read_b128 v[204:207], v145 offset:39936
	global_load_lds_dwordx4 v132, s[20:21]
	s_mov_b32 m0, s34
	s_nop 0
	global_load_lds_dwordx4 v130, s[20:21]
	s_waitcnt lgkmcnt(8)
	s_barrier
	s_waitcnt lgkmcnt(0)
	v_mfma_f32_16x16x32_bf16 v[124:127], v[146:149], v[162:165], v[124:127]
	v_mfma_f32_16x16x32_bf16 v[120:123], v[154:157], v[162:165], v[120:123]
	v_mfma_f32_16x16x32_bf16 v[116:119], v[146:149], v[170:173], v[116:119]
	v_mfma_f32_16x16x32_bf16 v[108:111], v[154:157], v[170:173], v[108:111]
	s_add_i32 s20, 0, 0x1c000
	s_add_i32 s21, s43, s28
	v_mfma_f32_16x16x32_bf16 v[100:103], v[146:149], v[178:181], v[100:103]
	s_add_i32 m0, s21, 0xffffff80
	v_mfma_f32_16x16x32_bf16 v[92:95], v[154:157], v[178:181], v[92:95]
	v_mfma_f32_16x16x32_bf16 v[84:87], v[146:149], v[186:189], v[84:87]
	v_mfma_f32_16x16x32_bf16 v[76:79], v[154:157], v[186:189], v[76:79]
	v_mfma_f32_16x16x32_bf16 v[124:127], v[150:153], v[166:169], v[124:127]
	v_mfma_f32_16x16x32_bf16 v[120:123], v[158:161], v[166:169], v[120:123]
	v_mfma_f32_16x16x32_bf16 v[116:119], v[150:153], v[174:177], v[116:119]
	v_mfma_f32_16x16x32_bf16 v[108:111], v[158:161], v[174:177], v[108:111]
	v_mfma_f32_16x16x32_bf16 v[100:103], v[150:153], v[182:185], v[100:103]
	v_mfma_f32_16x16x32_bf16 v[92:95], v[158:161], v[182:185], v[92:95]
	v_mfma_f32_16x16x32_bf16 v[84:87], v[150:153], v[204:207], v[84:87]
	v_mfma_f32_16x16x32_bf16 v[76:79], v[158:161], v[204:207], v[76:79]
	s_barrier
	ds_read_b128 v[208:211], v196 offset:49152
	ds_read_b128 v[214:217], v196 offset:50176
	ds_read_b128 v[218:221], v196 offset:51200
	ds_read_b128 v[222:225], v196 offset:52224
	global_load_lds_dwordx4 v192, s[18:19] offset:128
	s_add_i32 m0, s21, 0x1f80
	s_nop 0
	global_load_lds_dwordx4 v128, s[18:19] offset:128
	s_barrier
	s_waitcnt lgkmcnt(0)
	v_mfma_f32_16x16x32_bf16 v[112:115], v[208:211], v[162:165], v[112:115]
	v_mfma_f32_16x16x32_bf16 v[104:107], v[218:221], v[162:165], v[104:107]
	v_mfma_f32_16x16x32_bf16 v[96:99], v[208:211], v[170:173], v[96:99]
	v_mfma_f32_16x16x32_bf16 v[88:91], v[218:221], v[170:173], v[88:91]
	s_mov_b32 m0, s35
	v_mfma_f32_16x16x32_bf16 v[80:83], v[208:211], v[178:181], v[80:83]
	v_mfma_f32_16x16x32_bf16 v[72:75], v[218:221], v[178:181], v[72:75]
	v_mfma_f32_16x16x32_bf16 v[68:71], v[208:211], v[186:189], v[68:71]
	v_mfma_f32_16x16x32_bf16 v[64:67], v[218:221], v[186:189], v[64:67]
	v_mfma_f32_16x16x32_bf16 v[112:115], v[214:217], v[166:169], v[112:115]
	v_mfma_f32_16x16x32_bf16 v[104:107], v[222:225], v[166:169], v[104:107]
	v_mfma_f32_16x16x32_bf16 v[96:99], v[214:217], v[174:177], v[96:99]
	v_mfma_f32_16x16x32_bf16 v[88:91], v[222:225], v[174:177], v[88:91]
	v_mfma_f32_16x16x32_bf16 v[80:83], v[214:217], v[182:185], v[80:83]
	v_mfma_f32_16x16x32_bf16 v[72:75], v[222:225], v[182:185], v[72:75]
	v_mfma_f32_16x16x32_bf16 v[68:71], v[214:217], v[204:207], v[68:71]
	v_mfma_f32_16x16x32_bf16 v[64:67], v[222:225], v[204:207], v[64:67]
	s_barrier
	ds_read_b128 v[162:165], v145 offset:49152
	ds_read_b128 v[166:169], v145 offset:50176
	ds_read_b128 v[170:173], v145 offset:51200
	ds_read_b128 v[174:177], v145 offset:52224
	ds_read_b128 v[178:181], v145 offset:53248
	ds_read_b128 v[182:185], v145 offset:54272
	ds_read_b128 v[186:189], v145 offset:55296
	ds_read_b128 v[204:207], v145 offset:56320
	global_load_lds_dwordx4 v132, s[48:49]
	s_mov_b32 m0, s36
	s_nop 0
	global_load_lds_dwordx4 v130, s[48:49]
	s_barrier
	s_waitcnt lgkmcnt(0)
	v_mfma_f32_16x16x32_bf16 v[60:63], v[146:149], v[162:165], v[60:63]
	v_mfma_f32_16x16x32_bf16 v[56:59], v[154:157], v[162:165], v[56:59]
	v_mfma_f32_16x16x32_bf16 v[52:55], v[146:149], v[170:173], v[52:55]
	v_mfma_f32_16x16x32_bf16 v[44:47], v[154:157], v[170:173], v[44:47]
	s_add_u32 s18, s18, 0x80080
	s_addc_u32 s19, s19, 0
	v_mfma_f32_16x16x32_bf16 v[36:39], v[146:149], v[178:181], v[36:39]
	s_add_i32 s20, s20, s28
	s_mov_b32 m0, s20
	v_mfma_f32_16x16x32_bf16 v[28:31], v[154:157], v[178:181], v[28:31]
	v_mfma_f32_16x16x32_bf16 v[20:23], v[146:149], v[186:189], v[20:23]
	v_mfma_f32_16x16x32_bf16 v[12:15], v[154:157], v[186:189], v[12:15]
	v_mfma_f32_16x16x32_bf16 v[60:63], v[150:153], v[166:169], v[60:63]
	v_mfma_f32_16x16x32_bf16 v[56:59], v[158:161], v[166:169], v[56:59]
	v_mfma_f32_16x16x32_bf16 v[52:55], v[150:153], v[174:177], v[52:55]
	v_mfma_f32_16x16x32_bf16 v[44:47], v[158:161], v[174:177], v[44:47]
	v_mfma_f32_16x16x32_bf16 v[36:39], v[150:153], v[182:185], v[36:39]
	v_mfma_f32_16x16x32_bf16 v[28:31], v[158:161], v[182:185], v[28:31]
	v_mfma_f32_16x16x32_bf16 v[20:23], v[150:153], v[204:207], v[20:23]
	v_mfma_f32_16x16x32_bf16 v[12:15], v[158:161], v[204:207], v[12:15]
	s_barrier
	global_load_lds_dwordx4 v192, s[18:19]
	s_add_i32 m0, s20, 0x2000
	s_nop 0
	global_load_lds_dwordx4 v128, s[18:19]
	s_waitcnt vmcnt(6)
	s_barrier
	v_mfma_f32_16x16x32_bf16 v[48:51], v[208:211], v[162:165], v[48:51]
	v_mfma_f32_16x16x32_bf16 v[40:43], v[218:221], v[162:165], v[40:43]
	v_mfma_f32_16x16x32_bf16 v[32:35], v[208:211], v[170:173], v[32:35]
	v_mfma_f32_16x16x32_bf16 v[24:27], v[218:221], v[170:173], v[24:27]
	s_add_i32 s42, s42, 2
	v_mfma_f32_16x16x32_bf16 v[16:19], v[208:211], v[178:181], v[16:19]
	s_add_u32 s16, s16, 0x100
	s_addc_u32 s17, s17, 0
	v_mfma_f32_16x16x32_bf16 v[8:11], v[218:221], v[178:181], v[8:11]
	s_add_u32 s40, s40, 0x100
	s_addc_u32 s41, s41, 0
	v_mfma_f32_16x16x32_bf16 v[4:7], v[208:211], v[186:189], v[4:7]
	s_add_u32 s18, s16, 0xfff80080
	s_addc_u32 s19, s17, -1
	v_mfma_f32_16x16x32_bf16 v[0:3], v[218:221], v[186:189], v[0:3]
	s_add_i32 s43, 0, 0x10000
	s_cmp_eq_u32 s42, 28
	v_mfma_f32_16x16x32_bf16 v[48:51], v[214:217], v[166:169], v[48:51]
	s_cselect_b32 s21, s9, s19
	s_cselect_b32 s20, s38, s18
	v_mfma_f32_16x16x32_bf16 v[40:43], v[222:225], v[166:169], v[40:43]
	s_cselect_b32 s19, s7, s41
	s_cselect_b32 s18, s39, s40
	v_mfma_f32_16x16x32_bf16 v[32:35], v[214:217], v[174:177], v[32:35]
	s_add_i32 m0, s30, 0xc000
	v_mfma_f32_16x16x32_bf16 v[24:27], v[222:225], v[174:177], v[24:27]
	v_mfma_f32_16x16x32_bf16 v[16:19], v[214:217], v[182:185], v[16:19]
	v_mfma_f32_16x16x32_bf16 v[8:11], v[222:225], v[182:185], v[8:11]
	v_mfma_f32_16x16x32_bf16 v[4:7], v[214:217], v[204:207], v[4:7]
	v_mfma_f32_16x16x32_bf16 v[0:3], v[222:225], v[204:207], v[0:3]
	s_cmp_gt_u32 s42, 29
	s_cbranch_scc0 .Lrot_415
	s_barrier
	s_mul_hi_i32 s9, s15, 0x2aaaaaab
	v_lshl_add_u32 v153, s14, 8, v142
	s_lshr_b32 s14, s9, 31
	s_lshr_b32 s9, s9, 2
	s_add_i32 s9, s9, s14
	s_lshl_b32 s7, s15, 8
	s_mul_i32 s16, s9, 0x1800
	v_readlane_b32 s40, v254, 14
	v_readlane_b32 s41, v254, 15
	s_sub_i32 s40, s7, s16
	s_mov_b64 s[20:21], s[40:41]
	v_readlane_b32 s42, v254, 16
	v_readlane_b32 s43, v254, 17
	v_writelane_b32 v254, s20, 14
	s_mov_b64 s[14:15], -1
	s_cmpk_gt_i32 s40, 0xfff
	v_writelane_b32 v254, s21, 15
	v_writelane_b32 v254, s22, 16
	v_writelane_b32 v254, s23, 17
	v_or_b32_e32 v152, 16, v153
	v_or_b32_e32 v151, 32, v153
	v_or_b32_e32 v150, 48, v153
	v_add_u32_e32 v149, 0x80, v153
	v_add_u32_e32 v148, 0x90, v153
	v_add_u32_e32 v147, 0xa0, v153
	v_add_u32_e32 v146, 0xb0, v153
	s_cbranch_scc0 .LBB0_418
	v_mov_b32_e32 v156, v193
	v_mov_b32_e32 v157, v193
	s_ashr_i32 s17, s16, 31
	v_mov_b64_e32 v[140:141], s[2:3]
	s_mov_b32 s9, 0x9000
	v_cvt_pk_fp8_f32 v156, v124, v125
	v_cvt_pk_fp8_f32 v157, v120, v121
	s_lshl_b64 s[14:15], s[16:17], 1
	v_mad_i64_i32 v[154:155], s[16:17], v153, s9, v[140:141]
	s_add_u32 s14, s14, 0x2000
	v_readlane_b32 s16, v254, 14
	s_addc_u32 s15, s15, 0
	v_readlane_b32 s17, v254, 15
	v_lshl_add_u64 v[154:155], v[154:155], 0, s[14:15]
	s_mov_b64 s[20:21], s[16:17]
	v_cvt_pk_fp8_f32 v156, v126, v127 op_sel:[0,0,1]
	v_cvt_pk_fp8_f32 v157, v122, v123 op_sel:[0,0,1]
	v_lshl_add_u64 v[154:155], v[154:155], 0, s[20:21]
	v_lshl_add_u64 v[154:155], v[154:155], 0, s[4:5]
	v_lshl_add_u64 v[154:155], v[154:155], 0, v[134:135]
	global_store_dwordx2 v[154:155], v[156:157], off offset:-4096
	v_mov_b32_e32 v156, v193
	v_mov_b32_e32 v157, v193
	v_cvt_pk_fp8_f32 v156, v112, v113
	v_cvt_pk_fp8_f32 v157, v104, v105
	v_readlane_b32 s18, v254, 16
	v_readlane_b32 s19, v254, 17
	v_cvt_pk_fp8_f32 v156, v114, v115 op_sel:[0,0,1]
	v_cvt_pk_fp8_f32 v157, v106, v107 op_sel:[0,0,1]
	global_store_dwordx2 v[154:155], v[156:157], off offset:-3968
	v_mov_b32_e32 v156, v193
	v_mov_b32_e32 v157, v193
	v_cvt_pk_fp8_f32 v156, v116, v117
	v_cvt_pk_fp8_f32 v157, v108, v109
	v_mad_i64_i32 v[154:155], s[16:17], v152, s9, v[140:141]
	v_lshl_add_u64 v[154:155], v[154:155], 0, s[14:15]
	v_cvt_pk_fp8_f32 v156, v118, v119 op_sel:[0,0,1]
	v_cvt_pk_fp8_f32 v157, v110, v111 op_sel:[0,0,1]
	v_lshl_add_u64 v[154:155], v[154:155], 0, s[20:21]
	v_lshl_add_u64 v[154:155], v[154:155], 0, s[4:5]
	v_lshl_add_u64 v[154:155], v[154:155], 0, v[134:135]
	global_store_dwordx2 v[154:155], v[156:157], off offset:-4096
	v_mov_b32_e32 v156, v193
	v_mov_b32_e32 v157, v193
	v_cvt_pk_fp8_f32 v156, v96, v97
	v_cvt_pk_fp8_f32 v157, v88, v89
	v_cvt_pk_fp8_f32 v156, v98, v99 op_sel:[0,0,1]
	v_cvt_pk_fp8_f32 v157, v90, v91 op_sel:[0,0,1]
	global_store_dwordx2 v[154:155], v[156:157], off offset:-3968
	v_mov_b32_e32 v156, v193
	v_mov_b32_e32 v157, v193
	v_cvt_pk_fp8_f32 v156, v100, v101
	v_cvt_pk_fp8_f32 v157, v92, v93
	v_mad_i64_i32 v[154:155], s[16:17], v151, s9, v[140:141]
	v_lshl_add_u64 v[154:155], v[154:155], 0, s[14:15]
	v_cvt_pk_fp8_f32 v156, v102, v103 op_sel:[0,0,1]
	v_cvt_pk_fp8_f32 v157, v94, v95 op_sel:[0,0,1]
	v_lshl_add_u64 v[154:155], v[154:155], 0, s[20:21]
	v_lshl_add_u64 v[154:155], v[154:155], 0, s[4:5]
	v_lshl_add_u64 v[154:155], v[154:155], 0, v[134:135]
	global_store_dwordx2 v[154:155], v[156:157], off offset:-4096
	v_mov_b32_e32 v156, v193
	v_mov_b32_e32 v157, v193
	v_cvt_pk_fp8_f32 v156, v80, v81
	v_cvt_pk_fp8_f32 v157, v72, v73
	v_cvt_pk_fp8_f32 v156, v82, v83 op_sel:[0,0,1]
	v_cvt_pk_fp8_f32 v157, v74, v75 op_sel:[0,0,1]
	global_store_dwordx2 v[154:155], v[156:157], off offset:-3968
	v_mov_b32_e32 v156, v193
	v_mov_b32_e32 v157, v193
	v_cvt_pk_fp8_f32 v156, v84, v85
	v_cvt_pk_fp8_f32 v157, v76, v77
	v_mad_i64_i32 v[154:155], s[16:17], v150, s9, v[140:141]
	v_lshl_add_u64 v[154:155], v[154:155], 0, s[14:15]
	v_cvt_pk_fp8_f32 v156, v86, v87 op_sel:[0,0,1]
	v_cvt_pk_fp8_f32 v157, v78, v79 op_sel:[0,0,1]
	v_lshl_add_u64 v[154:155], v[154:155], 0, s[20:21]
	v_lshl_add_u64 v[154:155], v[154:155], 0, s[4:5]
	v_lshl_add_u64 v[154:155], v[154:155], 0, v[134:135]
	global_store_dwordx2 v[154:155], v[156:157], off offset:-4096
	v_mov_b32_e32 v156, v193
	v_mov_b32_e32 v157, v193
	v_cvt_pk_fp8_f32 v156, v68, v69
	v_cvt_pk_fp8_f32 v157, v64, v65
	v_cvt_pk_fp8_f32 v156, v70, v71 op_sel:[0,0,1]
	v_cvt_pk_fp8_f32 v157, v66, v67 op_sel:[0,0,1]
	global_store_dwordx2 v[154:155], v[156:157], off offset:-3968
	v_mov_b32_e32 v156, v193
	v_mov_b32_e32 v157, v193
	v_cvt_pk_fp8_f32 v156, v60, v61
	v_cvt_pk_fp8_f32 v157, v56, v57
	v_mad_i64_i32 v[154:155], s[16:17], v149, s9, v[140:141]
	v_lshl_add_u64 v[154:155], v[154:155], 0, s[14:15]
	v_cvt_pk_fp8_f32 v156, v62, v63 op_sel:[0,0,1]
	v_cvt_pk_fp8_f32 v157, v58, v59 op_sel:[0,0,1]
	v_lshl_add_u64 v[154:155], v[154:155], 0, s[20:21]
	v_lshl_add_u64 v[154:155], v[154:155], 0, s[4:5]
	v_lshl_add_u64 v[154:155], v[154:155], 0, v[134:135]
	global_store_dwordx2 v[154:155], v[156:157], off offset:-4096
	v_mov_b32_e32 v156, v193
	v_mov_b32_e32 v157, v193
	v_cvt_pk_fp8_f32 v156, v48, v49
	v_cvt_pk_fp8_f32 v157, v40, v41
	v_cvt_pk_fp8_f32 v156, v50, v51 op_sel:[0,0,1]
	v_cvt_pk_fp8_f32 v157, v42, v43 op_sel:[0,0,1]
	global_store_dwordx2 v[154:155], v[156:157], off offset:-3968
	v_mov_b32_e32 v156, v193
	v_mov_b32_e32 v157, v193
	v_cvt_pk_fp8_f32 v156, v52, v53
	v_cvt_pk_fp8_f32 v157, v44, v45
	v_mad_i64_i32 v[154:155], s[16:17], v148, s9, v[140:141]
	v_lshl_add_u64 v[154:155], v[154:155], 0, s[14:15]
	v_cvt_pk_fp8_f32 v156, v54, v55 op_sel:[0,0,1]
	v_cvt_pk_fp8_f32 v157, v46, v47 op_sel:[0,0,1]
	v_lshl_add_u64 v[154:155], v[154:155], 0, s[20:21]
	v_lshl_add_u64 v[154:155], v[154:155], 0, s[4:5]
	v_lshl_add_u64 v[154:155], v[154:155], 0, v[134:135]
	global_store_dwordx2 v[154:155], v[156:157], off offset:-4096
	v_mov_b32_e32 v156, v193
	v_mov_b32_e32 v157, v193
	v_cvt_pk_fp8_f32 v156, v32, v33
	v_cvt_pk_fp8_f32 v157, v24, v25
	v_cvt_pk_fp8_f32 v156, v34, v35 op_sel:[0,0,1]
	v_cvt_pk_fp8_f32 v157, v26, v27 op_sel:[0,0,1]
	global_store_dwordx2 v[154:155], v[156:157], off offset:-3968
	v_mov_b32_e32 v156, v193
	v_mov_b32_e32 v157, v193
	v_cvt_pk_fp8_f32 v156, v36, v37
	v_cvt_pk_fp8_f32 v157, v28, v29
	v_mad_i64_i32 v[154:155], s[16:17], v147, s9, v[140:141]
	v_lshl_add_u64 v[154:155], v[154:155], 0, s[14:15]
	v_cvt_pk_fp8_f32 v156, v38, v39 op_sel:[0,0,1]
	v_cvt_pk_fp8_f32 v157, v30, v31 op_sel:[0,0,1]
	v_lshl_add_u64 v[154:155], v[154:155], 0, s[20:21]
	v_lshl_add_u64 v[154:155], v[154:155], 0, s[4:5]
	v_lshl_add_u64 v[154:155], v[154:155], 0, v[134:135]
	global_store_dwordx2 v[154:155], v[156:157], off offset:-4096
	v_mov_b32_e32 v156, v193
	v_mov_b32_e32 v157, v193
	v_cvt_pk_fp8_f32 v156, v16, v17
	v_cvt_pk_fp8_f32 v157, v8, v9
	v_mad_i64_i32 v[140:141], s[16:17], v146, s9, v[140:141]
	v_cvt_pk_fp8_f32 v156, v18, v19 op_sel:[0,0,1]
	v_cvt_pk_fp8_f32 v157, v10, v11 op_sel:[0,0,1]
	v_lshl_add_u64 v[140:141], v[140:141], 0, s[14:15]
	v_lshl_add_u64 v[140:141], v[140:141], 0, s[20:21]
	v_lshl_add_u64 v[140:141], v[140:141], 0, s[4:5]
	global_store_dwordx2 v[154:155], v[156:157], off offset:-3968
	v_mov_b32_e32 v154, v193
	v_mov_b32_e32 v155, v193
	v_cvt_pk_fp8_f32 v154, v20, v21
	v_cvt_pk_fp8_f32 v155, v12, v13
	v_lshl_add_u64 v[140:141], v[140:141], 0, v[134:135]
	s_mov_b64 s[14:15], 0
	v_cvt_pk_fp8_f32 v154, v22, v23 op_sel:[0,0,1]
	v_cvt_pk_fp8_f32 v155, v14, v15 op_sel:[0,0,1]
	global_store_dwordx2 v[140:141], v[154:155], off offset:-4096
	v_mov_b32_e32 v154, v193
	v_mov_b32_e32 v155, v193
	v_cvt_pk_fp8_f32 v154, v4, v5
	v_cvt_pk_fp8_f32 v155, v0, v1
	v_cvt_pk_fp8_f32 v154, v6, v7 op_sel:[0,0,1]
	v_cvt_pk_fp8_f32 v155, v2, v3 op_sel:[0,0,1]
	global_store_dwordx2 v[140:141], v[154:155], off offset:-3968
